# residual-add epilogue de-serialised: x16 loads of steps 2..6 issued together at the top of the down / out-proj epilogues (5 phases), counted waits
# speedup vs baseline: 1.0043x; 1.0020x over previous
; #define PG8_STAGE(bufoff, gbase, voff) do { _Pragma("unroll") for (int _i = 0; _i < 2; ++_i) \
;         __builtin_amdgcn_global_load_lds((const unsigned*)((const char*)(gbase) + (voff)[_i]), (PG8_LAS unsigned*)(lds + (bufoff) + ldsw + _i * 8192), 16, 0, 0); } while (0)
; #define PG8_LDA(dst, b, h) do { _Pragma("unroll") for (int m = 0; m < 4; ++m) _Pragma("unroll") for (int k = 0; k < 2; ++k) dst[m][k] = *(const PG8_LAS bf16x8*)(lds + PG8_SA(b, h) + aoff + m * 2048 + k * 1024); } while (0)
; #define PG8_LDB(dst, b, h) do { _Pragma("unroll") for (int n = 0; n < 2; ++n) _Pragma("unroll") for (int k = 0; k < 2; ++k) dst[n][k] = *(const PG8_LAS bf16x8*)(lds + PG8_SB(b, h) + boff + n * 2048 + k * 1024); } while (0)
; #define PG8_MMA(ai, bj, At, Bt) do { __builtin_amdgcn_s_setprio(1); _Pragma("unroll") for (int m = 0; m < 4; ++m) _Pragma("unroll") for (int n = 0; n < 2; ++n) _Pragma("unroll") for (int k = 0; k < 2; ++k) \
;         acc[ai][bj][m][n] = mma16<F16>(Bt[n][k], At[m][k], acc[ai][bj][m][n]); __builtin_amdgcn_s_setprio(0); } while (0)
; #define PG8_WAIT_V(n) asm volatile("s_waitcnt vmcnt(" #n ")" ::: "memory")
; #define PG8_WAIT_L(n) asm volatile("s_waitcnt lgkmcnt(" #n ")" ::: "memory")
; #define PG8_BAR __builtin_amdgcn_s_barrier()
; #define PG8_SCHED __builtin_amdgcn_sched_barrier(0)
; template <class Epi, class Sched, bool ALIGN_EPI = false, bool SP2 = false, bool F16 = false, bool TOKPERM = false>
; __device__ __forceinline__ void gemm_phase(PG8_LAS unsigned char* lds, const Gemm g, const Sched& S, const Epi& E, int wv) {
;     ...
;             PG8_LDB(B0, 0, 0); PG8_LDB(B1, 0, 1); PG8_SCHED; PG8_LDA(At, 0, 0); PG8_STAGE(PG8_SA(1, 1), a1 + hstep, voffA);
;             PG8_WAIT_V(8); PG8_WAIT_L(0); PG8_BAR; PG8_MMA(0, 0, At, B0); PG8_MMA(0, 1, At, B1); PG8_BAR; PG8_SCHED;
;             PG8_LDA(At, 0, 1); PG8_STAGE(PG8_SB(0, 0), b2, voffB); PG8_STAGE(PG8_SB(0, 1), b2 + hstep, voffB); PG8_STAGE(PG8_SA(0, 0), a2, voffA);
;             PG8_WAIT_V(8); PG8_WAIT_L(0); PG8_BAR; PG8_MMA(1, 0, At, B0); PG8_MMA(1, 1, At, B1); PG8_BAR; PG8_SCHED;
.LBB0_297:
	ds_read_b128 v[166:169], v149
	ds_read_b128 v[170:173], v150
	ds_read_b128 v[174:177], v151
	ds_read_b128 v[178:181], v152
	ds_read_b128 v[182:185], v153
	ds_read_b128 v[186:189], v154
	ds_read_b128 v[190:193], v155
	ds_read_b128 v[194:197], v156
	s_add_u32 s18, s16, 0x100
	s_addc_u32 s19, s17, 0
	s_cmp_eq_u32 s70, 40
	s_cselect_b32 s51, s9, s19
	s_cselect_b32 s50, s8, s18
	s_cselect_b32 s49, s11, s69
	s_cselect_b32 s48, s10, s68
	s_mov_b32 m0, s61
	v_lshl_add_u64 v[232:233], s[16:17], 0, v[138:139]
	ds_read_b128 v[198:201], v147
	ds_read_b128 v[202:205], v147 offset:1024
	ds_read_b128 v[206:209], v147 offset:2048
	ds_read_b128 v[210:213], v147 offset:3072
	ds_read_b128 v[214:217], v147 offset:4096
	ds_read_b128 v[218:221], v147 offset:5120
	ds_read_b128 v[222:225], v147 offset:6144
	ds_read_b128 v[228:231], v147 offset:7168
	global_load_lds_dwordx4 v[232:233], off
	v_lshl_add_u64 v[232:233], s[16:17], 0, v[140:141]
	s_mov_b32 m0, s62
	s_nop 0
	global_load_lds_dwordx4 v[232:233], off
	s_waitcnt vmcnt(8)
	s_waitcnt lgkmcnt(0)
	s_barrier
	s_setprio 1
	s_waitcnt lgkmcnt(0)
	v_mfma_f32_16x16x32_bf16 v[124:127], v[166:169], v[198:201], v[124:127]
	v_mfma_f32_16x16x32_bf16 v[120:123], v[174:177], v[198:201], v[120:123]
	v_mfma_f32_16x16x32_bf16 v[108:111], v[166:169], v[206:209], v[108:111]
	v_mfma_f32_16x16x32_bf16 v[104:107], v[174:177], v[206:209], v[104:107]
	v_mfma_f32_16x16x32_bf16 v[92:95], v[166:169], v[214:217], v[92:95]
	v_mfma_f32_16x16x32_bf16 v[88:91], v[174:177], v[214:217], v[88:91]
	v_mfma_f32_16x16x32_bf16 v[76:79], v[166:169], v[222:225], v[76:79]
	v_mfma_f32_16x16x32_bf16 v[72:75], v[174:177], v[222:225], v[72:75]
	v_mfma_f32_16x16x32_bf16 v[124:127], v[170:173], v[202:205], v[124:127]
	v_mfma_f32_16x16x32_bf16 v[120:123], v[178:181], v[202:205], v[120:123]
	v_mfma_f32_16x16x32_bf16 v[108:111], v[170:173], v[210:213], v[108:111]
	v_mfma_f32_16x16x32_bf16 v[104:107], v[178:181], v[210:213], v[104:107]
	v_mfma_f32_16x16x32_bf16 v[92:95], v[170:173], v[218:221], v[92:95]
	v_mfma_f32_16x16x32_bf16 v[88:91], v[178:181], v[218:221], v[88:91]
	v_mfma_f32_16x16x32_bf16 v[76:79], v[170:173], v[228:231], v[76:79]
	v_mfma_f32_16x16x32_bf16 v[72:75], v[178:181], v[228:231], v[72:75]
	s_setprio 0
	s_setprio 1
	v_mfma_f32_16x16x32_bf16 v[116:119], v[182:185], v[198:201], v[116:119]
	v_mfma_f32_16x16x32_bf16 v[112:115], v[190:193], v[198:201], v[112:115]
	v_mfma_f32_16x16x32_bf16 v[100:103], v[182:185], v[206:209], v[100:103]
	v_mfma_f32_16x16x32_bf16 v[96:99], v[190:193], v[206:209], v[96:99]
	v_mfma_f32_16x16x32_bf16 v[84:87], v[182:185], v[214:217], v[84:87]
	v_mfma_f32_16x16x32_bf16 v[80:83], v[190:193], v[214:217], v[80:83]
	v_mfma_f32_16x16x32_bf16 v[68:71], v[182:185], v[222:225], v[68:71]
	v_mfma_f32_16x16x32_bf16 v[64:67], v[190:193], v[222:225], v[64:67]
	v_mfma_f32_16x16x32_bf16 v[116:119], v[186:189], v[202:205], v[116:119]
	v_mfma_f32_16x16x32_bf16 v[112:115], v[194:197], v[202:205], v[112:115]
	v_mfma_f32_16x16x32_bf16 v[100:103], v[186:189], v[210:213], v[100:103]
	v_mfma_f32_16x16x32_bf16 v[96:99], v[194:197], v[210:213], v[96:99]
	v_mfma_f32_16x16x32_bf16 v[84:87], v[186:189], v[218:221], v[84:87]
	v_mfma_f32_16x16x32_bf16 v[80:83], v[194:197], v[218:221], v[80:83]
	v_mfma_f32_16x16x32_bf16 v[68:71], v[186:189], v[228:231], v[68:71]
	v_mfma_f32_16x16x32_bf16 v[64:67], v[194:197], v[228:231], v[64:67]
	s_setprio 0
	s_barrier
	s_mov_b32 m0, s3
	v_lshl_add_u64 v[232:233], s[48:49], 0, v[130:131]
	s_add_u32 s16, s48, 0xb0000
	ds_read_b128 v[198:201], v147 offset:16384
	ds_read_b128 v[202:205], v147 offset:17408
	ds_read_b128 v[206:209], v147 offset:18432
	ds_read_b128 v[210:213], v147 offset:19456
	ds_read_b128 v[214:217], v147 offset:20480
	ds_read_b128 v[218:221], v147 offset:21504
	ds_read_b128 v[222:225], v147 offset:22528
	ds_read_b128 v[228:231], v147 offset:23552
	global_load_lds_dwordx4 v[232:233], off
	v_lshl_add_u64 v[234:235], s[48:49], 0, v[134:135]
	s_mov_b32 m0, s21
	s_addc_u32 s17, s49, 0
	global_load_lds_dwordx4 v[234:235], off
	v_lshl_add_u64 v[236:237], s[16:17], 0, v[130:131]
	s_mov_b32 m0, s22
	v_lshl_add_u64 v[238:239], s[50:51], 0, v[132:133]
	global_load_lds_dwordx4 v[236:237], off
	v_lshl_add_u64 v[236:237], s[16:17], 0, v[134:135]
	s_mov_b32 m0, s23
	s_nop 0
	global_load_lds_dwordx4 v[236:237], off
	v_lshl_add_u64 v[236:237], s[50:51], 0, v[128:129]
	s_mov_b32 m0, s2
	s_nop 0
	global_load_lds_dwordx4 v[236:237], off
	s_mov_b32 m0, s33
	s_nop 0
	global_load_lds_dwordx4 v[238:239], off
	s_waitcnt vmcnt(8)
	s_waitcnt lgkmcnt(0)
	s_barrier
; #define PG8_STAGE(bufoff, gbase, voff) do { _Pragma("unroll") for (int _i = 0; _i < 2; ++_i) \
;         __builtin_amdgcn_global_load_lds((const unsigned*)((const char*)(gbase) + (voff)[_i]), (PG8_LAS unsigned*)(lds + (bufoff) + ldsw + _i * 8192), 16, 0, 0); } while (0)
; #define PG8_LDA(dst, b, h) do { _Pragma("unroll") for (int m = 0; m < 4; ++m) _Pragma("unroll") for (int k = 0; k < 2; ++k) dst[m][k] = *(const PG8_LAS bf16x8*)(lds + PG8_SA(b, h) + aoff + m * 2048 + k * 1024); } while (0)
; #define PG8_LDB(dst, b, h) do { _Pragma("unroll") for (int n = 0; n < 2; ++n) _Pragma("unroll") for (int k = 0; k < 2; ++k) dst[n][k] = *(const PG8_LAS bf16x8*)(lds + PG8_SB(b, h) + boff + n * 2048 + k * 1024); } while (0)
; #define PG8_MMA(ai, bj, At, Bt) do { __builtin_amdgcn_s_setprio(1); _Pragma("unroll") for (int m = 0; m < 4; ++m) _Pragma("unroll") for (int n = 0; n < 2; ++n) _Pragma("unroll") for (int k = 0; k < 2; ++k) \
;         acc[ai][bj][m][n] = mma16<F16>(Bt[n][k], At[m][k], acc[ai][bj][m][n]); __builtin_amdgcn_s_setprio(0); } while (0)
; #define PG8_WAIT_V(n) asm volatile("s_waitcnt vmcnt(" #n ")" ::: "memory")
; #define PG8_WAIT_L(n) asm volatile("s_waitcnt lgkmcnt(" #n ")" ::: "memory")
; #define PG8_BAR __builtin_amdgcn_s_barrier()
; #define PG8_SCHED __builtin_amdgcn_sched_barrier(0)
; template <class Epi, class Sched, bool ALIGN_EPI = false, bool SP2 = false, bool F16 = false, bool TOKPERM = false>
; __device__ __forceinline__ void gemm_phase(PG8_LAS unsigned char* lds, const Gemm g, const Sched& S, const Epi& E, int wv) {
;     ...
;             PG8_WAIT_V(8); PG8_WAIT_L(0); PG8_BAR; PG8_MMA(1, 0, At, B0); PG8_MMA(1, 1, At, B1); PG8_BAR; PG8_SCHED;
;             PG8_LDB(B0, 1, 0); PG8_LDB(B1, 1, 1); PG8_SCHED; PG8_LDA(At, 1, 0); PG8_STAGE(PG8_SA(0, 1), a2 + hstep, voffA);
;             PG8_WAIT_V(8); PG8_WAIT_L(0); PG8_BAR; PG8_MMA(0, 0, At, B0); PG8_MMA(0, 1, At, B1); PG8_BAR; PG8_SCHED;
	s_setprio 1
	s_waitcnt lgkmcnt(0)
	v_mfma_f32_16x16x32_bf16 v[60:63], v[166:169], v[198:201], v[60:63]
	v_mfma_f32_16x16x32_bf16 v[56:59], v[174:177], v[198:201], v[56:59]
	v_mfma_f32_16x16x32_bf16 v[44:47], v[166:169], v[206:209], v[44:47]
	v_mfma_f32_16x16x32_bf16 v[40:43], v[174:177], v[206:209], v[40:43]
	v_mfma_f32_16x16x32_bf16 v[28:31], v[166:169], v[214:217], v[28:31]
	v_mfma_f32_16x16x32_bf16 v[24:27], v[174:177], v[214:217], v[24:27]
	v_mfma_f32_16x16x32_bf16 v[12:15], v[166:169], v[222:225], v[12:15]
	v_mfma_f32_16x16x32_bf16 v[8:11], v[174:177], v[222:225], v[8:11]
	v_mfma_f32_16x16x32_bf16 v[60:63], v[170:173], v[202:205], v[60:63]
	v_mfma_f32_16x16x32_bf16 v[56:59], v[178:181], v[202:205], v[56:59]
	v_mfma_f32_16x16x32_bf16 v[44:47], v[170:173], v[210:213], v[44:47]
	v_mfma_f32_16x16x32_bf16 v[40:43], v[178:181], v[210:213], v[40:43]
	v_mfma_f32_16x16x32_bf16 v[28:31], v[170:173], v[218:221], v[28:31]
	v_mfma_f32_16x16x32_bf16 v[24:27], v[178:181], v[218:221], v[24:27]
	v_mfma_f32_16x16x32_bf16 v[12:15], v[170:173], v[228:231], v[12:15]
	v_mfma_f32_16x16x32_bf16 v[8:11], v[178:181], v[228:231], v[8:11]
	s_setprio 0
	s_setprio 1
	v_mfma_f32_16x16x32_bf16 v[52:55], v[182:185], v[198:201], v[52:55]
	v_mfma_f32_16x16x32_bf16 v[48:51], v[190:193], v[198:201], v[48:51]
	v_mfma_f32_16x16x32_bf16 v[36:39], v[182:185], v[206:209], v[36:39]
	v_mfma_f32_16x16x32_bf16 v[32:35], v[190:193], v[206:209], v[32:35]
	v_mfma_f32_16x16x32_bf16 v[20:23], v[182:185], v[214:217], v[20:23]
	v_mfma_f32_16x16x32_bf16 v[16:19], v[190:193], v[214:217], v[16:19]
	v_mfma_f32_16x16x32_bf16 v[4:7], v[182:185], v[222:225], v[4:7]
	v_mfma_f32_16x16x32_bf16 v[0:3], v[190:193], v[222:225], v[0:3]
	v_mfma_f32_16x16x32_bf16 v[52:55], v[186:189], v[202:205], v[52:55]
	v_mfma_f32_16x16x32_bf16 v[48:51], v[194:197], v[202:205], v[48:51]
	v_mfma_f32_16x16x32_bf16 v[36:39], v[186:189], v[210:213], v[36:39]
	v_mfma_f32_16x16x32_bf16 v[32:35], v[194:197], v[210:213], v[32:35]
	v_mfma_f32_16x16x32_bf16 v[20:23], v[186:189], v[218:221], v[20:23]
	v_mfma_f32_16x16x32_bf16 v[16:19], v[194:197], v[218:221], v[16:19]
	v_mfma_f32_16x16x32_bf16 v[4:7], v[186:189], v[228:231], v[4:7]
	v_mfma_f32_16x16x32_bf16 v[0:3], v[194:197], v[228:231], v[0:3]
	s_setprio 0
	s_barrier
	ds_read_b128 v[166:169], v157
	ds_read_b128 v[170:173], v158
	ds_read_b128 v[174:177], v159
	ds_read_b128 v[178:181], v160
	ds_read_b128 v[182:185], v161
	ds_read_b128 v[186:189], v162
	ds_read_b128 v[190:193], v163
	ds_read_b128 v[194:197], v164
	s_add_u32 s16, s50, 0xb0000
	s_addc_u32 s17, s51, 0
	s_mov_b32 m0, s36
	v_lshl_add_u64 v[240:241], s[16:17], 0, v[128:129]
	ds_read_b128 v[198:201], v147 offset:32768
	ds_read_b128 v[202:205], v147 offset:33792
	ds_read_b128 v[206:209], v147 offset:34816
	ds_read_b128 v[210:213], v147 offset:35840
	ds_read_b128 v[214:217], v147 offset:36864
	ds_read_b128 v[218:221], v147 offset:37888
	ds_read_b128 v[222:225], v147 offset:38912
	ds_read_b128 v[228:231], v147 offset:39936
	global_load_lds_dwordx4 v[240:241], off
	v_lshl_add_u64 v[240:241], s[16:17], 0, v[132:133]
	s_mov_b32 m0, s37
	s_nop 0
	global_load_lds_dwordx4 v[240:241], off
	s_waitcnt vmcnt(8)
	s_waitcnt lgkmcnt(0)
	s_barrier
	s_setprio 1
	s_waitcnt lgkmcnt(0)
	v_mfma_f32_16x16x32_bf16 v[124:127], v[166:169], v[198:201], v[124:127]
	v_mfma_f32_16x16x32_bf16 v[120:123], v[174:177], v[198:201], v[120:123]
	v_mfma_f32_16x16x32_bf16 v[108:111], v[166:169], v[206:209], v[108:111]
	v_mfma_f32_16x16x32_bf16 v[104:107], v[174:177], v[206:209], v[104:107]
	v_mfma_f32_16x16x32_bf16 v[92:95], v[166:169], v[214:217], v[92:95]
	v_mfma_f32_16x16x32_bf16 v[88:91], v[174:177], v[214:217], v[88:91]
	v_mfma_f32_16x16x32_bf16 v[76:79], v[166:169], v[222:225], v[76:79]
	v_mfma_f32_16x16x32_bf16 v[72:75], v[174:177], v[222:225], v[72:75]
	v_mfma_f32_16x16x32_bf16 v[124:127], v[170:173], v[202:205], v[124:127]
	v_mfma_f32_16x16x32_bf16 v[120:123], v[178:181], v[202:205], v[120:123]
	v_mfma_f32_16x16x32_bf16 v[108:111], v[170:173], v[210:213], v[108:111]
	v_mfma_f32_16x16x32_bf16 v[104:107], v[178:181], v[210:213], v[104:107]
	v_mfma_f32_16x16x32_bf16 v[92:95], v[170:173], v[218:221], v[92:95]
	v_mfma_f32_16x16x32_bf16 v[88:91], v[178:181], v[218:221], v[88:91]
	v_mfma_f32_16x16x32_bf16 v[76:79], v[170:173], v[228:231], v[76:79]
	v_mfma_f32_16x16x32_bf16 v[72:75], v[178:181], v[228:231], v[72:75]
	s_setprio 0
	s_setprio 1
	v_mfma_f32_16x16x32_bf16 v[116:119], v[182:185], v[198:201], v[116:119]
	v_mfma_f32_16x16x32_bf16 v[112:115], v[190:193], v[198:201], v[112:115]
	v_mfma_f32_16x16x32_bf16 v[100:103], v[182:185], v[206:209], v[100:103]
	v_mfma_f32_16x16x32_bf16 v[96:99], v[190:193], v[206:209], v[96:99]
	v_mfma_f32_16x16x32_bf16 v[84:87], v[182:185], v[214:217], v[84:87]
	v_mfma_f32_16x16x32_bf16 v[80:83], v[190:193], v[214:217], v[80:83]
	v_mfma_f32_16x16x32_bf16 v[68:71], v[182:185], v[222:225], v[68:71]
	v_mfma_f32_16x16x32_bf16 v[64:67], v[190:193], v[222:225], v[64:67]
	v_mfma_f32_16x16x32_bf16 v[116:119], v[186:189], v[202:205], v[116:119]
	v_mfma_f32_16x16x32_bf16 v[112:115], v[194:197], v[202:205], v[112:115]
	v_mfma_f32_16x16x32_bf16 v[100:103], v[186:189], v[210:213], v[100:103]
	v_mfma_f32_16x16x32_bf16 v[96:99], v[194:197], v[210:213], v[96:99]
	v_mfma_f32_16x16x32_bf16 v[84:87], v[186:189], v[218:221], v[84:87]
	v_mfma_f32_16x16x32_bf16 v[80:83], v[194:197], v[218:221], v[80:83]
	v_mfma_f32_16x16x32_bf16 v[68:71], v[186:189], v[228:231], v[68:71]
	v_mfma_f32_16x16x32_bf16 v[64:67], v[194:197], v[228:231], v[64:67]
	s_setprio 0
	s_barrier
; #define PG8_STAGE(bufoff, gbase, voff) do { _Pragma("unroll") for (int _i = 0; _i < 2; ++_i) \
;         __builtin_amdgcn_global_load_lds((const unsigned*)((const char*)(gbase) + (voff)[_i]), (PG8_LAS unsigned*)(lds + (bufoff) + ldsw + _i * 8192), 16, 0, 0); } while (0)
; #define PG8_LDA(dst, b, h) do { _Pragma("unroll") for (int m = 0; m < 4; ++m) _Pragma("unroll") for (int k = 0; k < 2; ++k) dst[m][k] = *(const PG8_LAS bf16x8*)(lds + PG8_SA(b, h) + aoff + m * 2048 + k * 1024); } while (0)
; #define PG8_MMA(ai, bj, At, Bt) do { __builtin_amdgcn_s_setprio(1); _Pragma("unroll") for (int m = 0; m < 4; ++m) _Pragma("unroll") for (int n = 0; n < 2; ++n) _Pragma("unroll") for (int k = 0; k < 2; ++k) \
;         acc[ai][bj][m][n] = mma16<F16>(Bt[n][k], At[m][k], acc[ai][bj][m][n]); __builtin_amdgcn_s_setprio(0); } while (0)
; template <class Epi, class Sched, bool ALIGN_EPI = false, bool SP2 = false, bool F16 = false, bool TOKPERM = false>
; __device__ __forceinline__ void gemm_phase(PG8_LAS unsigned char* lds, const Gemm g, const Sched& S, const Epi& E, int wv) {
;     ...
;             PG8_LDA(At, 1, 1); PG8_STAGE(PG8_SB(1, 0), b3, voffB); PG8_STAGE(PG8_SB(1, 1), b3 + hstep, voffB); PG8_STAGE(PG8_SA(1, 0), a3, voffA);
;             PG8_WAIT_V(8); PG8_WAIT_L(0); PG8_BAR; PG8_MMA(1, 0, At, B0); PG8_MMA(1, 1, At, B1); PG8_BAR; PG8_SCHED;
;   __device__ __forceinline__ void operator()(const pg8::f32x4 (&acc)[2][2][4][2], const pg8::Unit& u, int wr, int wc, int fr, int fq) const {
;     int z; asm volatile("v_mov_b32 %0, 0" : "=v"(z));
;     const int row0 = u.pm * 256 + wr * 64 + fr + z, colb = u.pn * 256 + wc * 32 + 8 * fq + z;
; #pragma unroll
;     for (int ai = 0; ai < 2; ++ai)
; #pragma unroll
;       for (int m = 0; m < 4; ++m) {
;         const int tok = row0 + ai * 128 + m * 16; float ss = 0.f;
; #pragma unroll
;         for (int bj = 0; bj < 2; ++bj) {
;           const unsigned off = (unsigned)tok * DM + colb + 128 * bj;
;           f8_t n = __builtin_convertvector(*(const h8_t*)(x16 + off), f8_t);
; #pragma unroll
;           for (int c = 0; c < 4; ++c) { n[c] += sc * acc[ai][bj][m][0][c]; n[4 + c] += sc * acc[ai][bj][m][1][c]; }
;           if (aux) {
;             *(h8_t*)(x16 + off) = __builtin_convertvector(n, h8_t);
;             ss += ((n[0] * n[0] + n[1] * n[1]) + (n[2] * n[2] + n[3] * n[3])) + ((n[4] * n[4] + n[5] * n[5]) + (n[6] * n[6] + n[7] * n[7]));
	s_mov_b32 m0, s45
	v_lshl_add_u64 v[232:233], v[232:233], 0, s[12:13]
	s_add_u32 s16, s48, 0xb0080
	ds_read_b128 v[198:201], v147 offset:49152
	ds_read_b128 v[202:205], v147 offset:50176
	ds_read_b128 v[206:209], v147 offset:51200
	ds_read_b128 v[210:213], v147 offset:52224
	ds_read_b128 v[214:217], v147 offset:53248
	ds_read_b128 v[218:221], v147 offset:54272
	ds_read_b128 v[222:225], v147 offset:55296
	ds_read_b128 v[228:231], v147 offset:56320
	global_load_lds_dwordx4 v[232:233], off
	v_lshl_add_u64 v[232:233], v[234:235], 0, s[12:13]
	s_mov_b32 m0, s52
	s_addc_u32 s17, s49, 0
	global_load_lds_dwordx4 v[232:233], off
	v_lshl_add_u64 v[232:233], s[16:17], 0, v[130:131]
	s_mov_b32 m0, s55
	s_nop 0
	global_load_lds_dwordx4 v[232:233], off
	v_lshl_add_u64 v[232:233], s[16:17], 0, v[134:135]
	s_mov_b32 m0, s56
	s_nop 0
	global_load_lds_dwordx4 v[232:233], off
	v_lshl_add_u64 v[232:233], v[236:237], 0, s[12:13]
	s_mov_b32 m0, s53
	s_nop 0
	global_load_lds_dwordx4 v[232:233], off
	v_lshl_add_u64 v[232:233], v[238:239], 0, s[12:13]
	s_mov_b32 m0, s54
	s_nop 0
	global_load_lds_dwordx4 v[232:233], off
	s_waitcnt vmcnt(8)
	s_waitcnt lgkmcnt(0)
	s_barrier
	s_setprio 1
	s_waitcnt lgkmcnt(0)
	v_mfma_f32_16x16x32_bf16 v[60:63], v[166:169], v[198:201], v[60:63]
	v_mfma_f32_16x16x32_bf16 v[56:59], v[174:177], v[198:201], v[56:59]
	v_mfma_f32_16x16x32_bf16 v[44:47], v[166:169], v[206:209], v[44:47]
	v_mfma_f32_16x16x32_bf16 v[40:43], v[174:177], v[206:209], v[40:43]
	v_mfma_f32_16x16x32_bf16 v[28:31], v[166:169], v[214:217], v[28:31]
	v_mfma_f32_16x16x32_bf16 v[24:27], v[174:177], v[214:217], v[24:27]
	v_mfma_f32_16x16x32_bf16 v[12:15], v[166:169], v[222:225], v[12:15]
	v_mfma_f32_16x16x32_bf16 v[8:11], v[174:177], v[222:225], v[8:11]
	v_mfma_f32_16x16x32_bf16 v[60:63], v[170:173], v[202:205], v[60:63]
	v_mfma_f32_16x16x32_bf16 v[56:59], v[178:181], v[202:205], v[56:59]
	v_mfma_f32_16x16x32_bf16 v[44:47], v[170:173], v[210:213], v[44:47]
	v_mfma_f32_16x16x32_bf16 v[40:43], v[178:181], v[210:213], v[40:43]
	v_mfma_f32_16x16x32_bf16 v[28:31], v[170:173], v[218:221], v[28:31]
	v_mfma_f32_16x16x32_bf16 v[24:27], v[178:181], v[218:221], v[24:27]
	v_mfma_f32_16x16x32_bf16 v[12:15], v[170:173], v[228:231], v[12:15]
	v_mfma_f32_16x16x32_bf16 v[8:11], v[178:181], v[228:231], v[8:11]
	s_setprio 0
	s_setprio 1
	v_mfma_f32_16x16x32_bf16 v[52:55], v[182:185], v[198:201], v[52:55]
	v_mfma_f32_16x16x32_bf16 v[48:51], v[190:193], v[198:201], v[48:51]
	v_mfma_f32_16x16x32_bf16 v[36:39], v[182:185], v[206:209], v[36:39]
	v_mfma_f32_16x16x32_bf16 v[32:35], v[190:193], v[206:209], v[32:35]
	v_mfma_f32_16x16x32_bf16 v[20:23], v[182:185], v[214:217], v[20:23]
	v_mfma_f32_16x16x32_bf16 v[16:19], v[190:193], v[214:217], v[16:19]
	v_mfma_f32_16x16x32_bf16 v[4:7], v[182:185], v[222:225], v[4:7]
	v_mfma_f32_16x16x32_bf16 v[0:3], v[190:193], v[222:225], v[0:3]
	v_mfma_f32_16x16x32_bf16 v[52:55], v[186:189], v[202:205], v[52:55]
	v_mfma_f32_16x16x32_bf16 v[48:51], v[194:197], v[202:205], v[48:51]
	v_mfma_f32_16x16x32_bf16 v[36:39], v[186:189], v[210:213], v[36:39]
	v_mfma_f32_16x16x32_bf16 v[32:35], v[194:197], v[210:213], v[32:35]
	v_mfma_f32_16x16x32_bf16 v[20:23], v[186:189], v[218:221], v[20:23]
	v_mfma_f32_16x16x32_bf16 v[16:19], v[194:197], v[218:221], v[16:19]
	v_mfma_f32_16x16x32_bf16 v[4:7], v[186:189], v[228:231], v[4:7]
	v_mfma_f32_16x16x32_bf16 v[0:3], v[194:197], v[228:231], v[0:3]
	s_setprio 0
	s_barrier
	s_add_i32 s70, s70, 2
	s_add_u32 s68, s68, 0x100
	s_addc_u32 s69, s69, 0
	s_cmp_gt_u32 s70, 41
	s_mov_b64 s[16:17], s[18:19]
	s_cbranch_scc0 .LBB0_297
	s_lshl_b32 s16, s66, 8
	v_lshl_or_b32 v166, s65, 8, v148
	v_mov_b32 v136, 0
	v_xor_b32_e32 v169, 32, v165
	v_add3_u32 v167, s16, v146, v136
	v_add_u32_e32 v168, v166, v136
	v_lshl_add_u32 v136, v167, 10, v168
	v_lshl_add_u64 v[178:179], v[136:137], 1, s[40:41]
	v_add_u32_e32 v136, 0x80, v136
	global_load_dwordx4 v[170:173], v[178:179], off
	v_lshl_add_u64 v[180:181], v[136:137], 1, s[40:41]
	global_load_dwordx4 v[174:177], v[180:181], off
	v_add_u32_e32 v136, 16, v167
	v_lshl_add_u32 v136, v136, 10, v168
	v_lshl_add_u64 v[224:225], v[136:137], 1, s[40:41]
	v_add_u32_e32 v136, 0x80, v136
	global_load_dwordx4 v[192:195], v[224:225], off
	v_lshl_add_u64 v[248:249], v[136:137], 1, s[40:41]
	global_load_dwordx4 v[196:199], v[248:249], off
	v_add_u32_e32 v136, 32, v167
	v_lshl_add_u32 v136, v136, 10, v168
	v_lshl_add_u64 v[224:225], v[136:137], 1, s[40:41]
	v_add_u32_e32 v136, 0x80, v136
	global_load_dwordx4 v[200:203], v[224:225], off
	v_lshl_add_u64 v[248:249], v[136:137], 1, s[40:41]
	global_load_dwordx4 v[204:207], v[248:249], off
	v_add_u32_e32 v136, 48, v167
	v_lshl_add_u32 v136, v136, 10, v168
	v_lshl_add_u64 v[224:225], v[136:137], 1, s[40:41]
	v_add_u32_e32 v136, 0x80, v136
	global_load_dwordx4 v[208:211], v[224:225], off
	v_lshl_add_u64 v[248:249], v[136:137], 1, s[40:41]
	global_load_dwordx4 v[212:215], v[248:249], off
	v_add_u32_e32 v136, 0x80, v167
	v_lshl_add_u32 v136, v136, 10, v168
	v_lshl_add_u64 v[224:225], v[136:137], 1, s[40:41]
	v_add_u32_e32 v136, 0x80, v136
	global_load_dwordx4 v[216:219], v[224:225], off
	v_lshl_add_u64 v[248:249], v[136:137], 1, s[40:41]
	global_load_dwordx4 v[220:223], v[248:249], off
	v_add_u32_e32 v136, 0x90, v167
	v_lshl_add_u32 v136, v136, 10, v168
	v_lshl_add_u64 v[224:225], v[136:137], 1, s[40:41]
	v_add_u32_e32 v136, 0x80, v136
	global_load_dwordx4 v[228:231], v[224:225], off
	v_lshl_add_u64 v[248:249], v[136:137], 1, s[40:41]
	global_load_dwordx4 v[244:247], v[248:249], off
	v_and_b32_e32 v166, 64, v165
	v_xor_b32_e32 v136, 16, v165
	v_add_u32_e32 v166, 64, v166
	v_cmp_lt_i32_e32 vcc, v136, v166
	s_lshl_b32 s16, s65, 2
	s_or_b32 s18, s16, s44
	v_cndmask_b32_e32 v136, v165, v136, vcc
	v_cmp_lt_i32_e32 vcc, v169, v166
	v_lshlrev_b32_e32 v166, 2, v136
	s_waitcnt vmcnt(10)
;   __device__ __forceinline__ void operator()(const pg8::f32x4 (&acc)[2][2][4][2], const pg8::Unit& u, int wr, int wc, int fr, int fq) const {
;     ...
;       for (int m = 0; m < 4; ++m) {
;         const int tok = row0 + ai * 128 + m * 16; float ss = 0.f;
; #pragma unroll
;         for (int bj = 0; bj < 2; ++bj) {
;           const unsigned off = (unsigned)tok * DM + colb + 128 * bj;
;           f8_t n = __builtin_convertvector(*(const h8_t*)(x16 + off), f8_t);
; #pragma unroll
;           for (int c = 0; c < 4; ++c) { n[c] += sc * acc[ai][bj][m][0][c]; n[4 + c] += sc * acc[ai][bj][m][1][c]; }
;           if (aux) {
;             *(h8_t*)(x16 + off) = __builtin_convertvector(n, h8_t);
;             ss += ((n[0] * n[0] + n[1] * n[1]) + (n[2] * n[2] + n[3] * n[3])) + ((n[4] * n[4] + n[5] * n[5]) + (n[6] * n[6] + n[7] * n[7]));
;           } else {
;             *(f32x4*)(xout + off) = (f32x4){n[0], n[1], n[2], n[3]}; *(f32x4*)(xout + off + 4) = (f32x4){n[4], n[5], n[6], n[7]};
;           }
;         }
;         if (aux) { ss += __shfl_xor(ss, 16); ss += __shfl_xor(ss, 32); if (fq == 0) ssq[(unsigned)tok * 16 + u.pn * 4 + wc] = ss; }
;         if (m & 1) asm volatile("" ::: "memory");
	v_cvt_f32_f16_e32 v182, v173
	v_cvt_f32_f16_sdwa v183, v173 dst_sel:DWORD dst_unused:UNUSED_PAD src0_sel:WORD_1
	v_cvt_f32_f16_e32 v184, v171
	v_cvt_f32_f16_sdwa v185, v171 dst_sel:DWORD dst_unused:UNUSED_PAD src0_sel:WORD_1
	v_cvt_f32_f16_e32 v186, v172
	v_cvt_f32_f16_sdwa v187, v172 dst_sel:DWORD dst_unused:UNUSED_PAD src0_sel:WORD_1
	v_cvt_f32_f16_e32 v172, v170
	v_cvt_f32_f16_sdwa v173, v170 dst_sel:DWORD dst_unused:UNUSED_PAD src0_sel:WORD_1
	v_cvt_f32_f16_e32 v170, v177
	v_cvt_f32_f16_sdwa v171, v177 dst_sel:DWORD dst_unused:UNUSED_PAD src0_sel:WORD_1
	v_cvt_f32_f16_e32 v188, v175
	v_cvt_f32_f16_sdwa v189, v175 dst_sel:DWORD dst_unused:UNUSED_PAD src0_sel:WORD_1
	v_cvt_f32_f16_e32 v190, v176
	v_cvt_f32_f16_sdwa v191, v176 dst_sel:DWORD dst_unused:UNUSED_PAD src0_sel:WORD_1
	v_cvt_f32_f16_e32 v176, v174
	v_cvt_f32_f16_sdwa v177, v174 dst_sel:DWORD dst_unused:UNUSED_PAD src0_sel:WORD_1
	v_pk_fma_f32 v[124:125], v[124:125], 0.5, v[172:173] op_sel_hi:[1,0,1]
	v_pk_fma_f32 v[172:173], v[120:121], 0.5, v[186:187] op_sel_hi:[1,0,1]
	v_pk_fma_f32 v[126:127], v[126:127], 0.5, v[184:185] op_sel_hi:[1,0,1]
	v_pk_fma_f32 v[122:123], v[122:123], 0.5, v[182:183] op_sel_hi:[1,0,1]
	v_cvt_pk_f16_f32 v120, v172, v173
	v_cvt_pk_f16_f32 v121, v122, v123
	v_pk_mul_f32 v[174:175], v[124:125], v[124:125]
	v_pk_mul_f32 v[182:183], v[126:127], v[126:127]
	v_pk_mul_f32 v[172:173], v[172:173], v[172:173]
	v_pk_mul_f32 v[122:123], v[122:123], v[122:123]
	v_pk_fma_f32 v[176:177], v[116:117], 0.5, v[176:177] op_sel_hi:[1,0,1]
	v_pk_fma_f32 v[116:117], v[112:113], 0.5, v[190:191] op_sel_hi:[1,0,1]
	v_pk_fma_f32 v[184:185], v[118:119], 0.5, v[188:189] op_sel_hi:[1,0,1]
	v_pk_fma_f32 v[112:113], v[114:115], 0.5, v[170:171] op_sel_hi:[1,0,1]
	v_pk_mul_f32 v[114:115], v[176:177], v[176:177]
	v_pk_mul_f32 v[118:119], v[184:185], v[184:185]
	v_pk_mul_f32 v[170:171], v[116:117], v[116:117]
	v_pk_mul_f32 v[186:187], v[112:113], v[112:113]
	v_add_f32_e32 v122, v122, v123
	v_add_f32_e32 v123, v172, v173
	v_add_f32_e32 v136, v182, v183
	v_add_f32_e32 v172, v174, v175
	v_add_f32_e32 v122, v123, v122
	v_add_f32_e32 v123, v172, v136
	v_add_f32_e32 v136, v186, v187
	v_add_f32_e32 v170, v170, v171
	v_add_f32_e32 v118, v118, v119
	v_add_f32_e32 v114, v114, v115
	v_add_f32_e32 v119, v170, v136
	v_add_f32_e32 v114, v114, v118
	v_add_f32_e32 v115, v123, v122
	v_add_f32_e32 v114, v114, v119
	v_add_f32_e32 v114, v115, v114
	ds_bpermute_b32 v115, v166, v114
	v_cndmask_b32_e32 v169, v165, v169, vcc
	v_cvt_pk_f16_f32 v119, v126, v127
	v_cvt_pk_f16_f32 v118, v124, v125
	global_store_dwordx4 v[178:179], v[118:121], off
	s_nop 1
	v_cvt_pk_f16_f32 v119, v112, v113
	s_waitcnt lgkmcnt(0)
	v_add_f32_e32 v113, v114, v115
	v_lshlrev_b32_e32 v112, 2, v169
	ds_bpermute_b32 v114, v112, v113
	v_cvt_pk_f16_f32 v118, v116, v117
	v_cvt_pk_f16_f32 v117, v184, v185
	v_cvt_pk_f16_f32 v116, v176, v177
	global_store_dwordx4 v[180:181], v[116:119], off
	s_and_saveexec_b64 s[16:17], s[4:5]
	s_cbranch_execz .LBB0_300
	v_lshl_add_u32 v136, v167, 4, s18
	s_waitcnt lgkmcnt(0)
	v_add_f32_e32 v113, v113, v114
	v_lshl_add_u64 v[114:115], v[136:137], 2, s[42:43]
	global_store_dword v[114:115], v113, off
.LBB0_300:
	s_or_b64 exec, exec, s[16:17]
	v_add_u32_e32 v113, 16, v167
	v_lshl_add_u32 v136, v113, 10, v168
	v_lshl_add_u64 v[122:123], v[136:137], 1, s[40:41]
	v_add_u32_e32 v136, 0x80, v136
	v_lshl_add_u64 v[124:125], v[136:137], 1, s[40:41]
	s_waitcnt lgkmcnt(0)
	s_waitcnt vmcnt(10)
	v_cvt_f32_f16_e32 v126, v195
	v_cvt_f32_f16_sdwa v127, v195 dst_sel:DWORD dst_unused:UNUSED_PAD src0_sel:WORD_1
	v_cvt_f32_f16_e32 v170, v193
	v_cvt_f32_f16_sdwa v171, v193 dst_sel:DWORD dst_unused:UNUSED_PAD src0_sel:WORD_1
	v_cvt_f32_f16_e32 v172, v194
	v_cvt_f32_f16_sdwa v173, v194 dst_sel:DWORD dst_unused:UNUSED_PAD src0_sel:WORD_1
	v_cvt_f32_f16_e32 v116, v192
	v_cvt_f32_f16_sdwa v117, v192 dst_sel:DWORD dst_unused:UNUSED_PAD src0_sel:WORD_1
	v_cvt_f32_f16_e32 v114, v199
	v_cvt_f32_f16_sdwa v115, v199 dst_sel:DWORD dst_unused:UNUSED_PAD src0_sel:WORD_1
	v_cvt_f32_f16_e32 v174, v197
	v_cvt_f32_f16_sdwa v175, v197 dst_sel:DWORD dst_unused:UNUSED_PAD src0_sel:WORD_1
	v_cvt_f32_f16_e32 v176, v198
	v_cvt_f32_f16_sdwa v177, v198 dst_sel:DWORD dst_unused:UNUSED_PAD src0_sel:WORD_1
	v_cvt_f32_f16_e32 v120, v196
	v_cvt_f32_f16_sdwa v121, v196 dst_sel:DWORD dst_unused:UNUSED_PAD src0_sel:WORD_1
	v_pk_fma_f32 v[108:109], v[108:109], 0.5, v[116:117] op_sel_hi:[1,0,1]
	v_pk_fma_f32 v[116:117], v[104:105], 0.5, v[172:173] op_sel_hi:[1,0,1]
	v_pk_fma_f32 v[110:111], v[110:111], 0.5, v[170:171] op_sel_hi:[1,0,1]
	v_pk_fma_f32 v[106:107], v[106:107], 0.5, v[126:127] op_sel_hi:[1,0,1]
	v_pk_fma_f32 v[120:121], v[100:101], 0.5, v[120:121] op_sel_hi:[1,0,1]
	v_pk_fma_f32 v[170:171], v[96:97], 0.5, v[176:177] op_sel_hi:[1,0,1]
	v_pk_fma_f32 v[172:173], v[102:103], 0.5, v[174:175] op_sel_hi:[1,0,1]
	v_pk_fma_f32 v[96:97], v[98:99], 0.5, v[114:115] op_sel_hi:[1,0,1]
	v_cvt_pk_f16_f32 v105, v106, v107
	v_cvt_pk_f16_f32 v104, v116, v117
	v_pk_mul_f32 v[118:119], v[108:109], v[108:109]
	v_pk_mul_f32 v[126:127], v[110:111], v[110:111]
	v_pk_mul_f32 v[116:117], v[116:117], v[116:117]
	v_pk_mul_f32 v[106:107], v[106:107], v[106:107]
	v_pk_mul_f32 v[98:99], v[120:121], v[120:121]
	v_pk_mul_f32 v[100:101], v[172:173], v[172:173]
	v_pk_mul_f32 v[102:103], v[170:171], v[170:171]
	v_pk_mul_f32 v[114:115], v[96:97], v[96:97]
	v_add_f32_e32 v106, v106, v107
	v_add_f32_e32 v107, v116, v117
	v_add_f32_e32 v116, v126, v127
	v_add_f32_e32 v117, v118, v119
	v_add_f32_e32 v114, v114, v115
	v_add_f32_e32 v102, v102, v103
	v_add_f32_e32 v100, v100, v101
	v_add_f32_e32 v98, v98, v99
	v_add_f32_e32 v106, v107, v106
	v_add_f32_e32 v107, v117, v116
	v_add_f32_e32 v101, v102, v114
	v_add_f32_e32 v98, v98, v100
	v_add_f32_e32 v99, v107, v106
	v_add_f32_e32 v98, v98, v101
	v_add_f32_e32 v98, v99, v98
	ds_bpermute_b32 v99, v166, v98
	v_cvt_pk_f16_f32 v101, v96, v97
	v_cvt_pk_f16_f32 v103, v110, v111
	v_cvt_pk_f16_f32 v102, v108, v109
	v_cvt_pk_f16_f32 v100, v170, v171
	s_waitcnt lgkmcnt(0)
	v_add_f32_e32 v96, v98, v99
	ds_bpermute_b32 v97, v112, v96
	v_cvt_pk_f16_f32 v99, v172, v173
	v_cvt_pk_f16_f32 v98, v120, v121
	global_store_dwordx4 v[122:123], v[102:105], off
	global_store_dwordx4 v[124:125], v[98:101], off
	s_and_saveexec_b64 s[16:17], s[4:5]
	s_cbranch_execz .LBB0_302
	v_lshl_add_u32 v136, v113, 4, s18
	s_waitcnt lgkmcnt(0)
	v_add_f32_e32 v98, v96, v97
	v_lshl_add_u64 v[96:97], v[136:137], 2, s[42:43]
	global_store_dword v[96:97], v98, off
;   __device__ __forceinline__ void operator()(const pg8::f32x4 (&acc)[2][2][4][2], const pg8::Unit& u, int wr, int wc, int fr, int fq) const {
;     ...
;       for (int m = 0; m < 4; ++m) {
;         const int tok = row0 + ai * 128 + m * 16; float ss = 0.f;
; #pragma unroll
;         for (int bj = 0; bj < 2; ++bj) {
;           const unsigned off = (unsigned)tok * DM + colb + 128 * bj;
;           f8_t n = __builtin_convertvector(*(const h8_t*)(x16 + off), f8_t);
; #pragma unroll
;           for (int c = 0; c < 4; ++c) { n[c] += sc * acc[ai][bj][m][0][c]; n[4 + c] += sc * acc[ai][bj][m][1][c]; }
;           if (aux) {
;             *(h8_t*)(x16 + off) = __builtin_convertvector(n, h8_t);
;             ss += ((n[0] * n[0] + n[1] * n[1]) + (n[2] * n[2] + n[3] * n[3])) + ((n[4] * n[4] + n[5] * n[5]) + (n[6] * n[6] + n[7] * n[7]));
;           } else {
;             *(f32x4*)(xout + off) = (f32x4){n[0], n[1], n[2], n[3]}; *(f32x4*)(xout + off + 4) = (f32x4){n[4], n[5], n[6], n[7]};
;           }
;         }
;         if (aux) { ss += __shfl_xor(ss, 16); ss += __shfl_xor(ss, 32); if (fq == 0) ssq[(unsigned)tok * 16 + u.pn * 4 + wc] = ss; }
;         if (m & 1) asm volatile("" ::: "memory");
.LBB0_302:
	s_or_b64 exec, exec, s[16:17]
	v_add_u32_e32 v96, 32, v167
	v_lshl_add_u32 v136, v96, 10, v168
	v_lshl_add_u64 v[106:107], v[136:137], 1, s[40:41]
	v_add_u32_e32 v136, 0x80, v136
	v_lshl_add_u64 v[108:109], v[136:137], 1, s[40:41]
	s_waitcnt vmcnt(10)
	v_cvt_f32_f16_e32 v110, v203
	v_cvt_f32_f16_sdwa v111, v203 dst_sel:DWORD dst_unused:UNUSED_PAD src0_sel:WORD_1
	v_cvt_f32_f16_e32 v114, v201
	v_cvt_f32_f16_sdwa v115, v201 dst_sel:DWORD dst_unused:UNUSED_PAD src0_sel:WORD_1
	v_cvt_f32_f16_e32 v116, v202
	v_cvt_f32_f16_sdwa v117, v202 dst_sel:DWORD dst_unused:UNUSED_PAD src0_sel:WORD_1
	v_cvt_f32_f16_e32 v100, v200
	v_cvt_f32_f16_sdwa v101, v200 dst_sel:DWORD dst_unused:UNUSED_PAD src0_sel:WORD_1
	v_cvt_f32_f16_e32 v98, v207
	v_cvt_f32_f16_sdwa v99, v207 dst_sel:DWORD dst_unused:UNUSED_PAD src0_sel:WORD_1
	v_cvt_f32_f16_e32 v118, v205
	v_cvt_f32_f16_sdwa v119, v205 dst_sel:DWORD dst_unused:UNUSED_PAD src0_sel:WORD_1
	v_cvt_f32_f16_e32 v120, v206
	v_cvt_f32_f16_sdwa v121, v206 dst_sel:DWORD dst_unused:UNUSED_PAD src0_sel:WORD_1
	v_cvt_f32_f16_e32 v104, v204
	v_cvt_f32_f16_sdwa v105, v204 dst_sel:DWORD dst_unused:UNUSED_PAD src0_sel:WORD_1
	v_pk_fma_f32 v[92:93], v[92:93], 0.5, v[100:101] op_sel_hi:[1,0,1]
	v_pk_fma_f32 v[100:101], v[88:89], 0.5, v[116:117] op_sel_hi:[1,0,1]
	v_pk_fma_f32 v[94:95], v[94:95], 0.5, v[114:115] op_sel_hi:[1,0,1]
	v_pk_fma_f32 v[90:91], v[90:91], 0.5, v[110:111] op_sel_hi:[1,0,1]
	v_cvt_pk_f16_f32 v88, v100, v101
	v_cvt_pk_f16_f32 v89, v90, v91
	v_pk_mul_f32 v[102:103], v[92:93], v[92:93]
	v_pk_mul_f32 v[110:111], v[94:95], v[94:95]
	v_pk_mul_f32 v[100:101], v[100:101], v[100:101]
	v_pk_mul_f32 v[90:91], v[90:91], v[90:91]
	v_pk_fma_f32 v[104:105], v[84:85], 0.5, v[104:105] op_sel_hi:[1,0,1]
	v_pk_fma_f32 v[114:115], v[80:81], 0.5, v[120:121] op_sel_hi:[1,0,1]
	v_pk_fma_f32 v[116:117], v[86:87], 0.5, v[118:119] op_sel_hi:[1,0,1]
	v_pk_fma_f32 v[80:81], v[82:83], 0.5, v[98:99] op_sel_hi:[1,0,1]
	v_pk_mul_f32 v[82:83], v[104:105], v[104:105]
	v_pk_mul_f32 v[84:85], v[116:117], v[116:117]
	v_pk_mul_f32 v[86:87], v[114:115], v[114:115]
	v_pk_mul_f32 v[98:99], v[80:81], v[80:81]
	v_add_f32_e32 v90, v90, v91
	v_add_f32_e32 v91, v100, v101
	s_waitcnt lgkmcnt(0)
	v_add_f32_e32 v97, v110, v111
	v_add_f32_e32 v100, v102, v103
	v_add_f32_e32 v90, v91, v90
	v_add_f32_e32 v91, v100, v97
	v_add_f32_e32 v97, v98, v99
	v_add_f32_e32 v86, v86, v87
	v_add_f32_e32 v84, v84, v85
	v_add_f32_e32 v82, v82, v83
	v_add_f32_e32 v85, v86, v97
	v_add_f32_e32 v82, v82, v84
	v_add_f32_e32 v83, v91, v90
	v_add_f32_e32 v82, v82, v85
	v_add_f32_e32 v82, v83, v82
	ds_bpermute_b32 v83, v166, v82
	v_cvt_pk_f16_f32 v85, v80, v81
	v_cvt_pk_f16_f32 v87, v94, v95
	v_cvt_pk_f16_f32 v86, v92, v93
	v_cvt_pk_f16_f32 v84, v114, v115
	s_waitcnt lgkmcnt(0)
	v_add_f32_e32 v80, v82, v83
	ds_bpermute_b32 v81, v112, v80
	v_cvt_pk_f16_f32 v83, v116, v117
	v_cvt_pk_f16_f32 v82, v104, v105
	global_store_dwordx4 v[106:107], v[86:89], off
	global_store_dwordx4 v[108:109], v[82:85], off
	s_and_saveexec_b64 s[16:17], s[4:5]
	s_cbranch_execz .LBB0_304
	v_lshl_add_u32 v136, v96, 4, s18
	s_waitcnt lgkmcnt(0)
	v_add_f32_e32 v82, v80, v81
	v_lshl_add_u64 v[80:81], v[136:137], 2, s[42:43]
	global_store_dword v[80:81], v82, off
.LBB0_304:
	s_or_b64 exec, exec, s[16:17]
	v_add_u32_e32 v80, 48, v167
	v_lshl_add_u32 v136, v80, 10, v168
	v_lshl_add_u64 v[90:91], v[136:137], 1, s[40:41]
	v_add_u32_e32 v136, 0x80, v136
	v_lshl_add_u64 v[92:93], v[136:137], 1, s[40:41]
	s_waitcnt vmcnt(10)
	v_cvt_f32_f16_e32 v94, v211
	v_cvt_f32_f16_sdwa v95, v211 dst_sel:DWORD dst_unused:UNUSED_PAD src0_sel:WORD_1
	v_cvt_f32_f16_e32 v96, v209
	v_cvt_f32_f16_sdwa v97, v209 dst_sel:DWORD dst_unused:UNUSED_PAD src0_sel:WORD_1
	v_cvt_f32_f16_e32 v98, v210
	v_cvt_f32_f16_sdwa v99, v210 dst_sel:DWORD dst_unused:UNUSED_PAD src0_sel:WORD_1
	v_cvt_f32_f16_e32 v84, v208
	v_cvt_f32_f16_sdwa v85, v208 dst_sel:DWORD dst_unused:UNUSED_PAD src0_sel:WORD_1
	v_cvt_f32_f16_e32 v82, v215
	v_cvt_f32_f16_sdwa v83, v215 dst_sel:DWORD dst_unused:UNUSED_PAD src0_sel:WORD_1
	v_cvt_f32_f16_e32 v100, v213
	v_cvt_f32_f16_sdwa v101, v213 dst_sel:DWORD dst_unused:UNUSED_PAD src0_sel:WORD_1
	v_cvt_f32_f16_e32 v102, v214
	v_cvt_f32_f16_sdwa v103, v214 dst_sel:DWORD dst_unused:UNUSED_PAD src0_sel:WORD_1
	v_cvt_f32_f16_e32 v88, v212
	v_cvt_f32_f16_sdwa v89, v212 dst_sel:DWORD dst_unused:UNUSED_PAD src0_sel:WORD_1
	v_pk_fma_f32 v[76:77], v[76:77], 0.5, v[84:85] op_sel_hi:[1,0,1]
	v_pk_fma_f32 v[84:85], v[72:73], 0.5, v[98:99] op_sel_hi:[1,0,1]
	v_pk_fma_f32 v[78:79], v[78:79], 0.5, v[96:97] op_sel_hi:[1,0,1]
	v_pk_fma_f32 v[74:75], v[74:75], 0.5, v[94:95] op_sel_hi:[1,0,1]
	v_cvt_pk_f16_f32 v72, v84, v85
	v_cvt_pk_f16_f32 v73, v74, v75
	v_pk_mul_f32 v[86:87], v[76:77], v[76:77]
	v_pk_mul_f32 v[94:95], v[78:79], v[78:79]
	v_pk_mul_f32 v[84:85], v[84:85], v[84:85]
	v_pk_mul_f32 v[74:75], v[74:75], v[74:75]
	v_pk_fma_f32 v[88:89], v[68:69], 0.5, v[88:89] op_sel_hi:[1,0,1]
	v_pk_fma_f32 v[96:97], v[64:65], 0.5, v[102:103] op_sel_hi:[1,0,1]
	v_pk_fma_f32 v[98:99], v[70:71], 0.5, v[100:101] op_sel_hi:[1,0,1]
	v_pk_fma_f32 v[64:65], v[66:67], 0.5, v[82:83] op_sel_hi:[1,0,1]
	v_pk_mul_f32 v[66:67], v[88:89], v[88:89]
	v_pk_mul_f32 v[68:69], v[98:99], v[98:99]
	v_pk_mul_f32 v[70:71], v[96:97], v[96:97]
	v_pk_mul_f32 v[82:83], v[64:65], v[64:65]
	v_add_f32_e32 v74, v74, v75
	v_add_f32_e32 v75, v84, v85
	s_waitcnt lgkmcnt(0)
	v_add_f32_e32 v81, v94, v95
	v_add_f32_e32 v84, v86, v87
	v_add_f32_e32 v74, v75, v74
	v_add_f32_e32 v75, v84, v81
	v_add_f32_e32 v81, v82, v83
	v_add_f32_e32 v70, v70, v71
	v_add_f32_e32 v68, v68, v69
	v_add_f32_e32 v66, v66, v67
	v_add_f32_e32 v69, v70, v81
	v_add_f32_e32 v66, v66, v68
	v_add_f32_e32 v67, v75, v74
	v_add_f32_e32 v66, v66, v69
	v_add_f32_e32 v66, v67, v66
	ds_bpermute_b32 v67, v166, v66
	v_cvt_pk_f16_f32 v69, v64, v65
	v_cvt_pk_f16_f32 v71, v78, v79
	v_cvt_pk_f16_f32 v70, v76, v77
	v_cvt_pk_f16_f32 v68, v96, v97
	s_waitcnt lgkmcnt(0)
	v_add_f32_e32 v64, v66, v67
	ds_bpermute_b32 v65, v112, v64
	v_cvt_pk_f16_f32 v67, v98, v99
	v_cvt_pk_f16_f32 v66, v88, v89
	global_store_dwordx4 v[90:91], v[70:73], off
	global_store_dwordx4 v[92:93], v[66:69], off
	s_and_saveexec_b64 s[16:17], s[4:5]
	s_cbranch_execz .LBB0_306
	v_lshl_add_u32 v136, v80, 4, s18
	s_waitcnt lgkmcnt(0)
	v_add_f32_e32 v66, v64, v65
	v_lshl_add_u64 v[64:65], v[136:137], 2, s[42:43]
	global_store_dword v[64:65], v66, off
;   __device__ __forceinline__ void operator()(const pg8::f32x4 (&acc)[2][2][4][2], const pg8::Unit& u, int wr, int wc, int fr, int fq) const {
;     ...
;       for (int m = 0; m < 4; ++m) {
;         const int tok = row0 + ai * 128 + m * 16; float ss = 0.f;
; #pragma unroll
;         for (int bj = 0; bj < 2; ++bj) {
;           const unsigned off = (unsigned)tok * DM + colb + 128 * bj;
;           f8_t n = __builtin_convertvector(*(const h8_t*)(x16 + off), f8_t);
; #pragma unroll
;           for (int c = 0; c < 4; ++c) { n[c] += sc * acc[ai][bj][m][0][c]; n[4 + c] += sc * acc[ai][bj][m][1][c]; }
;           if (aux) {
;             *(h8_t*)(x16 + off) = __builtin_convertvector(n, h8_t);
;             ss += ((n[0] * n[0] + n[1] * n[1]) + (n[2] * n[2] + n[3] * n[3])) + ((n[4] * n[4] + n[5] * n[5]) + (n[6] * n[6] + n[7] * n[7]));
;           } else {
;             *(f32x4*)(xout + off) = (f32x4){n[0], n[1], n[2], n[3]}; *(f32x4*)(xout + off + 4) = (f32x4){n[4], n[5], n[6], n[7]};
;           }
;         }
;         if (aux) { ss += __shfl_xor(ss, 16); ss += __shfl_xor(ss, 32); if (fq == 0) ssq[(unsigned)tok * 16 + u.pn * 4 + wc] = ss; }
;         if (m & 1) asm volatile("" ::: "memory");
.LBB0_306:
	s_or_b64 exec, exec, s[16:17]
	v_add_u32_e32 v64, 0x80, v167
	v_lshl_add_u32 v136, v64, 10, v168
	v_lshl_add_u64 v[74:75], v[136:137], 1, s[40:41]
	v_add_u32_e32 v136, 0x80, v136
	v_lshl_add_u64 v[76:77], v[136:137], 1, s[40:41]
	s_waitcnt vmcnt(10)
	v_cvt_f32_f16_e32 v78, v219
	v_cvt_f32_f16_sdwa v79, v219 dst_sel:DWORD dst_unused:UNUSED_PAD src0_sel:WORD_1
	v_cvt_f32_f16_e32 v80, v217
	v_cvt_f32_f16_sdwa v81, v217 dst_sel:DWORD dst_unused:UNUSED_PAD src0_sel:WORD_1
	v_cvt_f32_f16_e32 v82, v218
	v_cvt_f32_f16_sdwa v83, v218 dst_sel:DWORD dst_unused:UNUSED_PAD src0_sel:WORD_1
	v_cvt_f32_f16_e32 v68, v216
	v_cvt_f32_f16_sdwa v69, v216 dst_sel:DWORD dst_unused:UNUSED_PAD src0_sel:WORD_1
	v_cvt_f32_f16_e32 v66, v223
	v_cvt_f32_f16_sdwa v67, v223 dst_sel:DWORD dst_unused:UNUSED_PAD src0_sel:WORD_1
	v_cvt_f32_f16_e32 v84, v221
	v_cvt_f32_f16_sdwa v85, v221 dst_sel:DWORD dst_unused:UNUSED_PAD src0_sel:WORD_1
	v_cvt_f32_f16_e32 v86, v222
	v_cvt_f32_f16_sdwa v87, v222 dst_sel:DWORD dst_unused:UNUSED_PAD src0_sel:WORD_1
	v_cvt_f32_f16_e32 v72, v220
	v_cvt_f32_f16_sdwa v73, v220 dst_sel:DWORD dst_unused:UNUSED_PAD src0_sel:WORD_1
	v_pk_fma_f32 v[60:61], v[60:61], 0.5, v[68:69] op_sel_hi:[1,0,1]
	v_pk_fma_f32 v[68:69], v[56:57], 0.5, v[82:83] op_sel_hi:[1,0,1]
	v_pk_fma_f32 v[62:63], v[62:63], 0.5, v[80:81] op_sel_hi:[1,0,1]
	v_pk_fma_f32 v[58:59], v[58:59], 0.5, v[78:79] op_sel_hi:[1,0,1]
	v_cvt_pk_f16_f32 v56, v68, v69
	v_cvt_pk_f16_f32 v57, v58, v59
	v_pk_mul_f32 v[70:71], v[60:61], v[60:61]
	v_pk_mul_f32 v[78:79], v[62:63], v[62:63]
	v_pk_mul_f32 v[68:69], v[68:69], v[68:69]
	v_pk_mul_f32 v[58:59], v[58:59], v[58:59]
	v_pk_fma_f32 v[72:73], v[52:53], 0.5, v[72:73] op_sel_hi:[1,0,1]
	v_pk_fma_f32 v[80:81], v[48:49], 0.5, v[86:87] op_sel_hi:[1,0,1]
	v_pk_fma_f32 v[82:83], v[54:55], 0.5, v[84:85] op_sel_hi:[1,0,1]
	v_pk_fma_f32 v[48:49], v[50:51], 0.5, v[66:67] op_sel_hi:[1,0,1]
	v_pk_mul_f32 v[50:51], v[72:73], v[72:73]
	v_pk_mul_f32 v[52:53], v[82:83], v[82:83]
	v_pk_mul_f32 v[54:55], v[80:81], v[80:81]
	v_pk_mul_f32 v[66:67], v[48:49], v[48:49]
	v_add_f32_e32 v58, v58, v59
	v_add_f32_e32 v59, v68, v69
	s_waitcnt lgkmcnt(0)
	v_add_f32_e32 v65, v78, v79
	v_add_f32_e32 v68, v70, v71
	v_add_f32_e32 v58, v59, v58
	v_add_f32_e32 v59, v68, v65
	v_add_f32_e32 v65, v66, v67
	v_add_f32_e32 v54, v54, v55
	v_add_f32_e32 v52, v52, v53
	v_add_f32_e32 v50, v50, v51
	v_add_f32_e32 v53, v54, v65
	v_add_f32_e32 v50, v50, v52
	v_add_f32_e32 v51, v59, v58
	v_add_f32_e32 v50, v50, v53
	v_add_f32_e32 v50, v51, v50
	ds_bpermute_b32 v51, v166, v50
	v_cvt_pk_f16_f32 v53, v48, v49
	v_cvt_pk_f16_f32 v55, v62, v63
	v_cvt_pk_f16_f32 v54, v60, v61
	v_cvt_pk_f16_f32 v52, v80, v81
	s_waitcnt lgkmcnt(0)
	v_add_f32_e32 v48, v50, v51
	ds_bpermute_b32 v49, v112, v48
	v_cvt_pk_f16_f32 v51, v82, v83
	v_cvt_pk_f16_f32 v50, v72, v73
	global_store_dwordx4 v[74:75], v[54:57], off
	global_store_dwordx4 v[76:77], v[50:53], off
	s_and_saveexec_b64 s[16:17], s[4:5]
	s_cbranch_execz .LBB0_308
	v_lshl_add_u32 v136, v64, 4, s18
	s_waitcnt lgkmcnt(0)
	v_add_f32_e32 v50, v48, v49
	v_lshl_add_u64 v[48:49], v[136:137], 2, s[42:43]
	global_store_dword v[48:49], v50, off
.LBB0_308:
	s_or_b64 exec, exec, s[16:17]
	v_add_u32_e32 v48, 0x90, v167
	v_lshl_add_u32 v136, v48, 10, v168
	v_lshl_add_u64 v[58:59], v[136:137], 1, s[40:41]
	v_add_u32_e32 v136, 0x80, v136
	v_lshl_add_u64 v[60:61], v[136:137], 1, s[40:41]
	s_waitcnt vmcnt(10)
	v_cvt_f32_f16_e32 v62, v231
	v_cvt_f32_f16_sdwa v63, v231 dst_sel:DWORD dst_unused:UNUSED_PAD src0_sel:WORD_1
	v_cvt_f32_f16_e32 v64, v229
	v_cvt_f32_f16_sdwa v65, v229 dst_sel:DWORD dst_unused:UNUSED_PAD src0_sel:WORD_1
	v_cvt_f32_f16_e32 v66, v230
	v_cvt_f32_f16_sdwa v67, v230 dst_sel:DWORD dst_unused:UNUSED_PAD src0_sel:WORD_1
	v_cvt_f32_f16_e32 v52, v228
	v_cvt_f32_f16_sdwa v53, v228 dst_sel:DWORD dst_unused:UNUSED_PAD src0_sel:WORD_1
	v_cvt_f32_f16_e32 v50, v247
	v_cvt_f32_f16_sdwa v51, v247 dst_sel:DWORD dst_unused:UNUSED_PAD src0_sel:WORD_1
	v_cvt_f32_f16_e32 v68, v245
	v_cvt_f32_f16_sdwa v69, v245 dst_sel:DWORD dst_unused:UNUSED_PAD src0_sel:WORD_1
	v_cvt_f32_f16_e32 v70, v246
	v_cvt_f32_f16_sdwa v71, v246 dst_sel:DWORD dst_unused:UNUSED_PAD src0_sel:WORD_1
	v_cvt_f32_f16_e32 v56, v244
	v_cvt_f32_f16_sdwa v57, v244 dst_sel:DWORD dst_unused:UNUSED_PAD src0_sel:WORD_1
	v_pk_fma_f32 v[44:45], v[44:45], 0.5, v[52:53] op_sel_hi:[1,0,1]
	v_pk_fma_f32 v[52:53], v[40:41], 0.5, v[66:67] op_sel_hi:[1,0,1]
	v_pk_fma_f32 v[46:47], v[46:47], 0.5, v[64:65] op_sel_hi:[1,0,1]
	v_pk_fma_f32 v[42:43], v[42:43], 0.5, v[62:63] op_sel_hi:[1,0,1]
	v_cvt_pk_f16_f32 v40, v52, v53
	v_cvt_pk_f16_f32 v41, v42, v43
	v_pk_mul_f32 v[54:55], v[44:45], v[44:45]
	v_pk_mul_f32 v[62:63], v[46:47], v[46:47]
	v_pk_mul_f32 v[52:53], v[52:53], v[52:53]
	v_pk_mul_f32 v[42:43], v[42:43], v[42:43]
	v_pk_fma_f32 v[56:57], v[36:37], 0.5, v[56:57] op_sel_hi:[1,0,1]
	v_pk_fma_f32 v[64:65], v[32:33], 0.5, v[70:71] op_sel_hi:[1,0,1]
	v_pk_fma_f32 v[66:67], v[38:39], 0.5, v[68:69] op_sel_hi:[1,0,1]
	v_pk_fma_f32 v[32:33], v[34:35], 0.5, v[50:51] op_sel_hi:[1,0,1]
	v_pk_mul_f32 v[34:35], v[56:57], v[56:57]
	v_pk_mul_f32 v[36:37], v[66:67], v[66:67]
	v_pk_mul_f32 v[38:39], v[64:65], v[64:65]
	v_pk_mul_f32 v[50:51], v[32:33], v[32:33]
	v_add_f32_e32 v42, v42, v43
	v_add_f32_e32 v43, v52, v53
	s_waitcnt lgkmcnt(0)
	v_add_f32_e32 v49, v62, v63
	v_add_f32_e32 v52, v54, v55
	v_add_f32_e32 v42, v43, v42
	v_add_f32_e32 v43, v52, v49
	v_add_f32_e32 v49, v50, v51
	v_add_f32_e32 v38, v38, v39
	v_add_f32_e32 v36, v36, v37
	v_add_f32_e32 v34, v34, v35
	v_add_f32_e32 v37, v38, v49
	v_add_f32_e32 v34, v34, v36
	v_add_f32_e32 v35, v43, v42
	v_add_f32_e32 v34, v34, v37
	v_add_f32_e32 v34, v35, v34
	ds_bpermute_b32 v35, v166, v34
	v_cvt_pk_f16_f32 v37, v32, v33
	v_cvt_pk_f16_f32 v39, v46, v47
	v_cvt_pk_f16_f32 v38, v44, v45
	v_cvt_pk_f16_f32 v36, v64, v65
	s_waitcnt lgkmcnt(0)
	v_add_f32_e32 v32, v34, v35
	ds_bpermute_b32 v33, v112, v32
	v_cvt_pk_f16_f32 v35, v66, v67
	v_cvt_pk_f16_f32 v34, v56, v57
	global_store_dwordx4 v[58:59], v[38:41], off
	global_store_dwordx4 v[60:61], v[34:37], off
	s_and_saveexec_b64 s[16:17], s[4:5]
	s_cbranch_execz .LBB0_310
	v_lshl_add_u32 v136, v48, 4, s18
	s_waitcnt lgkmcnt(0)
	v_add_f32_e32 v34, v32, v33
	v_lshl_add_u64 v[32:33], v[136:137], 2, s[42:43]
	global_store_dword v[32:33], v34, off

; #define PG8_STAGE(bufoff, gbase, voff) do { _Pragma("unroll") for (int _i = 0; _i < 2; ++_i) \
;         __builtin_amdgcn_global_load_lds((const unsigned*)((const char*)(gbase) + (voff)[_i]), (PG8_LAS unsigned*)(lds + (bufoff) + ldsw + _i * 8192), 16, 0, 0); } while (0)
; #define PG8_LDA(dst, b, h) do { _Pragma("unroll") for (int m = 0; m < 4; ++m) _Pragma("unroll") for (int k = 0; k < 2; ++k) dst[m][k] = *(const PG8_LAS bf16x8*)(lds + PG8_SA(b, h) + aoff + m * 2048 + k * 1024); } while (0)
; #define PG8_LDB(dst, b, h) do { _Pragma("unroll") for (int n = 0; n < 2; ++n) _Pragma("unroll") for (int k = 0; k < 2; ++k) dst[n][k] = *(const PG8_LAS bf16x8*)(lds + PG8_SB(b, h) + boff + n * 2048 + k * 1024); } while (0)
; #define PG8_MMA(ai, bj, At, Bt) do { __builtin_amdgcn_s_setprio(1); _Pragma("unroll") for (int m = 0; m < 4; ++m) _Pragma("unroll") for (int n = 0; n < 2; ++n) _Pragma("unroll") for (int k = 0; k < 2; ++k) \
;         acc[ai][bj][m][n] = mma16<F16>(Bt[n][k], At[m][k], acc[ai][bj][m][n]); __builtin_amdgcn_s_setprio(0); } while (0)
; #define PG8_WAIT_V(n) asm volatile("s_waitcnt vmcnt(" #n ")" ::: "memory")
; #define PG8_WAIT_L(n) asm volatile("s_waitcnt lgkmcnt(" #n ")" ::: "memory")
; #define PG8_BAR __builtin_amdgcn_s_barrier()
; #define PG8_SCHED __builtin_amdgcn_sched_barrier(0)
; template <class Epi, class Sched, bool ALIGN_EPI = false, bool SP2 = false, bool F16 = false, bool TOKPERM = false>
; __device__ __forceinline__ void gemm_phase(PG8_LAS unsigned char* lds, const Gemm g, const Sched& S, const Epi& E, int wv) {
;     ...
;             PG8_LDB(B0, 0, 0); PG8_LDB(B1, 0, 1); PG8_SCHED; PG8_LDA(At, 0, 0); PG8_STAGE(PG8_SA(1, 1), a1 + hstep, voffA);
;             PG8_WAIT_V(8); PG8_WAIT_L(0); PG8_BAR; PG8_MMA(0, 0, At, B0); PG8_MMA(0, 1, At, B1); PG8_BAR; PG8_SCHED;
;             PG8_LDA(At, 0, 1); PG8_STAGE(PG8_SB(0, 0), b2, voffB); PG8_STAGE(PG8_SB(0, 1), b2 + hstep, voffB); PG8_STAGE(PG8_SA(0, 0), a2, voffA);
.LBB0_685:
	ds_read_b128 v[166:169], v149
	ds_read_b128 v[170:173], v150
	ds_read_b128 v[174:177], v151
	ds_read_b128 v[178:181], v152
	ds_read_b128 v[182:185], v153
	ds_read_b128 v[186:189], v154
	ds_read_b128 v[190:193], v155
	ds_read_b128 v[194:197], v156
	s_add_u32 s54, s52, 0xfffc0080
	s_addc_u32 s55, s53, -1
	s_cmp_eq_u32 s69, 12
	s_cselect_b32 s57, s13, s55
	s_cselect_b32 s56, s49, s54
	s_cselect_b32 s55, s11, s68
	s_cselect_b32 s54, s66, s67
	s_mov_b32 m0, s64
	v_lshl_add_u64 v[232:233], s[52:53], 0, v[138:139]
	ds_read_b128 v[198:201], v147
	ds_read_b128 v[202:205], v147 offset:1024
	ds_read_b128 v[206:209], v147 offset:2048
	ds_read_b128 v[210:213], v147 offset:3072
	ds_read_b128 v[214:217], v147 offset:4096
	ds_read_b128 v[218:221], v147 offset:5120
	ds_read_b128 v[222:225], v147 offset:6144
	ds_read_b128 v[228:231], v147 offset:7168
	global_load_lds_dwordx4 v[232:233], off
	v_lshl_add_u64 v[232:233], s[52:53], 0, v[140:141]
	s_mov_b32 m0, s65
	s_nop 0
	global_load_lds_dwordx4 v[232:233], off
	s_waitcnt vmcnt(8)
	s_waitcnt lgkmcnt(0)
	s_barrier
	s_setprio 1
	s_waitcnt lgkmcnt(0)
	v_mfma_f32_16x16x32_bf16 v[124:127], v[166:169], v[198:201], v[124:127]
	v_mfma_f32_16x16x32_bf16 v[120:123], v[174:177], v[198:201], v[120:123]
	v_mfma_f32_16x16x32_bf16 v[108:111], v[166:169], v[206:209], v[108:111]
	v_mfma_f32_16x16x32_bf16 v[104:107], v[174:177], v[206:209], v[104:107]
	v_mfma_f32_16x16x32_bf16 v[92:95], v[166:169], v[214:217], v[92:95]
	v_mfma_f32_16x16x32_bf16 v[88:91], v[174:177], v[214:217], v[88:91]
	v_mfma_f32_16x16x32_bf16 v[76:79], v[166:169], v[222:225], v[76:79]
	v_mfma_f32_16x16x32_bf16 v[72:75], v[174:177], v[222:225], v[72:75]
	v_mfma_f32_16x16x32_bf16 v[124:127], v[170:173], v[202:205], v[124:127]
	v_mfma_f32_16x16x32_bf16 v[120:123], v[178:181], v[202:205], v[120:123]
	v_mfma_f32_16x16x32_bf16 v[108:111], v[170:173], v[210:213], v[108:111]
	v_mfma_f32_16x16x32_bf16 v[104:107], v[178:181], v[210:213], v[104:107]
	v_mfma_f32_16x16x32_bf16 v[92:95], v[170:173], v[218:221], v[92:95]
	v_mfma_f32_16x16x32_bf16 v[88:91], v[178:181], v[218:221], v[88:91]
	v_mfma_f32_16x16x32_bf16 v[76:79], v[170:173], v[228:231], v[76:79]
	v_mfma_f32_16x16x32_bf16 v[72:75], v[178:181], v[228:231], v[72:75]
	s_setprio 0
	s_setprio 1
	v_mfma_f32_16x16x32_bf16 v[116:119], v[182:185], v[198:201], v[116:119]
	v_mfma_f32_16x16x32_bf16 v[112:115], v[190:193], v[198:201], v[112:115]
	v_mfma_f32_16x16x32_bf16 v[100:103], v[182:185], v[206:209], v[100:103]
	v_mfma_f32_16x16x32_bf16 v[96:99], v[190:193], v[206:209], v[96:99]
	v_mfma_f32_16x16x32_bf16 v[84:87], v[182:185], v[214:217], v[84:87]
	v_mfma_f32_16x16x32_bf16 v[80:83], v[190:193], v[214:217], v[80:83]
	v_mfma_f32_16x16x32_bf16 v[68:71], v[182:185], v[222:225], v[68:71]
	v_mfma_f32_16x16x32_bf16 v[64:67], v[190:193], v[222:225], v[64:67]
	v_mfma_f32_16x16x32_bf16 v[116:119], v[186:189], v[202:205], v[116:119]
	v_mfma_f32_16x16x32_bf16 v[112:115], v[194:197], v[202:205], v[112:115]
	v_mfma_f32_16x16x32_bf16 v[100:103], v[186:189], v[210:213], v[100:103]
	v_mfma_f32_16x16x32_bf16 v[96:99], v[194:197], v[210:213], v[96:99]
	v_mfma_f32_16x16x32_bf16 v[84:87], v[186:189], v[218:221], v[84:87]
	v_mfma_f32_16x16x32_bf16 v[80:83], v[194:197], v[218:221], v[80:83]
	v_mfma_f32_16x16x32_bf16 v[68:71], v[186:189], v[228:231], v[68:71]
	v_mfma_f32_16x16x32_bf16 v[64:67], v[194:197], v[228:231], v[64:67]
	s_setprio 0
	s_barrier
	s_mov_b32 m0, s2
	v_lshl_add_u64 v[232:233], s[54:55], 0, v[130:131]
	s_add_u32 s70, s54, 0x40000
	ds_read_b128 v[198:201], v147 offset:16384
	ds_read_b128 v[202:205], v147 offset:17408
	ds_read_b128 v[206:209], v147 offset:18432
	ds_read_b128 v[210:213], v147 offset:19456
	ds_read_b128 v[214:217], v147 offset:20480
	ds_read_b128 v[218:221], v147 offset:21504
	ds_read_b128 v[222:225], v147 offset:22528
	ds_read_b128 v[228:231], v147 offset:23552
	global_load_lds_dwordx4 v[232:233], off
	v_lshl_add_u64 v[234:235], s[54:55], 0, v[134:135]
	s_mov_b32 m0, s3
	s_addc_u32 s71, s55, 0
	global_load_lds_dwordx4 v[234:235], off
	v_lshl_add_u64 v[236:237], s[70:71], 0, v[130:131]
	s_mov_b32 m0, s20
	v_lshl_add_u64 v[238:239], s[56:57], 0, v[132:133]
	global_load_lds_dwordx4 v[236:237], off
	v_lshl_add_u64 v[236:237], s[70:71], 0, v[134:135]
	s_mov_b32 m0, s21
	s_nop 0
	global_load_lds_dwordx4 v[236:237], off
	v_lshl_add_u64 v[236:237], s[56:57], 0, v[128:129]
	s_mov_b32 m0, s1
	s_nop 0
	global_load_lds_dwordx4 v[236:237], off
	s_mov_b32 m0, s22
	s_nop 0
	global_load_lds_dwordx4 v[238:239], off
	s_waitcnt vmcnt(8)
	s_waitcnt lgkmcnt(0)
	s_barrier
; #define PG8_STAGE(bufoff, gbase, voff) do { _Pragma("unroll") for (int _i = 0; _i < 2; ++_i) \
;         __builtin_amdgcn_global_load_lds((const unsigned*)((const char*)(gbase) + (voff)[_i]), (PG8_LAS unsigned*)(lds + (bufoff) + ldsw + _i * 8192), 16, 0, 0); } while (0)
; #define PG8_LDA(dst, b, h) do { _Pragma("unroll") for (int m = 0; m < 4; ++m) _Pragma("unroll") for (int k = 0; k < 2; ++k) dst[m][k] = *(const PG8_LAS bf16x8*)(lds + PG8_SA(b, h) + aoff + m * 2048 + k * 1024); } while (0)
; #define PG8_LDB(dst, b, h) do { _Pragma("unroll") for (int n = 0; n < 2; ++n) _Pragma("unroll") for (int k = 0; k < 2; ++k) dst[n][k] = *(const PG8_LAS bf16x8*)(lds + PG8_SB(b, h) + boff + n * 2048 + k * 1024); } while (0)
; #define PG8_MMA(ai, bj, At, Bt) do { __builtin_amdgcn_s_setprio(1); _Pragma("unroll") for (int m = 0; m < 4; ++m) _Pragma("unroll") for (int n = 0; n < 2; ++n) _Pragma("unroll") for (int k = 0; k < 2; ++k) \
;         acc[ai][bj][m][n] = mma16<F16>(Bt[n][k], At[m][k], acc[ai][bj][m][n]); __builtin_amdgcn_s_setprio(0); } while (0)
; #define PG8_WAIT_V(n) asm volatile("s_waitcnt vmcnt(" #n ")" ::: "memory")
; #define PG8_WAIT_L(n) asm volatile("s_waitcnt lgkmcnt(" #n ")" ::: "memory")
; #define PG8_BAR __builtin_amdgcn_s_barrier()
; #define PG8_SCHED __builtin_amdgcn_sched_barrier(0)
; template <class Epi, class Sched, bool ALIGN_EPI = false, bool SP2 = false, bool F16 = false, bool TOKPERM = false>
; __device__ __forceinline__ void gemm_phase(PG8_LAS unsigned char* lds, const Gemm g, const Sched& S, const Epi& E, int wv) {
;     ...
;             PG8_WAIT_V(8); PG8_WAIT_L(0); PG8_BAR; PG8_MMA(1, 0, At, B0); PG8_MMA(1, 1, At, B1); PG8_BAR; PG8_SCHED;
;             PG8_LDB(B0, 1, 0); PG8_LDB(B1, 1, 1); PG8_SCHED; PG8_LDA(At, 1, 0); PG8_STAGE(PG8_SA(0, 1), a2 + hstep, voffA);
;             PG8_WAIT_V(8); PG8_WAIT_L(0); PG8_BAR; PG8_MMA(0, 0, At, B0); PG8_MMA(0, 1, At, B1); PG8_BAR; PG8_SCHED;
	s_setprio 1
	s_waitcnt lgkmcnt(0)
	v_mfma_f32_16x16x32_bf16 v[60:63], v[166:169], v[198:201], v[60:63]
	v_mfma_f32_16x16x32_bf16 v[56:59], v[174:177], v[198:201], v[56:59]
	v_mfma_f32_16x16x32_bf16 v[44:47], v[166:169], v[206:209], v[44:47]
	v_mfma_f32_16x16x32_bf16 v[40:43], v[174:177], v[206:209], v[40:43]
	v_mfma_f32_16x16x32_bf16 v[28:31], v[166:169], v[214:217], v[28:31]
	v_mfma_f32_16x16x32_bf16 v[24:27], v[174:177], v[214:217], v[24:27]
	v_mfma_f32_16x16x32_bf16 v[12:15], v[166:169], v[222:225], v[12:15]
	v_mfma_f32_16x16x32_bf16 v[8:11], v[174:177], v[222:225], v[8:11]
	v_mfma_f32_16x16x32_bf16 v[60:63], v[170:173], v[202:205], v[60:63]
	v_mfma_f32_16x16x32_bf16 v[56:59], v[178:181], v[202:205], v[56:59]
	v_mfma_f32_16x16x32_bf16 v[44:47], v[170:173], v[210:213], v[44:47]
	v_mfma_f32_16x16x32_bf16 v[40:43], v[178:181], v[210:213], v[40:43]
	v_mfma_f32_16x16x32_bf16 v[28:31], v[170:173], v[218:221], v[28:31]
	v_mfma_f32_16x16x32_bf16 v[24:27], v[178:181], v[218:221], v[24:27]
	v_mfma_f32_16x16x32_bf16 v[12:15], v[170:173], v[228:231], v[12:15]
	v_mfma_f32_16x16x32_bf16 v[8:11], v[178:181], v[228:231], v[8:11]
	s_setprio 0
	s_setprio 1
	v_mfma_f32_16x16x32_bf16 v[52:55], v[182:185], v[198:201], v[52:55]
	v_mfma_f32_16x16x32_bf16 v[48:51], v[190:193], v[198:201], v[48:51]
	v_mfma_f32_16x16x32_bf16 v[36:39], v[182:185], v[206:209], v[36:39]
	v_mfma_f32_16x16x32_bf16 v[32:35], v[190:193], v[206:209], v[32:35]
	v_mfma_f32_16x16x32_bf16 v[20:23], v[182:185], v[214:217], v[20:23]
	v_mfma_f32_16x16x32_bf16 v[16:19], v[190:193], v[214:217], v[16:19]
	v_mfma_f32_16x16x32_bf16 v[4:7], v[182:185], v[222:225], v[4:7]
	v_mfma_f32_16x16x32_bf16 v[0:3], v[190:193], v[222:225], v[0:3]
	v_mfma_f32_16x16x32_bf16 v[52:55], v[186:189], v[202:205], v[52:55]
	v_mfma_f32_16x16x32_bf16 v[48:51], v[194:197], v[202:205], v[48:51]
	v_mfma_f32_16x16x32_bf16 v[36:39], v[186:189], v[210:213], v[36:39]
	v_mfma_f32_16x16x32_bf16 v[32:35], v[194:197], v[210:213], v[32:35]
	v_mfma_f32_16x16x32_bf16 v[20:23], v[186:189], v[218:221], v[20:23]
	v_mfma_f32_16x16x32_bf16 v[16:19], v[194:197], v[218:221], v[16:19]
	v_mfma_f32_16x16x32_bf16 v[4:7], v[186:189], v[228:231], v[4:7]
	v_mfma_f32_16x16x32_bf16 v[0:3], v[194:197], v[228:231], v[0:3]
	s_setprio 0
	s_barrier
	ds_read_b128 v[166:169], v157
	ds_read_b128 v[170:173], v158
	ds_read_b128 v[174:177], v159
	ds_read_b128 v[178:181], v160
	ds_read_b128 v[182:185], v161
	ds_read_b128 v[186:189], v162
	ds_read_b128 v[190:193], v163
	ds_read_b128 v[194:197], v164
	s_add_u32 s56, s56, 0x40000
	s_addc_u32 s57, s57, 0
	s_mov_b32 m0, s23
	v_lshl_add_u64 v[240:241], s[56:57], 0, v[128:129]
	ds_read_b128 v[198:201], v147 offset:32768
	ds_read_b128 v[202:205], v147 offset:33792
	ds_read_b128 v[206:209], v147 offset:34816
	ds_read_b128 v[210:213], v147 offset:35840
	ds_read_b128 v[214:217], v147 offset:36864
	ds_read_b128 v[218:221], v147 offset:37888
	ds_read_b128 v[222:225], v147 offset:38912
	ds_read_b128 v[228:231], v147 offset:39936
	global_load_lds_dwordx4 v[240:241], off
	v_lshl_add_u64 v[240:241], s[56:57], 0, v[132:133]
	s_mov_b32 m0, s33
	s_nop 0
	global_load_lds_dwordx4 v[240:241], off
	s_waitcnt vmcnt(8)
	s_waitcnt lgkmcnt(0)
	s_barrier
	s_setprio 1
	s_waitcnt lgkmcnt(0)
	v_mfma_f32_16x16x32_bf16 v[124:127], v[166:169], v[198:201], v[124:127]
	v_mfma_f32_16x16x32_bf16 v[120:123], v[174:177], v[198:201], v[120:123]
	v_mfma_f32_16x16x32_bf16 v[108:111], v[166:169], v[206:209], v[108:111]
	v_mfma_f32_16x16x32_bf16 v[104:107], v[174:177], v[206:209], v[104:107]
	v_mfma_f32_16x16x32_bf16 v[92:95], v[166:169], v[214:217], v[92:95]
	v_mfma_f32_16x16x32_bf16 v[88:91], v[174:177], v[214:217], v[88:91]
	v_mfma_f32_16x16x32_bf16 v[76:79], v[166:169], v[222:225], v[76:79]
	v_mfma_f32_16x16x32_bf16 v[72:75], v[174:177], v[222:225], v[72:75]
	v_mfma_f32_16x16x32_bf16 v[124:127], v[170:173], v[202:205], v[124:127]
	v_mfma_f32_16x16x32_bf16 v[120:123], v[178:181], v[202:205], v[120:123]
	v_mfma_f32_16x16x32_bf16 v[108:111], v[170:173], v[210:213], v[108:111]
	v_mfma_f32_16x16x32_bf16 v[104:107], v[178:181], v[210:213], v[104:107]
	v_mfma_f32_16x16x32_bf16 v[92:95], v[170:173], v[218:221], v[92:95]
	v_mfma_f32_16x16x32_bf16 v[88:91], v[178:181], v[218:221], v[88:91]
	v_mfma_f32_16x16x32_bf16 v[76:79], v[170:173], v[228:231], v[76:79]
	v_mfma_f32_16x16x32_bf16 v[72:75], v[178:181], v[228:231], v[72:75]
	s_setprio 0
	s_setprio 1
	v_mfma_f32_16x16x32_bf16 v[116:119], v[182:185], v[198:201], v[116:119]
	v_mfma_f32_16x16x32_bf16 v[112:115], v[190:193], v[198:201], v[112:115]
	v_mfma_f32_16x16x32_bf16 v[100:103], v[182:185], v[206:209], v[100:103]
	v_mfma_f32_16x16x32_bf16 v[96:99], v[190:193], v[206:209], v[96:99]
	v_mfma_f32_16x16x32_bf16 v[84:87], v[182:185], v[214:217], v[84:87]
	v_mfma_f32_16x16x32_bf16 v[80:83], v[190:193], v[214:217], v[80:83]
	v_mfma_f32_16x16x32_bf16 v[68:71], v[182:185], v[222:225], v[68:71]
	v_mfma_f32_16x16x32_bf16 v[64:67], v[190:193], v[222:225], v[64:67]
	v_mfma_f32_16x16x32_bf16 v[116:119], v[186:189], v[202:205], v[116:119]
	v_mfma_f32_16x16x32_bf16 v[112:115], v[194:197], v[202:205], v[112:115]
	v_mfma_f32_16x16x32_bf16 v[100:103], v[186:189], v[210:213], v[100:103]
	v_mfma_f32_16x16x32_bf16 v[96:99], v[194:197], v[210:213], v[96:99]
	v_mfma_f32_16x16x32_bf16 v[84:87], v[186:189], v[218:221], v[84:87]
	v_mfma_f32_16x16x32_bf16 v[80:83], v[194:197], v[218:221], v[80:83]
	v_mfma_f32_16x16x32_bf16 v[68:71], v[186:189], v[228:231], v[68:71]
	v_mfma_f32_16x16x32_bf16 v[64:67], v[194:197], v[228:231], v[64:67]
	s_setprio 0
	s_barrier
; #define PG8_STAGE(bufoff, gbase, voff) do { _Pragma("unroll") for (int _i = 0; _i < 2; ++_i) \
;         __builtin_amdgcn_global_load_lds((const unsigned*)((const char*)(gbase) + (voff)[_i]), (PG8_LAS unsigned*)(lds + (bufoff) + ldsw + _i * 8192), 16, 0, 0); } while (0)
; #define PG8_LDA(dst, b, h) do { _Pragma("unroll") for (int m = 0; m < 4; ++m) _Pragma("unroll") for (int k = 0; k < 2; ++k) dst[m][k] = *(const PG8_LAS bf16x8*)(lds + PG8_SA(b, h) + aoff + m * 2048 + k * 1024); } while (0)
; #define PG8_MMA(ai, bj, At, Bt) do { __builtin_amdgcn_s_setprio(1); _Pragma("unroll") for (int m = 0; m < 4; ++m) _Pragma("unroll") for (int n = 0; n < 2; ++n) _Pragma("unroll") for (int k = 0; k < 2; ++k) \
;         acc[ai][bj][m][n] = mma16<F16>(Bt[n][k], At[m][k], acc[ai][bj][m][n]); __builtin_amdgcn_s_setprio(0); } while (0)
; template <class Epi, class Sched, bool ALIGN_EPI = false, bool SP2 = false, bool F16 = false, bool TOKPERM = false>
; __device__ __forceinline__ void gemm_phase(PG8_LAS unsigned char* lds, const Gemm g, const Sched& S, const Epi& E, int wv) {
;     ...
;             PG8_LDA(At, 1, 1); PG8_STAGE(PG8_SB(1, 0), b3, voffB); PG8_STAGE(PG8_SB(1, 1), b3 + hstep, voffB); PG8_STAGE(PG8_SA(1, 0), a3, voffA);
;             PG8_WAIT_V(8); PG8_WAIT_L(0); PG8_BAR; PG8_MMA(1, 0, At, B0); PG8_MMA(1, 1, At, B1); PG8_BAR; PG8_SCHED;
;   __device__ __forceinline__ void operator()(const pg8::f32x4 (&acc)[2][2][4][2], const pg8::Unit& u, int wr, int wc, int fr, int fq) const {
;     int z; asm volatile("v_mov_b32 %0, 0" : "=v"(z));
;     const int row0 = u.pm * 256 + wr * 64 + fr + z, colb = u.pn * 256 + wc * 32 + 8 * fq + z;
; #pragma unroll
;     for (int ai = 0; ai < 2; ++ai)
; #pragma unroll
;       for (int m = 0; m < 4; ++m) {
;         const int tok = row0 + ai * 128 + m * 16; float ss = 0.f;
; #pragma unroll
;         for (int bj = 0; bj < 2; ++bj) {
;           const unsigned off = (unsigned)tok * DM + colb + 128 * bj;
;           f8_t n = __builtin_convertvector(*(const h8_t*)(x16 + off), f8_t);
; #pragma unroll
;           for (int c = 0; c < 4; ++c) { n[c] += sc * acc[ai][bj][m][0][c]; n[4 + c] += sc * acc[ai][bj][m][1][c]; }
;           if (aux) {
;             *(h8_t*)(x16 + off) = __builtin_convertvector(n, h8_t);
;             ss += ((n[0] * n[0] + n[1] * n[1]) + (n[2] * n[2] + n[3] * n[3])) + ((n[4] * n[4] + n[5] * n[5]) + (n[6] * n[6] + n[7] * n[7]));
	s_mov_b32 m0, s37
	v_lshl_add_u64 v[232:233], v[232:233], 0, s[8:9]
	s_add_u32 s54, s54, 0x40080
	ds_read_b128 v[198:201], v147 offset:49152
	ds_read_b128 v[202:205], v147 offset:50176
	ds_read_b128 v[206:209], v147 offset:51200
	ds_read_b128 v[210:213], v147 offset:52224
	ds_read_b128 v[214:217], v147 offset:53248
	ds_read_b128 v[218:221], v147 offset:54272
	ds_read_b128 v[222:225], v147 offset:55296
	ds_read_b128 v[228:231], v147 offset:56320
	global_load_lds_dwordx4 v[232:233], off
	v_lshl_add_u64 v[232:233], v[234:235], 0, s[8:9]
	s_mov_b32 m0, s44
	s_addc_u32 s55, s55, 0
	global_load_lds_dwordx4 v[232:233], off
	v_lshl_add_u64 v[232:233], s[54:55], 0, v[130:131]
	s_mov_b32 m0, s58
	s_nop 0
	global_load_lds_dwordx4 v[232:233], off
	v_lshl_add_u64 v[232:233], s[54:55], 0, v[134:135]
	s_mov_b32 m0, s59
	s_nop 0
	global_load_lds_dwordx4 v[232:233], off
	v_lshl_add_u64 v[232:233], v[236:237], 0, s[8:9]
	s_mov_b32 m0, s45
	s_nop 0
	global_load_lds_dwordx4 v[232:233], off
	v_lshl_add_u64 v[232:233], v[238:239], 0, s[8:9]
	s_mov_b32 m0, s51
	s_nop 0
	global_load_lds_dwordx4 v[232:233], off
	s_waitcnt vmcnt(8)
	s_waitcnt lgkmcnt(0)
	s_barrier
	s_setprio 1
	s_waitcnt lgkmcnt(0)
	v_mfma_f32_16x16x32_bf16 v[60:63], v[166:169], v[198:201], v[60:63]
	v_mfma_f32_16x16x32_bf16 v[56:59], v[174:177], v[198:201], v[56:59]
	v_mfma_f32_16x16x32_bf16 v[44:47], v[166:169], v[206:209], v[44:47]
	v_mfma_f32_16x16x32_bf16 v[40:43], v[174:177], v[206:209], v[40:43]
	v_mfma_f32_16x16x32_bf16 v[28:31], v[166:169], v[214:217], v[28:31]
	v_mfma_f32_16x16x32_bf16 v[24:27], v[174:177], v[214:217], v[24:27]
	v_mfma_f32_16x16x32_bf16 v[12:15], v[166:169], v[222:225], v[12:15]
	v_mfma_f32_16x16x32_bf16 v[8:11], v[174:177], v[222:225], v[8:11]
	v_mfma_f32_16x16x32_bf16 v[60:63], v[170:173], v[202:205], v[60:63]
	v_mfma_f32_16x16x32_bf16 v[56:59], v[178:181], v[202:205], v[56:59]
	v_mfma_f32_16x16x32_bf16 v[44:47], v[170:173], v[210:213], v[44:47]
	v_mfma_f32_16x16x32_bf16 v[40:43], v[178:181], v[210:213], v[40:43]
	v_mfma_f32_16x16x32_bf16 v[28:31], v[170:173], v[218:221], v[28:31]
	v_mfma_f32_16x16x32_bf16 v[24:27], v[178:181], v[218:221], v[24:27]
	v_mfma_f32_16x16x32_bf16 v[12:15], v[170:173], v[228:231], v[12:15]
	v_mfma_f32_16x16x32_bf16 v[8:11], v[178:181], v[228:231], v[8:11]
	s_setprio 0
	s_setprio 1
	v_mfma_f32_16x16x32_bf16 v[52:55], v[182:185], v[198:201], v[52:55]
	v_mfma_f32_16x16x32_bf16 v[48:51], v[190:193], v[198:201], v[48:51]
	v_mfma_f32_16x16x32_bf16 v[36:39], v[182:185], v[206:209], v[36:39]
	v_mfma_f32_16x16x32_bf16 v[32:35], v[190:193], v[206:209], v[32:35]
	v_mfma_f32_16x16x32_bf16 v[20:23], v[182:185], v[214:217], v[20:23]
	v_mfma_f32_16x16x32_bf16 v[16:19], v[190:193], v[214:217], v[16:19]
	v_mfma_f32_16x16x32_bf16 v[4:7], v[182:185], v[222:225], v[4:7]
	v_mfma_f32_16x16x32_bf16 v[0:3], v[190:193], v[222:225], v[0:3]
	v_mfma_f32_16x16x32_bf16 v[52:55], v[186:189], v[202:205], v[52:55]
	v_mfma_f32_16x16x32_bf16 v[48:51], v[194:197], v[202:205], v[48:51]
	v_mfma_f32_16x16x32_bf16 v[36:39], v[186:189], v[210:213], v[36:39]
	v_mfma_f32_16x16x32_bf16 v[32:35], v[194:197], v[210:213], v[32:35]
	v_mfma_f32_16x16x32_bf16 v[20:23], v[186:189], v[218:221], v[20:23]
	v_mfma_f32_16x16x32_bf16 v[16:19], v[194:197], v[218:221], v[16:19]
	v_mfma_f32_16x16x32_bf16 v[4:7], v[186:189], v[228:231], v[4:7]
	v_mfma_f32_16x16x32_bf16 v[0:3], v[194:197], v[228:231], v[0:3]
	s_setprio 0
	s_barrier
	s_add_i32 s69, s69, 2
	s_add_u32 s52, s52, 0x100
	s_addc_u32 s53, s53, 0
	s_add_u32 s67, s67, 0x100
	s_addc_u32 s68, s68, 0
	s_cmp_gt_u32 s69, 13
	s_cbranch_scc0 .LBB0_685
	s_lshl_b32 s11, s50, 8
	v_lshl_or_b32 v166, s48, 8, v148
	v_mov_b32 v136, 0
	v_xor_b32_e32 v169, 32, v165
	v_add3_u32 v167, s11, v146, v136
	v_add_u32_e32 v168, v166, v136
	v_lshl_add_u32 v136, v167, 10, v168
	v_lshl_add_u64 v[178:179], v[136:137], 1, s[40:41]
	v_add_u32_e32 v136, 0x80, v136
	global_load_dwordx4 v[170:173], v[178:179], off
	v_lshl_add_u64 v[180:181], v[136:137], 1, s[40:41]
	global_load_dwordx4 v[174:177], v[180:181], off
	v_add_u32_e32 v136, 16, v167
	v_lshl_add_u32 v136, v136, 10, v168
	v_lshl_add_u64 v[224:225], v[136:137], 1, s[40:41]
	v_add_u32_e32 v136, 0x80, v136
	global_load_dwordx4 v[192:195], v[224:225], off
	v_lshl_add_u64 v[248:249], v[136:137], 1, s[40:41]
	global_load_dwordx4 v[196:199], v[248:249], off
	v_add_u32_e32 v136, 32, v167
	v_lshl_add_u32 v136, v136, 10, v168
	v_lshl_add_u64 v[224:225], v[136:137], 1, s[40:41]
	v_add_u32_e32 v136, 0x80, v136
	global_load_dwordx4 v[200:203], v[224:225], off
	v_lshl_add_u64 v[248:249], v[136:137], 1, s[40:41]
	global_load_dwordx4 v[204:207], v[248:249], off
	v_add_u32_e32 v136, 48, v167
	v_lshl_add_u32 v136, v136, 10, v168
	v_lshl_add_u64 v[224:225], v[136:137], 1, s[40:41]
	v_add_u32_e32 v136, 0x80, v136
	global_load_dwordx4 v[208:211], v[224:225], off
	v_lshl_add_u64 v[248:249], v[136:137], 1, s[40:41]
	global_load_dwordx4 v[212:215], v[248:249], off
	v_add_u32_e32 v136, 0x80, v167
	v_lshl_add_u32 v136, v136, 10, v168
	v_lshl_add_u64 v[224:225], v[136:137], 1, s[40:41]
	v_add_u32_e32 v136, 0x80, v136
	global_load_dwordx4 v[216:219], v[224:225], off
	v_lshl_add_u64 v[248:249], v[136:137], 1, s[40:41]
	global_load_dwordx4 v[220:223], v[248:249], off
	v_add_u32_e32 v136, 0x90, v167
	v_lshl_add_u32 v136, v136, 10, v168
	v_lshl_add_u64 v[224:225], v[136:137], 1, s[40:41]
	v_add_u32_e32 v136, 0x80, v136
	global_load_dwordx4 v[228:231], v[224:225], off
	v_lshl_add_u64 v[248:249], v[136:137], 1, s[40:41]
	global_load_dwordx4 v[244:247], v[248:249], off
	v_and_b32_e32 v166, 64, v165
	v_xor_b32_e32 v136, 16, v165
	v_add_u32_e32 v166, 64, v166
	v_cmp_lt_i32_e32 vcc, v136, v166
	s_lshl_b32 s11, s48, 2
	s_or_b32 s11, s11, s36
	v_cndmask_b32_e32 v136, v165, v136, vcc
	v_cmp_lt_i32_e32 vcc, v169, v166
	v_lshlrev_b32_e32 v166, 2, v136
	s_waitcnt vmcnt(10)
;   __device__ __forceinline__ void operator()(const pg8::f32x4 (&acc)[2][2][4][2], const pg8::Unit& u, int wr, int wc, int fr, int fq) const {
;     ...
;       for (int m = 0; m < 4; ++m) {
;         const int tok = row0 + ai * 128 + m * 16; float ss = 0.f;
; #pragma unroll
;         for (int bj = 0; bj < 2; ++bj) {
;           const unsigned off = (unsigned)tok * DM + colb + 128 * bj;
;           f8_t n = __builtin_convertvector(*(const h8_t*)(x16 + off), f8_t);
; #pragma unroll
;           for (int c = 0; c < 4; ++c) { n[c] += sc * acc[ai][bj][m][0][c]; n[4 + c] += sc * acc[ai][bj][m][1][c]; }
;           if (aux) {
;             *(h8_t*)(x16 + off) = __builtin_convertvector(n, h8_t);
;             ss += ((n[0] * n[0] + n[1] * n[1]) + (n[2] * n[2] + n[3] * n[3])) + ((n[4] * n[4] + n[5] * n[5]) + (n[6] * n[6] + n[7] * n[7]));
;           } else {
;             *(f32x4*)(xout + off) = (f32x4){n[0], n[1], n[2], n[3]}; *(f32x4*)(xout + off + 4) = (f32x4){n[4], n[5], n[6], n[7]};
;           }
;         }
;         if (aux) { ss += __shfl_xor(ss, 16); ss += __shfl_xor(ss, 32); if (fq == 0) ssq[(unsigned)tok * 16 + u.pn * 4 + wc] = ss; }
;         if (m & 1) asm volatile("" ::: "memory");
	v_cvt_f32_f16_e32 v182, v173
	v_cvt_f32_f16_sdwa v183, v173 dst_sel:DWORD dst_unused:UNUSED_PAD src0_sel:WORD_1
	v_cvt_f32_f16_e32 v184, v171
	v_cvt_f32_f16_sdwa v185, v171 dst_sel:DWORD dst_unused:UNUSED_PAD src0_sel:WORD_1
	v_cvt_f32_f16_e32 v186, v172
	v_cvt_f32_f16_sdwa v187, v172 dst_sel:DWORD dst_unused:UNUSED_PAD src0_sel:WORD_1
	v_cvt_f32_f16_e32 v172, v170
	v_cvt_f32_f16_sdwa v173, v170 dst_sel:DWORD dst_unused:UNUSED_PAD src0_sel:WORD_1
	v_cvt_f32_f16_e32 v170, v177
	v_cvt_f32_f16_sdwa v171, v177 dst_sel:DWORD dst_unused:UNUSED_PAD src0_sel:WORD_1
	v_cvt_f32_f16_e32 v188, v175
	v_cvt_f32_f16_sdwa v189, v175 dst_sel:DWORD dst_unused:UNUSED_PAD src0_sel:WORD_1
	v_cvt_f32_f16_e32 v190, v176
	v_cvt_f32_f16_sdwa v191, v176 dst_sel:DWORD dst_unused:UNUSED_PAD src0_sel:WORD_1
	v_cvt_f32_f16_e32 v176, v174
	v_cvt_f32_f16_sdwa v177, v174 dst_sel:DWORD dst_unused:UNUSED_PAD src0_sel:WORD_1
	v_pk_add_f32 v[124:125], v[124:125], v[172:173]
	v_pk_add_f32 v[172:173], v[120:121], v[186:187]
	v_pk_add_f32 v[126:127], v[126:127], v[184:185]
	v_pk_add_f32 v[122:123], v[122:123], v[182:183]
	v_cvt_pk_f16_f32 v120, v172, v173
	v_cvt_pk_f16_f32 v121, v122, v123
	v_pk_mul_f32 v[174:175], v[124:125], v[124:125]
	v_pk_mul_f32 v[182:183], v[126:127], v[126:127]
	v_pk_mul_f32 v[172:173], v[172:173], v[172:173]
	v_pk_mul_f32 v[122:123], v[122:123], v[122:123]
	v_pk_add_f32 v[176:177], v[116:117], v[176:177]
	v_pk_add_f32 v[116:117], v[112:113], v[190:191]
	v_pk_add_f32 v[184:185], v[118:119], v[188:189]
	v_pk_add_f32 v[112:113], v[114:115], v[170:171]
	v_pk_mul_f32 v[114:115], v[176:177], v[176:177]
	v_pk_mul_f32 v[118:119], v[184:185], v[184:185]
	v_pk_mul_f32 v[170:171], v[116:117], v[116:117]
	v_pk_mul_f32 v[186:187], v[112:113], v[112:113]
	v_add_f32_e32 v122, v122, v123
	v_add_f32_e32 v123, v172, v173
	v_add_f32_e32 v136, v182, v183
	v_add_f32_e32 v172, v174, v175
	v_add_f32_e32 v122, v123, v122
	v_add_f32_e32 v123, v172, v136
	v_add_f32_e32 v136, v186, v187
	v_add_f32_e32 v170, v170, v171
	v_add_f32_e32 v118, v118, v119
	v_add_f32_e32 v114, v114, v115
	v_add_f32_e32 v119, v170, v136
	v_add_f32_e32 v114, v114, v118
	v_add_f32_e32 v115, v123, v122
	v_add_f32_e32 v114, v114, v119
	v_add_f32_e32 v114, v115, v114
	ds_bpermute_b32 v115, v166, v114
	v_cndmask_b32_e32 v169, v165, v169, vcc
	v_cvt_pk_f16_f32 v119, v126, v127
	v_cvt_pk_f16_f32 v118, v124, v125
	global_store_dwordx4 v[178:179], v[118:121], off
	s_nop 1
	v_cvt_pk_f16_f32 v119, v112, v113
	s_waitcnt lgkmcnt(0)
	v_add_f32_e32 v113, v114, v115
	v_lshlrev_b32_e32 v112, 2, v169
	ds_bpermute_b32 v114, v112, v113
	v_cvt_pk_f16_f32 v118, v116, v117
	v_cvt_pk_f16_f32 v117, v184, v185
	v_cvt_pk_f16_f32 v116, v176, v177
	global_store_dwordx4 v[180:181], v[116:119], off
	s_and_saveexec_b64 s[48:49], s[4:5]
	s_cbranch_execz .LBB0_688
	v_lshl_add_u32 v136, v167, 4, s11
	s_waitcnt lgkmcnt(0)
	v_add_f32_e32 v113, v113, v114
	v_lshl_add_u64 v[114:115], v[136:137], 2, s[42:43]
	global_store_dword v[114:115], v113, off
.LBB0_688:
	s_or_b64 exec, exec, s[48:49]
	v_add_u32_e32 v113, 16, v167
	v_lshl_add_u32 v136, v113, 10, v168
	v_lshl_add_u64 v[122:123], v[136:137], 1, s[40:41]
	v_add_u32_e32 v136, 0x80, v136
	v_lshl_add_u64 v[124:125], v[136:137], 1, s[40:41]
	s_waitcnt lgkmcnt(0)
	s_waitcnt vmcnt(10)
	v_cvt_f32_f16_e32 v126, v195
	v_cvt_f32_f16_sdwa v127, v195 dst_sel:DWORD dst_unused:UNUSED_PAD src0_sel:WORD_1
	v_cvt_f32_f16_e32 v170, v193
	v_cvt_f32_f16_sdwa v171, v193 dst_sel:DWORD dst_unused:UNUSED_PAD src0_sel:WORD_1
	v_cvt_f32_f16_e32 v172, v194
	v_cvt_f32_f16_sdwa v173, v194 dst_sel:DWORD dst_unused:UNUSED_PAD src0_sel:WORD_1
	v_cvt_f32_f16_e32 v116, v192
	v_cvt_f32_f16_sdwa v117, v192 dst_sel:DWORD dst_unused:UNUSED_PAD src0_sel:WORD_1
	v_cvt_f32_f16_e32 v114, v199
	v_cvt_f32_f16_sdwa v115, v199 dst_sel:DWORD dst_unused:UNUSED_PAD src0_sel:WORD_1
	v_cvt_f32_f16_e32 v174, v197
	v_cvt_f32_f16_sdwa v175, v197 dst_sel:DWORD dst_unused:UNUSED_PAD src0_sel:WORD_1
	v_cvt_f32_f16_e32 v176, v198
	v_cvt_f32_f16_sdwa v177, v198 dst_sel:DWORD dst_unused:UNUSED_PAD src0_sel:WORD_1
	v_cvt_f32_f16_e32 v120, v196
	v_cvt_f32_f16_sdwa v121, v196 dst_sel:DWORD dst_unused:UNUSED_PAD src0_sel:WORD_1
	v_pk_add_f32 v[108:109], v[108:109], v[116:117]
	v_pk_add_f32 v[116:117], v[104:105], v[172:173]
	v_pk_add_f32 v[110:111], v[110:111], v[170:171]
	v_pk_add_f32 v[106:107], v[106:107], v[126:127]
	v_pk_add_f32 v[120:121], v[100:101], v[120:121]
	v_pk_add_f32 v[170:171], v[96:97], v[176:177]
	v_pk_add_f32 v[172:173], v[102:103], v[174:175]
	v_pk_add_f32 v[96:97], v[98:99], v[114:115]
	v_cvt_pk_f16_f32 v105, v106, v107
	v_cvt_pk_f16_f32 v104, v116, v117
	v_pk_mul_f32 v[118:119], v[108:109], v[108:109]
	v_pk_mul_f32 v[126:127], v[110:111], v[110:111]
	v_pk_mul_f32 v[116:117], v[116:117], v[116:117]
	v_pk_mul_f32 v[106:107], v[106:107], v[106:107]
	v_pk_mul_f32 v[98:99], v[120:121], v[120:121]
	v_pk_mul_f32 v[100:101], v[172:173], v[172:173]
	v_pk_mul_f32 v[102:103], v[170:171], v[170:171]
	v_pk_mul_f32 v[114:115], v[96:97], v[96:97]
	v_add_f32_e32 v106, v106, v107
	v_add_f32_e32 v107, v116, v117
	v_add_f32_e32 v116, v126, v127
	v_add_f32_e32 v117, v118, v119
	v_add_f32_e32 v114, v114, v115
	v_add_f32_e32 v102, v102, v103
	v_add_f32_e32 v100, v100, v101
	v_add_f32_e32 v98, v98, v99
	v_add_f32_e32 v106, v107, v106
	v_add_f32_e32 v107, v117, v116
	v_add_f32_e32 v101, v102, v114
	v_add_f32_e32 v98, v98, v100
	v_add_f32_e32 v99, v107, v106
	v_add_f32_e32 v98, v98, v101
	v_add_f32_e32 v98, v99, v98
	ds_bpermute_b32 v99, v166, v98
	v_cvt_pk_f16_f32 v101, v96, v97
	v_cvt_pk_f16_f32 v103, v110, v111
	v_cvt_pk_f16_f32 v102, v108, v109
	v_cvt_pk_f16_f32 v100, v170, v171
	s_waitcnt lgkmcnt(0)
	v_add_f32_e32 v96, v98, v99
	ds_bpermute_b32 v97, v112, v96
	v_cvt_pk_f16_f32 v99, v172, v173
	v_cvt_pk_f16_f32 v98, v120, v121
	global_store_dwordx4 v[122:123], v[102:105], off
	global_store_dwordx4 v[124:125], v[98:101], off
	s_and_saveexec_b64 s[48:49], s[4:5]
	s_cbranch_execz .LBB0_690
	v_lshl_add_u32 v136, v113, 4, s11
	s_waitcnt lgkmcnt(0)
	v_add_f32_e32 v98, v96, v97
	v_lshl_add_u64 v[96:97], v[136:137], 2, s[42:43]
	global_store_dword v[96:97], v98, off
;   __device__ __forceinline__ void operator()(const pg8::f32x4 (&acc)[2][2][4][2], const pg8::Unit& u, int wr, int wc, int fr, int fq) const {
;     ...
;       for (int m = 0; m < 4; ++m) {
;         const int tok = row0 + ai * 128 + m * 16; float ss = 0.f;
; #pragma unroll
;         for (int bj = 0; bj < 2; ++bj) {
;           const unsigned off = (unsigned)tok * DM + colb + 128 * bj;
;           f8_t n = __builtin_convertvector(*(const h8_t*)(x16 + off), f8_t);
; #pragma unroll
;           for (int c = 0; c < 4; ++c) { n[c] += sc * acc[ai][bj][m][0][c]; n[4 + c] += sc * acc[ai][bj][m][1][c]; }
;           if (aux) {
;             *(h8_t*)(x16 + off) = __builtin_convertvector(n, h8_t);
;             ss += ((n[0] * n[0] + n[1] * n[1]) + (n[2] * n[2] + n[3] * n[3])) + ((n[4] * n[4] + n[5] * n[5]) + (n[6] * n[6] + n[7] * n[7]));
;           } else {
;             *(f32x4*)(xout + off) = (f32x4){n[0], n[1], n[2], n[3]}; *(f32x4*)(xout + off + 4) = (f32x4){n[4], n[5], n[6], n[7]};
;           }
;         }
;         if (aux) { ss += __shfl_xor(ss, 16); ss += __shfl_xor(ss, 32); if (fq == 0) ssq[(unsigned)tok * 16 + u.pn * 4 + wc] = ss; }
;         if (m & 1) asm volatile("" ::: "memory");
.LBB0_690:
	s_or_b64 exec, exec, s[48:49]
	v_add_u32_e32 v96, 32, v167
	v_lshl_add_u32 v136, v96, 10, v168
	v_lshl_add_u64 v[106:107], v[136:137], 1, s[40:41]
	v_add_u32_e32 v136, 0x80, v136
	v_lshl_add_u64 v[108:109], v[136:137], 1, s[40:41]
	s_waitcnt vmcnt(10)
	v_cvt_f32_f16_e32 v110, v203
	v_cvt_f32_f16_sdwa v111, v203 dst_sel:DWORD dst_unused:UNUSED_PAD src0_sel:WORD_1
	v_cvt_f32_f16_e32 v114, v201
	v_cvt_f32_f16_sdwa v115, v201 dst_sel:DWORD dst_unused:UNUSED_PAD src0_sel:WORD_1
	v_cvt_f32_f16_e32 v116, v202
	v_cvt_f32_f16_sdwa v117, v202 dst_sel:DWORD dst_unused:UNUSED_PAD src0_sel:WORD_1
	v_cvt_f32_f16_e32 v100, v200
	v_cvt_f32_f16_sdwa v101, v200 dst_sel:DWORD dst_unused:UNUSED_PAD src0_sel:WORD_1
	v_cvt_f32_f16_e32 v98, v207
	v_cvt_f32_f16_sdwa v99, v207 dst_sel:DWORD dst_unused:UNUSED_PAD src0_sel:WORD_1
	v_cvt_f32_f16_e32 v118, v205
	v_cvt_f32_f16_sdwa v119, v205 dst_sel:DWORD dst_unused:UNUSED_PAD src0_sel:WORD_1
	v_cvt_f32_f16_e32 v120, v206
	v_cvt_f32_f16_sdwa v121, v206 dst_sel:DWORD dst_unused:UNUSED_PAD src0_sel:WORD_1
	v_cvt_f32_f16_e32 v104, v204
	v_cvt_f32_f16_sdwa v105, v204 dst_sel:DWORD dst_unused:UNUSED_PAD src0_sel:WORD_1
	v_pk_add_f32 v[92:93], v[92:93], v[100:101]
	v_pk_add_f32 v[100:101], v[88:89], v[116:117]
	v_pk_add_f32 v[94:95], v[94:95], v[114:115]
	v_pk_add_f32 v[90:91], v[90:91], v[110:111]
	v_cvt_pk_f16_f32 v88, v100, v101
	v_cvt_pk_f16_f32 v89, v90, v91
	v_pk_mul_f32 v[102:103], v[92:93], v[92:93]
	v_pk_mul_f32 v[110:111], v[94:95], v[94:95]
	v_pk_mul_f32 v[100:101], v[100:101], v[100:101]
	v_pk_mul_f32 v[90:91], v[90:91], v[90:91]
	v_pk_add_f32 v[104:105], v[84:85], v[104:105]
	v_pk_add_f32 v[114:115], v[80:81], v[120:121]
	v_pk_add_f32 v[116:117], v[86:87], v[118:119]
	v_pk_add_f32 v[80:81], v[82:83], v[98:99]
	v_pk_mul_f32 v[82:83], v[104:105], v[104:105]
	v_pk_mul_f32 v[84:85], v[116:117], v[116:117]
	v_pk_mul_f32 v[86:87], v[114:115], v[114:115]
	v_pk_mul_f32 v[98:99], v[80:81], v[80:81]
	v_add_f32_e32 v90, v90, v91
	v_add_f32_e32 v91, v100, v101
	s_waitcnt lgkmcnt(0)
	v_add_f32_e32 v97, v110, v111
	v_add_f32_e32 v100, v102, v103
	v_add_f32_e32 v90, v91, v90
	v_add_f32_e32 v91, v100, v97
	v_add_f32_e32 v97, v98, v99
	v_add_f32_e32 v86, v86, v87
	v_add_f32_e32 v84, v84, v85
	v_add_f32_e32 v82, v82, v83
	v_add_f32_e32 v85, v86, v97
	v_add_f32_e32 v82, v82, v84
	v_add_f32_e32 v83, v91, v90
	v_add_f32_e32 v82, v82, v85
	v_add_f32_e32 v82, v83, v82
	ds_bpermute_b32 v83, v166, v82
	v_cvt_pk_f16_f32 v85, v80, v81
	v_cvt_pk_f16_f32 v87, v94, v95
	v_cvt_pk_f16_f32 v86, v92, v93
	v_cvt_pk_f16_f32 v84, v114, v115
	s_waitcnt lgkmcnt(0)
	v_add_f32_e32 v80, v82, v83
	ds_bpermute_b32 v81, v112, v80
	v_cvt_pk_f16_f32 v83, v116, v117
	v_cvt_pk_f16_f32 v82, v104, v105
	global_store_dwordx4 v[106:107], v[86:89], off
	global_store_dwordx4 v[108:109], v[82:85], off
	s_and_saveexec_b64 s[48:49], s[4:5]
	s_cbranch_execz .LBB0_692
	v_lshl_add_u32 v136, v96, 4, s11
	s_waitcnt lgkmcnt(0)
	v_add_f32_e32 v82, v80, v81
	v_lshl_add_u64 v[80:81], v[136:137], 2, s[42:43]
	global_store_dword v[80:81], v82, off
.LBB0_692:
	s_or_b64 exec, exec, s[48:49]
	v_add_u32_e32 v80, 48, v167
	v_lshl_add_u32 v136, v80, 10, v168
	v_lshl_add_u64 v[90:91], v[136:137], 1, s[40:41]
	v_add_u32_e32 v136, 0x80, v136
	v_lshl_add_u64 v[92:93], v[136:137], 1, s[40:41]
	s_waitcnt vmcnt(10)
	v_cvt_f32_f16_e32 v94, v211
	v_cvt_f32_f16_sdwa v95, v211 dst_sel:DWORD dst_unused:UNUSED_PAD src0_sel:WORD_1
	v_cvt_f32_f16_e32 v96, v209
	v_cvt_f32_f16_sdwa v97, v209 dst_sel:DWORD dst_unused:UNUSED_PAD src0_sel:WORD_1
	v_cvt_f32_f16_e32 v98, v210
	v_cvt_f32_f16_sdwa v99, v210 dst_sel:DWORD dst_unused:UNUSED_PAD src0_sel:WORD_1
	v_cvt_f32_f16_e32 v84, v208
	v_cvt_f32_f16_sdwa v85, v208 dst_sel:DWORD dst_unused:UNUSED_PAD src0_sel:WORD_1
	v_cvt_f32_f16_e32 v82, v215
	v_cvt_f32_f16_sdwa v83, v215 dst_sel:DWORD dst_unused:UNUSED_PAD src0_sel:WORD_1
	v_cvt_f32_f16_e32 v100, v213
	v_cvt_f32_f16_sdwa v101, v213 dst_sel:DWORD dst_unused:UNUSED_PAD src0_sel:WORD_1
	v_cvt_f32_f16_e32 v102, v214
	v_cvt_f32_f16_sdwa v103, v214 dst_sel:DWORD dst_unused:UNUSED_PAD src0_sel:WORD_1
	v_cvt_f32_f16_e32 v88, v212
	v_cvt_f32_f16_sdwa v89, v212 dst_sel:DWORD dst_unused:UNUSED_PAD src0_sel:WORD_1
	v_pk_add_f32 v[76:77], v[76:77], v[84:85]
	v_pk_add_f32 v[84:85], v[72:73], v[98:99]
	v_pk_add_f32 v[78:79], v[78:79], v[96:97]
	v_pk_add_f32 v[74:75], v[74:75], v[94:95]
	v_cvt_pk_f16_f32 v72, v84, v85
	v_cvt_pk_f16_f32 v73, v74, v75
	v_pk_mul_f32 v[86:87], v[76:77], v[76:77]
	v_pk_mul_f32 v[94:95], v[78:79], v[78:79]
	v_pk_mul_f32 v[84:85], v[84:85], v[84:85]
	v_pk_mul_f32 v[74:75], v[74:75], v[74:75]
	v_pk_add_f32 v[88:89], v[68:69], v[88:89]
	v_pk_add_f32 v[96:97], v[64:65], v[102:103]
	v_pk_add_f32 v[98:99], v[70:71], v[100:101]
	v_pk_add_f32 v[64:65], v[66:67], v[82:83]
	v_pk_mul_f32 v[66:67], v[88:89], v[88:89]
	v_pk_mul_f32 v[68:69], v[98:99], v[98:99]
	v_pk_mul_f32 v[70:71], v[96:97], v[96:97]
	v_pk_mul_f32 v[82:83], v[64:65], v[64:65]
	v_add_f32_e32 v74, v74, v75
	v_add_f32_e32 v75, v84, v85
	s_waitcnt lgkmcnt(0)
	v_add_f32_e32 v81, v94, v95
	v_add_f32_e32 v84, v86, v87
	v_add_f32_e32 v74, v75, v74
	v_add_f32_e32 v75, v84, v81
	v_add_f32_e32 v81, v82, v83
	v_add_f32_e32 v70, v70, v71
	v_add_f32_e32 v68, v68, v69
	v_add_f32_e32 v66, v66, v67
	v_add_f32_e32 v69, v70, v81
	v_add_f32_e32 v66, v66, v68
	v_add_f32_e32 v67, v75, v74
	v_add_f32_e32 v66, v66, v69
	v_add_f32_e32 v66, v67, v66
	ds_bpermute_b32 v67, v166, v66
	v_cvt_pk_f16_f32 v69, v64, v65
	v_cvt_pk_f16_f32 v71, v78, v79
	v_cvt_pk_f16_f32 v70, v76, v77
	v_cvt_pk_f16_f32 v68, v96, v97
	s_waitcnt lgkmcnt(0)
	v_add_f32_e32 v64, v66, v67
	ds_bpermute_b32 v65, v112, v64
	v_cvt_pk_f16_f32 v67, v98, v99
	v_cvt_pk_f16_f32 v66, v88, v89
	global_store_dwordx4 v[90:91], v[70:73], off
	global_store_dwordx4 v[92:93], v[66:69], off
	s_and_saveexec_b64 s[48:49], s[4:5]
	s_cbranch_execz .LBB0_694
	v_lshl_add_u32 v136, v80, 4, s11
	s_waitcnt lgkmcnt(0)
	v_add_f32_e32 v66, v64, v65
	v_lshl_add_u64 v[64:65], v[136:137], 2, s[42:43]
	global_store_dword v[64:65], v66, off
;   __device__ __forceinline__ void operator()(const pg8::f32x4 (&acc)[2][2][4][2], const pg8::Unit& u, int wr, int wc, int fr, int fq) const {
;     ...
;       for (int m = 0; m < 4; ++m) {
;         const int tok = row0 + ai * 128 + m * 16; float ss = 0.f;
; #pragma unroll
;         for (int bj = 0; bj < 2; ++bj) {
;           const unsigned off = (unsigned)tok * DM + colb + 128 * bj;
;           f8_t n = __builtin_convertvector(*(const h8_t*)(x16 + off), f8_t);
; #pragma unroll
;           for (int c = 0; c < 4; ++c) { n[c] += sc * acc[ai][bj][m][0][c]; n[4 + c] += sc * acc[ai][bj][m][1][c]; }
;           if (aux) {
;             *(h8_t*)(x16 + off) = __builtin_convertvector(n, h8_t);
;             ss += ((n[0] * n[0] + n[1] * n[1]) + (n[2] * n[2] + n[3] * n[3])) + ((n[4] * n[4] + n[5] * n[5]) + (n[6] * n[6] + n[7] * n[7]));
;           } else {
;             *(f32x4*)(xout + off) = (f32x4){n[0], n[1], n[2], n[3]}; *(f32x4*)(xout + off + 4) = (f32x4){n[4], n[5], n[6], n[7]};
;           }
;         }
;         if (aux) { ss += __shfl_xor(ss, 16); ss += __shfl_xor(ss, 32); if (fq == 0) ssq[(unsigned)tok * 16 + u.pn * 4 + wc] = ss; }
;         if (m & 1) asm volatile("" ::: "memory");
.LBB0_694:
	s_or_b64 exec, exec, s[48:49]
	v_add_u32_e32 v64, 0x80, v167
	v_lshl_add_u32 v136, v64, 10, v168
	v_lshl_add_u64 v[74:75], v[136:137], 1, s[40:41]
	v_add_u32_e32 v136, 0x80, v136
	v_lshl_add_u64 v[76:77], v[136:137], 1, s[40:41]
	s_waitcnt vmcnt(10)
	v_cvt_f32_f16_e32 v78, v219
	v_cvt_f32_f16_sdwa v79, v219 dst_sel:DWORD dst_unused:UNUSED_PAD src0_sel:WORD_1
	v_cvt_f32_f16_e32 v80, v217
	v_cvt_f32_f16_sdwa v81, v217 dst_sel:DWORD dst_unused:UNUSED_PAD src0_sel:WORD_1
	v_cvt_f32_f16_e32 v82, v218
	v_cvt_f32_f16_sdwa v83, v218 dst_sel:DWORD dst_unused:UNUSED_PAD src0_sel:WORD_1
	v_cvt_f32_f16_e32 v68, v216
	v_cvt_f32_f16_sdwa v69, v216 dst_sel:DWORD dst_unused:UNUSED_PAD src0_sel:WORD_1
	v_cvt_f32_f16_e32 v66, v223
	v_cvt_f32_f16_sdwa v67, v223 dst_sel:DWORD dst_unused:UNUSED_PAD src0_sel:WORD_1
	v_cvt_f32_f16_e32 v84, v221
	v_cvt_f32_f16_sdwa v85, v221 dst_sel:DWORD dst_unused:UNUSED_PAD src0_sel:WORD_1
	v_cvt_f32_f16_e32 v86, v222
	v_cvt_f32_f16_sdwa v87, v222 dst_sel:DWORD dst_unused:UNUSED_PAD src0_sel:WORD_1
	v_cvt_f32_f16_e32 v72, v220
	v_cvt_f32_f16_sdwa v73, v220 dst_sel:DWORD dst_unused:UNUSED_PAD src0_sel:WORD_1
	v_pk_add_f32 v[60:61], v[60:61], v[68:69]
	v_pk_add_f32 v[68:69], v[56:57], v[82:83]
	v_pk_add_f32 v[62:63], v[62:63], v[80:81]
	v_pk_add_f32 v[58:59], v[58:59], v[78:79]
	v_cvt_pk_f16_f32 v56, v68, v69
	v_cvt_pk_f16_f32 v57, v58, v59
	v_pk_mul_f32 v[70:71], v[60:61], v[60:61]
	v_pk_mul_f32 v[78:79], v[62:63], v[62:63]
	v_pk_mul_f32 v[68:69], v[68:69], v[68:69]
	v_pk_mul_f32 v[58:59], v[58:59], v[58:59]
	v_pk_add_f32 v[72:73], v[52:53], v[72:73]
	v_pk_add_f32 v[80:81], v[48:49], v[86:87]
	v_pk_add_f32 v[82:83], v[54:55], v[84:85]
	v_pk_add_f32 v[48:49], v[50:51], v[66:67]
	v_pk_mul_f32 v[50:51], v[72:73], v[72:73]
	v_pk_mul_f32 v[52:53], v[82:83], v[82:83]
	v_pk_mul_f32 v[54:55], v[80:81], v[80:81]
	v_pk_mul_f32 v[66:67], v[48:49], v[48:49]
	v_add_f32_e32 v58, v58, v59
	v_add_f32_e32 v59, v68, v69
	s_waitcnt lgkmcnt(0)
	v_add_f32_e32 v65, v78, v79
	v_add_f32_e32 v68, v70, v71
	v_add_f32_e32 v58, v59, v58
	v_add_f32_e32 v59, v68, v65
	v_add_f32_e32 v65, v66, v67
	v_add_f32_e32 v54, v54, v55
	v_add_f32_e32 v52, v52, v53
	v_add_f32_e32 v50, v50, v51
	v_add_f32_e32 v53, v54, v65
	v_add_f32_e32 v50, v50, v52
	v_add_f32_e32 v51, v59, v58
	v_add_f32_e32 v50, v50, v53
	v_add_f32_e32 v50, v51, v50
	ds_bpermute_b32 v51, v166, v50
	v_cvt_pk_f16_f32 v53, v48, v49
	v_cvt_pk_f16_f32 v55, v62, v63
	v_cvt_pk_f16_f32 v54, v60, v61
	v_cvt_pk_f16_f32 v52, v80, v81
	s_waitcnt lgkmcnt(0)
	v_add_f32_e32 v48, v50, v51
	ds_bpermute_b32 v49, v112, v48
	v_cvt_pk_f16_f32 v51, v82, v83
	v_cvt_pk_f16_f32 v50, v72, v73
	global_store_dwordx4 v[74:75], v[54:57], off
	global_store_dwordx4 v[76:77], v[50:53], off
	s_and_saveexec_b64 s[48:49], s[4:5]
	s_cbranch_execz .LBB0_696
	v_lshl_add_u32 v136, v64, 4, s11
	s_waitcnt lgkmcnt(0)
	v_add_f32_e32 v50, v48, v49
	v_lshl_add_u64 v[48:49], v[136:137], 2, s[42:43]
	global_store_dword v[48:49], v50, off
.LBB0_696:
	s_or_b64 exec, exec, s[48:49]
	v_add_u32_e32 v48, 0x90, v167
	v_lshl_add_u32 v136, v48, 10, v168
	v_lshl_add_u64 v[58:59], v[136:137], 1, s[40:41]
	v_add_u32_e32 v136, 0x80, v136
	v_lshl_add_u64 v[60:61], v[136:137], 1, s[40:41]
	s_waitcnt vmcnt(10)
	v_cvt_f32_f16_e32 v62, v231
	v_cvt_f32_f16_sdwa v63, v231 dst_sel:DWORD dst_unused:UNUSED_PAD src0_sel:WORD_1
	v_cvt_f32_f16_e32 v64, v229
	v_cvt_f32_f16_sdwa v65, v229 dst_sel:DWORD dst_unused:UNUSED_PAD src0_sel:WORD_1
	v_cvt_f32_f16_e32 v66, v230
	v_cvt_f32_f16_sdwa v67, v230 dst_sel:DWORD dst_unused:UNUSED_PAD src0_sel:WORD_1
	v_cvt_f32_f16_e32 v52, v228
	v_cvt_f32_f16_sdwa v53, v228 dst_sel:DWORD dst_unused:UNUSED_PAD src0_sel:WORD_1
	v_cvt_f32_f16_e32 v50, v247
	v_cvt_f32_f16_sdwa v51, v247 dst_sel:DWORD dst_unused:UNUSED_PAD src0_sel:WORD_1
	v_cvt_f32_f16_e32 v68, v245
	v_cvt_f32_f16_sdwa v69, v245 dst_sel:DWORD dst_unused:UNUSED_PAD src0_sel:WORD_1
	v_cvt_f32_f16_e32 v70, v246
	v_cvt_f32_f16_sdwa v71, v246 dst_sel:DWORD dst_unused:UNUSED_PAD src0_sel:WORD_1
	v_cvt_f32_f16_e32 v56, v244
	v_cvt_f32_f16_sdwa v57, v244 dst_sel:DWORD dst_unused:UNUSED_PAD src0_sel:WORD_1
	v_pk_add_f32 v[44:45], v[44:45], v[52:53]
	v_pk_add_f32 v[52:53], v[40:41], v[66:67]
	v_pk_add_f32 v[46:47], v[46:47], v[64:65]
	v_pk_add_f32 v[42:43], v[42:43], v[62:63]
	v_cvt_pk_f16_f32 v40, v52, v53
	v_cvt_pk_f16_f32 v41, v42, v43
	v_pk_mul_f32 v[54:55], v[44:45], v[44:45]
	v_pk_mul_f32 v[62:63], v[46:47], v[46:47]
	v_pk_mul_f32 v[52:53], v[52:53], v[52:53]
	v_pk_mul_f32 v[42:43], v[42:43], v[42:43]
	v_pk_add_f32 v[56:57], v[36:37], v[56:57]
	v_pk_add_f32 v[64:65], v[32:33], v[70:71]
	v_pk_add_f32 v[66:67], v[38:39], v[68:69]
	v_pk_add_f32 v[32:33], v[34:35], v[50:51]
	v_pk_mul_f32 v[34:35], v[56:57], v[56:57]
	v_pk_mul_f32 v[36:37], v[66:67], v[66:67]
	v_pk_mul_f32 v[38:39], v[64:65], v[64:65]
	v_pk_mul_f32 v[50:51], v[32:33], v[32:33]
	v_add_f32_e32 v42, v42, v43
	v_add_f32_e32 v43, v52, v53
	s_waitcnt lgkmcnt(0)
	v_add_f32_e32 v49, v62, v63
	v_add_f32_e32 v52, v54, v55
	v_add_f32_e32 v42, v43, v42
	v_add_f32_e32 v43, v52, v49
	v_add_f32_e32 v49, v50, v51
	v_add_f32_e32 v38, v38, v39
	v_add_f32_e32 v36, v36, v37
	v_add_f32_e32 v34, v34, v35
	v_add_f32_e32 v37, v38, v49
	v_add_f32_e32 v34, v34, v36
	v_add_f32_e32 v35, v43, v42
	v_add_f32_e32 v34, v34, v37
	v_add_f32_e32 v34, v35, v34
	ds_bpermute_b32 v35, v166, v34
	v_cvt_pk_f16_f32 v37, v32, v33
	v_cvt_pk_f16_f32 v39, v46, v47
	v_cvt_pk_f16_f32 v38, v44, v45
	v_cvt_pk_f16_f32 v36, v64, v65
	s_waitcnt lgkmcnt(0)
	v_add_f32_e32 v32, v34, v35
	ds_bpermute_b32 v33, v112, v32
	v_cvt_pk_f16_f32 v35, v66, v67
	v_cvt_pk_f16_f32 v34, v56, v57
	global_store_dwordx4 v[58:59], v[38:41], off
	global_store_dwordx4 v[60:61], v[34:37], off
	s_and_saveexec_b64 s[48:49], s[4:5]
	s_cbranch_execz .LBB0_698
	v_lshl_add_u32 v136, v48, 4, s11
	s_waitcnt lgkmcnt(0)
	v_add_f32_e32 v34, v32, v33
	v_lshl_add_u64 v[32:33], v[136:137], 2, s[42:43]
	global_store_dword v[32:33], v34, off

; #define PG8_STAGE(bufoff, gbase, voff) do { _Pragma("unroll") for (int _i = 0; _i < 2; ++_i) \
;         __builtin_amdgcn_global_load_lds((const unsigned*)((const char*)(gbase) + (voff)[_i]), (PG8_LAS unsigned*)(lds + (bufoff) + ldsw + _i * 8192), 16, 0, 0); } while (0)
; #define PG8_LDA(dst, b, h) do { _Pragma("unroll") for (int m = 0; m < 4; ++m) _Pragma("unroll") for (int k = 0; k < 2; ++k) dst[m][k] = *(const PG8_LAS bf16x8*)(lds + PG8_SA(b, h) + aoff + m * 2048 + k * 1024); } while (0)
; #define PG8_LDB(dst, b, h) do { _Pragma("unroll") for (int n = 0; n < 2; ++n) _Pragma("unroll") for (int k = 0; k < 2; ++k) dst[n][k] = *(const PG8_LAS bf16x8*)(lds + PG8_SB(b, h) + boff + n * 2048 + k * 1024); } while (0)
; #define PG8_MMA(ai, bj, At, Bt) do { __builtin_amdgcn_s_setprio(1); _Pragma("unroll") for (int m = 0; m < 4; ++m) _Pragma("unroll") for (int n = 0; n < 2; ++n) _Pragma("unroll") for (int k = 0; k < 2; ++k) \
;         acc[ai][bj][m][n] = mma16<F16>(Bt[n][k], At[m][k], acc[ai][bj][m][n]); __builtin_amdgcn_s_setprio(0); } while (0)
; #define PG8_WAIT_V(n) asm volatile("s_waitcnt vmcnt(" #n ")" ::: "memory")
; #define PG8_WAIT_L(n) asm volatile("s_waitcnt lgkmcnt(" #n ")" ::: "memory")
; #define PG8_BAR __builtin_amdgcn_s_barrier()
; #define PG8_SCHED __builtin_amdgcn_sched_barrier(0)
; template <class Epi, class Sched, bool ALIGN_EPI = false, bool SP2 = false, bool F16 = false, bool TOKPERM = false>
; __device__ __forceinline__ void gemm_phase(PG8_LAS unsigned char* lds, const Gemm g, const Sched& S, const Epi& E, int wv) {
;     ...
;             PG8_LDB(B0, 0, 0); PG8_LDB(B1, 0, 1); PG8_SCHED; PG8_LDA(At, 0, 0); PG8_STAGE(PG8_SA(1, 1), a1 + hstep, voffA);
;             PG8_WAIT_V(8); PG8_WAIT_L(0); PG8_BAR; PG8_MMA(0, 0, At, B0); PG8_MMA(0, 1, At, B1); PG8_BAR; PG8_SCHED;
;             PG8_LDA(At, 0, 1); PG8_STAGE(PG8_SB(0, 0), b2, voffB); PG8_STAGE(PG8_SB(0, 1), b2 + hstep, voffB); PG8_STAGE(PG8_SA(0, 0), a2, voffA);
.LBB0_867:
	ds_read_b128 v[166:169], v149
	ds_read_b128 v[170:173], v150
	ds_read_b128 v[174:177], v151
	ds_read_b128 v[178:181], v152
	ds_read_b128 v[182:185], v153
	ds_read_b128 v[186:189], v154
	ds_read_b128 v[190:193], v155
	ds_read_b128 v[194:197], v156
	s_add_u32 s18, s16, 0x100
	s_addc_u32 s19, s17, 0
	s_cmp_eq_u32 s67, 40
	s_cselect_b32 s23, s11, s19
	s_cselect_b32 s22, s10, s18
	s_cselect_b32 s21, s13, s66
	s_cselect_b32 s20, s12, s65
	s_mov_b32 m0, s59
	v_lshl_add_u64 v[232:233], s[16:17], 0, v[138:139]
	ds_read_b128 v[198:201], v147
	ds_read_b128 v[202:205], v147 offset:1024
	ds_read_b128 v[206:209], v147 offset:2048
	ds_read_b128 v[210:213], v147 offset:3072
	ds_read_b128 v[214:217], v147 offset:4096
	ds_read_b128 v[218:221], v147 offset:5120
	ds_read_b128 v[222:225], v147 offset:6144
	ds_read_b128 v[228:231], v147 offset:7168
	global_load_lds_dwordx4 v[232:233], off
	v_lshl_add_u64 v[232:233], s[16:17], 0, v[140:141]
	s_mov_b32 m0, s60
	s_nop 0
	global_load_lds_dwordx4 v[232:233], off
	s_waitcnt vmcnt(8)
	s_waitcnt lgkmcnt(0)
	s_barrier
	s_setprio 1
	s_waitcnt lgkmcnt(0)
	v_mfma_f32_16x16x32_bf16 v[124:127], v[166:169], v[198:201], v[124:127]
	v_mfma_f32_16x16x32_bf16 v[120:123], v[174:177], v[198:201], v[120:123]
	v_mfma_f32_16x16x32_bf16 v[108:111], v[166:169], v[206:209], v[108:111]
	v_mfma_f32_16x16x32_bf16 v[104:107], v[174:177], v[206:209], v[104:107]
	v_mfma_f32_16x16x32_bf16 v[92:95], v[166:169], v[214:217], v[92:95]
	v_mfma_f32_16x16x32_bf16 v[88:91], v[174:177], v[214:217], v[88:91]
	v_mfma_f32_16x16x32_bf16 v[76:79], v[166:169], v[222:225], v[76:79]
	v_mfma_f32_16x16x32_bf16 v[72:75], v[174:177], v[222:225], v[72:75]
	v_mfma_f32_16x16x32_bf16 v[124:127], v[170:173], v[202:205], v[124:127]
	v_mfma_f32_16x16x32_bf16 v[120:123], v[178:181], v[202:205], v[120:123]
	v_mfma_f32_16x16x32_bf16 v[108:111], v[170:173], v[210:213], v[108:111]
	v_mfma_f32_16x16x32_bf16 v[104:107], v[178:181], v[210:213], v[104:107]
	v_mfma_f32_16x16x32_bf16 v[92:95], v[170:173], v[218:221], v[92:95]
	v_mfma_f32_16x16x32_bf16 v[88:91], v[178:181], v[218:221], v[88:91]
	v_mfma_f32_16x16x32_bf16 v[76:79], v[170:173], v[228:231], v[76:79]
	v_mfma_f32_16x16x32_bf16 v[72:75], v[178:181], v[228:231], v[72:75]
	s_setprio 0
	s_setprio 1
	v_mfma_f32_16x16x32_bf16 v[116:119], v[182:185], v[198:201], v[116:119]
	v_mfma_f32_16x16x32_bf16 v[112:115], v[190:193], v[198:201], v[112:115]
	v_mfma_f32_16x16x32_bf16 v[100:103], v[182:185], v[206:209], v[100:103]
	v_mfma_f32_16x16x32_bf16 v[96:99], v[190:193], v[206:209], v[96:99]
	v_mfma_f32_16x16x32_bf16 v[84:87], v[182:185], v[214:217], v[84:87]
	v_mfma_f32_16x16x32_bf16 v[80:83], v[190:193], v[214:217], v[80:83]
	v_mfma_f32_16x16x32_bf16 v[68:71], v[182:185], v[222:225], v[68:71]
	v_mfma_f32_16x16x32_bf16 v[64:67], v[190:193], v[222:225], v[64:67]
	v_mfma_f32_16x16x32_bf16 v[116:119], v[186:189], v[202:205], v[116:119]
	v_mfma_f32_16x16x32_bf16 v[112:115], v[194:197], v[202:205], v[112:115]
	v_mfma_f32_16x16x32_bf16 v[100:103], v[186:189], v[210:213], v[100:103]
	v_mfma_f32_16x16x32_bf16 v[96:99], v[194:197], v[210:213], v[96:99]
	v_mfma_f32_16x16x32_bf16 v[84:87], v[186:189], v[218:221], v[84:87]
	v_mfma_f32_16x16x32_bf16 v[80:83], v[194:197], v[218:221], v[80:83]
	v_mfma_f32_16x16x32_bf16 v[68:71], v[186:189], v[228:231], v[68:71]
	v_mfma_f32_16x16x32_bf16 v[64:67], v[194:197], v[228:231], v[64:67]
	s_setprio 0
	s_barrier
	s_mov_b32 m0, s4
	v_lshl_add_u64 v[232:233], s[20:21], 0, v[130:131]
	s_add_u32 s16, s20, 0xb0000
	ds_read_b128 v[198:201], v147 offset:16384
	ds_read_b128 v[202:205], v147 offset:17408
	ds_read_b128 v[206:209], v147 offset:18432
	ds_read_b128 v[210:213], v147 offset:19456
	ds_read_b128 v[214:217], v147 offset:20480
	ds_read_b128 v[218:221], v147 offset:21504
	ds_read_b128 v[222:225], v147 offset:22528
	ds_read_b128 v[228:231], v147 offset:23552
	global_load_lds_dwordx4 v[232:233], off
	v_lshl_add_u64 v[234:235], s[20:21], 0, v[134:135]
	s_mov_b32 m0, s5
	s_addc_u32 s17, s21, 0
	global_load_lds_dwordx4 v[234:235], off
	v_lshl_add_u64 v[236:237], s[16:17], 0, v[130:131]
	s_mov_b32 m0, s33
	v_lshl_add_u64 v[238:239], s[22:23], 0, v[132:133]
	global_load_lds_dwordx4 v[236:237], off
	v_lshl_add_u64 v[236:237], s[16:17], 0, v[134:135]
	s_mov_b32 m0, s36
	s_nop 0
	global_load_lds_dwordx4 v[236:237], off
	v_lshl_add_u64 v[236:237], s[22:23], 0, v[128:129]
	s_mov_b32 m0, s3
	s_nop 0
	global_load_lds_dwordx4 v[236:237], off
	s_mov_b32 m0, s37
	s_nop 0
	global_load_lds_dwordx4 v[238:239], off
	s_waitcnt vmcnt(8)
	s_waitcnt lgkmcnt(0)
	s_barrier
; #define PG8_STAGE(bufoff, gbase, voff) do { _Pragma("unroll") for (int _i = 0; _i < 2; ++_i) \
;         __builtin_amdgcn_global_load_lds((const unsigned*)((const char*)(gbase) + (voff)[_i]), (PG8_LAS unsigned*)(lds + (bufoff) + ldsw + _i * 8192), 16, 0, 0); } while (0)
; #define PG8_LDA(dst, b, h) do { _Pragma("unroll") for (int m = 0; m < 4; ++m) _Pragma("unroll") for (int k = 0; k < 2; ++k) dst[m][k] = *(const PG8_LAS bf16x8*)(lds + PG8_SA(b, h) + aoff + m * 2048 + k * 1024); } while (0)
; #define PG8_LDB(dst, b, h) do { _Pragma("unroll") for (int n = 0; n < 2; ++n) _Pragma("unroll") for (int k = 0; k < 2; ++k) dst[n][k] = *(const PG8_LAS bf16x8*)(lds + PG8_SB(b, h) + boff + n * 2048 + k * 1024); } while (0)
; #define PG8_MMA(ai, bj, At, Bt) do { __builtin_amdgcn_s_setprio(1); _Pragma("unroll") for (int m = 0; m < 4; ++m) _Pragma("unroll") for (int n = 0; n < 2; ++n) _Pragma("unroll") for (int k = 0; k < 2; ++k) \
;         acc[ai][bj][m][n] = mma16<F16>(Bt[n][k], At[m][k], acc[ai][bj][m][n]); __builtin_amdgcn_s_setprio(0); } while (0)
; #define PG8_WAIT_V(n) asm volatile("s_waitcnt vmcnt(" #n ")" ::: "memory")
; #define PG8_WAIT_L(n) asm volatile("s_waitcnt lgkmcnt(" #n ")" ::: "memory")
; #define PG8_BAR __builtin_amdgcn_s_barrier()
; #define PG8_SCHED __builtin_amdgcn_sched_barrier(0)
; template <class Epi, class Sched, bool ALIGN_EPI = false, bool SP2 = false, bool F16 = false, bool TOKPERM = false>
; __device__ __forceinline__ void gemm_phase(PG8_LAS unsigned char* lds, const Gemm g, const Sched& S, const Epi& E, int wv) {
;     ...
;             PG8_WAIT_V(8); PG8_WAIT_L(0); PG8_BAR; PG8_MMA(1, 0, At, B0); PG8_MMA(1, 1, At, B1); PG8_BAR; PG8_SCHED;
;             PG8_LDB(B0, 1, 0); PG8_LDB(B1, 1, 1); PG8_SCHED; PG8_LDA(At, 1, 0); PG8_STAGE(PG8_SA(0, 1), a2 + hstep, voffA);
;             PG8_WAIT_V(8); PG8_WAIT_L(0); PG8_BAR; PG8_MMA(0, 0, At, B0); PG8_MMA(0, 1, At, B1); PG8_BAR; PG8_SCHED;
	s_setprio 1
	s_waitcnt lgkmcnt(0)
	v_mfma_f32_16x16x32_bf16 v[60:63], v[166:169], v[198:201], v[60:63]
	v_mfma_f32_16x16x32_bf16 v[56:59], v[174:177], v[198:201], v[56:59]
	v_mfma_f32_16x16x32_bf16 v[44:47], v[166:169], v[206:209], v[44:47]
	v_mfma_f32_16x16x32_bf16 v[40:43], v[174:177], v[206:209], v[40:43]
	v_mfma_f32_16x16x32_bf16 v[28:31], v[166:169], v[214:217], v[28:31]
	v_mfma_f32_16x16x32_bf16 v[24:27], v[174:177], v[214:217], v[24:27]
	v_mfma_f32_16x16x32_bf16 v[12:15], v[166:169], v[222:225], v[12:15]
	v_mfma_f32_16x16x32_bf16 v[8:11], v[174:177], v[222:225], v[8:11]
	v_mfma_f32_16x16x32_bf16 v[60:63], v[170:173], v[202:205], v[60:63]
	v_mfma_f32_16x16x32_bf16 v[56:59], v[178:181], v[202:205], v[56:59]
	v_mfma_f32_16x16x32_bf16 v[44:47], v[170:173], v[210:213], v[44:47]
	v_mfma_f32_16x16x32_bf16 v[40:43], v[178:181], v[210:213], v[40:43]
	v_mfma_f32_16x16x32_bf16 v[28:31], v[170:173], v[218:221], v[28:31]
	v_mfma_f32_16x16x32_bf16 v[24:27], v[178:181], v[218:221], v[24:27]
	v_mfma_f32_16x16x32_bf16 v[12:15], v[170:173], v[228:231], v[12:15]
	v_mfma_f32_16x16x32_bf16 v[8:11], v[178:181], v[228:231], v[8:11]
	s_setprio 0
	s_setprio 1
	v_mfma_f32_16x16x32_bf16 v[52:55], v[182:185], v[198:201], v[52:55]
	v_mfma_f32_16x16x32_bf16 v[48:51], v[190:193], v[198:201], v[48:51]
	v_mfma_f32_16x16x32_bf16 v[36:39], v[182:185], v[206:209], v[36:39]
	v_mfma_f32_16x16x32_bf16 v[32:35], v[190:193], v[206:209], v[32:35]
	v_mfma_f32_16x16x32_bf16 v[20:23], v[182:185], v[214:217], v[20:23]
	v_mfma_f32_16x16x32_bf16 v[16:19], v[190:193], v[214:217], v[16:19]
	v_mfma_f32_16x16x32_bf16 v[4:7], v[182:185], v[222:225], v[4:7]
	v_mfma_f32_16x16x32_bf16 v[0:3], v[190:193], v[222:225], v[0:3]
	v_mfma_f32_16x16x32_bf16 v[52:55], v[186:189], v[202:205], v[52:55]
	v_mfma_f32_16x16x32_bf16 v[48:51], v[194:197], v[202:205], v[48:51]
	v_mfma_f32_16x16x32_bf16 v[36:39], v[186:189], v[210:213], v[36:39]
	v_mfma_f32_16x16x32_bf16 v[32:35], v[194:197], v[210:213], v[32:35]
	v_mfma_f32_16x16x32_bf16 v[20:23], v[186:189], v[218:221], v[20:23]
	v_mfma_f32_16x16x32_bf16 v[16:19], v[194:197], v[218:221], v[16:19]
	v_mfma_f32_16x16x32_bf16 v[4:7], v[186:189], v[228:231], v[4:7]
	v_mfma_f32_16x16x32_bf16 v[0:3], v[194:197], v[228:231], v[0:3]
	s_setprio 0
	s_barrier
	ds_read_b128 v[166:169], v157
	ds_read_b128 v[170:173], v158
	ds_read_b128 v[174:177], v159
	ds_read_b128 v[178:181], v160
	ds_read_b128 v[182:185], v161
	ds_read_b128 v[186:189], v162
	ds_read_b128 v[190:193], v163
	ds_read_b128 v[194:197], v164
	s_add_u32 s16, s22, 0xb0000
	s_addc_u32 s17, s23, 0
	s_mov_b32 m0, s44
	v_lshl_add_u64 v[240:241], s[16:17], 0, v[128:129]
	ds_read_b128 v[198:201], v147 offset:32768
	ds_read_b128 v[202:205], v147 offset:33792
	ds_read_b128 v[206:209], v147 offset:34816
	ds_read_b128 v[210:213], v147 offset:35840
	ds_read_b128 v[214:217], v147 offset:36864
	ds_read_b128 v[218:221], v147 offset:37888
	ds_read_b128 v[222:225], v147 offset:38912
	ds_read_b128 v[228:231], v147 offset:39936
	global_load_lds_dwordx4 v[240:241], off
	v_lshl_add_u64 v[240:241], s[16:17], 0, v[132:133]
	s_mov_b32 m0, s45
	s_nop 0
	global_load_lds_dwordx4 v[240:241], off
	s_waitcnt vmcnt(8)
	s_waitcnt lgkmcnt(0)
	s_barrier
	s_setprio 1
	s_waitcnt lgkmcnt(0)
	v_mfma_f32_16x16x32_bf16 v[124:127], v[166:169], v[198:201], v[124:127]
	v_mfma_f32_16x16x32_bf16 v[120:123], v[174:177], v[198:201], v[120:123]
	v_mfma_f32_16x16x32_bf16 v[108:111], v[166:169], v[206:209], v[108:111]
	v_mfma_f32_16x16x32_bf16 v[104:107], v[174:177], v[206:209], v[104:107]
	v_mfma_f32_16x16x32_bf16 v[92:95], v[166:169], v[214:217], v[92:95]
	v_mfma_f32_16x16x32_bf16 v[88:91], v[174:177], v[214:217], v[88:91]
	v_mfma_f32_16x16x32_bf16 v[76:79], v[166:169], v[222:225], v[76:79]
	v_mfma_f32_16x16x32_bf16 v[72:75], v[174:177], v[222:225], v[72:75]
	v_mfma_f32_16x16x32_bf16 v[124:127], v[170:173], v[202:205], v[124:127]
	v_mfma_f32_16x16x32_bf16 v[120:123], v[178:181], v[202:205], v[120:123]
	v_mfma_f32_16x16x32_bf16 v[108:111], v[170:173], v[210:213], v[108:111]
	v_mfma_f32_16x16x32_bf16 v[104:107], v[178:181], v[210:213], v[104:107]
	v_mfma_f32_16x16x32_bf16 v[92:95], v[170:173], v[218:221], v[92:95]
	v_mfma_f32_16x16x32_bf16 v[88:91], v[178:181], v[218:221], v[88:91]
	v_mfma_f32_16x16x32_bf16 v[76:79], v[170:173], v[228:231], v[76:79]
	v_mfma_f32_16x16x32_bf16 v[72:75], v[178:181], v[228:231], v[72:75]
	s_setprio 0
	s_setprio 1
	v_mfma_f32_16x16x32_bf16 v[116:119], v[182:185], v[198:201], v[116:119]
	v_mfma_f32_16x16x32_bf16 v[112:115], v[190:193], v[198:201], v[112:115]
	v_mfma_f32_16x16x32_bf16 v[100:103], v[182:185], v[206:209], v[100:103]
	v_mfma_f32_16x16x32_bf16 v[96:99], v[190:193], v[206:209], v[96:99]
	v_mfma_f32_16x16x32_bf16 v[84:87], v[182:185], v[214:217], v[84:87]
	v_mfma_f32_16x16x32_bf16 v[80:83], v[190:193], v[214:217], v[80:83]
	v_mfma_f32_16x16x32_bf16 v[68:71], v[182:185], v[222:225], v[68:71]
	v_mfma_f32_16x16x32_bf16 v[64:67], v[190:193], v[222:225], v[64:67]
	v_mfma_f32_16x16x32_bf16 v[116:119], v[186:189], v[202:205], v[116:119]
	v_mfma_f32_16x16x32_bf16 v[112:115], v[194:197], v[202:205], v[112:115]
	v_mfma_f32_16x16x32_bf16 v[100:103], v[186:189], v[210:213], v[100:103]
	v_mfma_f32_16x16x32_bf16 v[96:99], v[194:197], v[210:213], v[96:99]
	v_mfma_f32_16x16x32_bf16 v[84:87], v[186:189], v[218:221], v[84:87]
	v_mfma_f32_16x16x32_bf16 v[80:83], v[194:197], v[218:221], v[80:83]
	v_mfma_f32_16x16x32_bf16 v[68:71], v[186:189], v[228:231], v[68:71]
	v_mfma_f32_16x16x32_bf16 v[64:67], v[194:197], v[228:231], v[64:67]
	s_setprio 0
	s_barrier
; #define PG8_STAGE(bufoff, gbase, voff) do { _Pragma("unroll") for (int _i = 0; _i < 2; ++_i) \
;         __builtin_amdgcn_global_load_lds((const unsigned*)((const char*)(gbase) + (voff)[_i]), (PG8_LAS unsigned*)(lds + (bufoff) + ldsw + _i * 8192), 16, 0, 0); } while (0)
; #define PG8_LDA(dst, b, h) do { _Pragma("unroll") for (int m = 0; m < 4; ++m) _Pragma("unroll") for (int k = 0; k < 2; ++k) dst[m][k] = *(const PG8_LAS bf16x8*)(lds + PG8_SA(b, h) + aoff + m * 2048 + k * 1024); } while (0)
; #define PG8_MMA(ai, bj, At, Bt) do { __builtin_amdgcn_s_setprio(1); _Pragma("unroll") for (int m = 0; m < 4; ++m) _Pragma("unroll") for (int n = 0; n < 2; ++n) _Pragma("unroll") for (int k = 0; k < 2; ++k) \
;         acc[ai][bj][m][n] = mma16<F16>(Bt[n][k], At[m][k], acc[ai][bj][m][n]); __builtin_amdgcn_s_setprio(0); } while (0)
; template <class Epi, class Sched, bool ALIGN_EPI = false, bool SP2 = false, bool F16 = false, bool TOKPERM = false>
; __device__ __forceinline__ void gemm_phase(PG8_LAS unsigned char* lds, const Gemm g, const Sched& S, const Epi& E, int wv) {
;     ...
;             PG8_LDA(At, 1, 1); PG8_STAGE(PG8_SB(1, 0), b3, voffB); PG8_STAGE(PG8_SB(1, 1), b3 + hstep, voffB); PG8_STAGE(PG8_SA(1, 0), a3, voffA);
;             PG8_WAIT_V(8); PG8_WAIT_L(0); PG8_BAR; PG8_MMA(1, 0, At, B0); PG8_MMA(1, 1, At, B1); PG8_BAR; PG8_SCHED;
;   __device__ __forceinline__ void operator()(const pg8::f32x4 (&acc)[2][2][4][2], const pg8::Unit& u, int wr, int wc, int fr, int fq) const {
;     int z; asm volatile("v_mov_b32 %0, 0" : "=v"(z));
;     const int row0 = u.pm * 256 + wr * 64 + fr + z, colb = u.pn * 256 + wc * 32 + 8 * fq + z;
; #pragma unroll
;     for (int ai = 0; ai < 2; ++ai)
; #pragma unroll
;       for (int m = 0; m < 4; ++m) {
;         const int tok = row0 + ai * 128 + m * 16; float ss = 0.f;
; #pragma unroll
;         for (int bj = 0; bj < 2; ++bj) {
;           const unsigned off = (unsigned)tok * DM + colb + 128 * bj;
;           f8_t n = __builtin_convertvector(*(const h8_t*)(x16 + off), f8_t);
; #pragma unroll
;           for (int c = 0; c < 4; ++c) { n[c] += sc * acc[ai][bj][m][0][c]; n[4 + c] += sc * acc[ai][bj][m][1][c]; }
;           if (aux) {
;             *(h8_t*)(x16 + off) = __builtin_convertvector(n, h8_t);
;             ss += ((n[0] * n[0] + n[1] * n[1]) + (n[2] * n[2] + n[3] * n[3])) + ((n[4] * n[4] + n[5] * n[5]) + (n[6] * n[6] + n[7] * n[7]));
	s_mov_b32 m0, s49
	v_lshl_add_u64 v[232:233], v[232:233], 0, s[14:15]
	s_add_u32 s16, s20, 0xb0080
	ds_read_b128 v[198:201], v147 offset:49152
	ds_read_b128 v[202:205], v147 offset:50176
	ds_read_b128 v[206:209], v147 offset:51200
	ds_read_b128 v[210:213], v147 offset:52224
	ds_read_b128 v[214:217], v147 offset:53248
	ds_read_b128 v[218:221], v147 offset:54272
	ds_read_b128 v[222:225], v147 offset:55296
	ds_read_b128 v[228:231], v147 offset:56320
	global_load_lds_dwordx4 v[232:233], off
	v_lshl_add_u64 v[232:233], v[234:235], 0, s[14:15]
	s_mov_b32 m0, s50
	s_addc_u32 s17, s21, 0
	global_load_lds_dwordx4 v[232:233], off
	v_lshl_add_u64 v[232:233], s[16:17], 0, v[130:131]
	s_mov_b32 m0, s53
	s_nop 0
	global_load_lds_dwordx4 v[232:233], off
	v_lshl_add_u64 v[232:233], s[16:17], 0, v[134:135]
	s_mov_b32 m0, s54
	s_nop 0
	global_load_lds_dwordx4 v[232:233], off
	v_lshl_add_u64 v[232:233], v[236:237], 0, s[14:15]
	s_mov_b32 m0, s51
	s_nop 0
	global_load_lds_dwordx4 v[232:233], off
	v_lshl_add_u64 v[232:233], v[238:239], 0, s[14:15]
	s_mov_b32 m0, s52
	s_nop 0
	global_load_lds_dwordx4 v[232:233], off
	s_waitcnt vmcnt(8)
	s_waitcnt lgkmcnt(0)
	s_barrier
	s_setprio 1
	s_waitcnt lgkmcnt(0)
	v_mfma_f32_16x16x32_bf16 v[60:63], v[166:169], v[198:201], v[60:63]
	v_mfma_f32_16x16x32_bf16 v[56:59], v[174:177], v[198:201], v[56:59]
	v_mfma_f32_16x16x32_bf16 v[44:47], v[166:169], v[206:209], v[44:47]
	v_mfma_f32_16x16x32_bf16 v[40:43], v[174:177], v[206:209], v[40:43]
	v_mfma_f32_16x16x32_bf16 v[28:31], v[166:169], v[214:217], v[28:31]
	v_mfma_f32_16x16x32_bf16 v[24:27], v[174:177], v[214:217], v[24:27]
	v_mfma_f32_16x16x32_bf16 v[12:15], v[166:169], v[222:225], v[12:15]
	v_mfma_f32_16x16x32_bf16 v[8:11], v[174:177], v[222:225], v[8:11]
	v_mfma_f32_16x16x32_bf16 v[60:63], v[170:173], v[202:205], v[60:63]
	v_mfma_f32_16x16x32_bf16 v[56:59], v[178:181], v[202:205], v[56:59]
	v_mfma_f32_16x16x32_bf16 v[44:47], v[170:173], v[210:213], v[44:47]
	v_mfma_f32_16x16x32_bf16 v[40:43], v[178:181], v[210:213], v[40:43]
	v_mfma_f32_16x16x32_bf16 v[28:31], v[170:173], v[218:221], v[28:31]
	v_mfma_f32_16x16x32_bf16 v[24:27], v[178:181], v[218:221], v[24:27]
	v_mfma_f32_16x16x32_bf16 v[12:15], v[170:173], v[228:231], v[12:15]
	v_mfma_f32_16x16x32_bf16 v[8:11], v[178:181], v[228:231], v[8:11]
	s_setprio 0
	s_setprio 1
	v_mfma_f32_16x16x32_bf16 v[52:55], v[182:185], v[198:201], v[52:55]
	v_mfma_f32_16x16x32_bf16 v[48:51], v[190:193], v[198:201], v[48:51]
	v_mfma_f32_16x16x32_bf16 v[36:39], v[182:185], v[206:209], v[36:39]
	v_mfma_f32_16x16x32_bf16 v[32:35], v[190:193], v[206:209], v[32:35]
	v_mfma_f32_16x16x32_bf16 v[20:23], v[182:185], v[214:217], v[20:23]
	v_mfma_f32_16x16x32_bf16 v[16:19], v[190:193], v[214:217], v[16:19]
	v_mfma_f32_16x16x32_bf16 v[4:7], v[182:185], v[222:225], v[4:7]
	v_mfma_f32_16x16x32_bf16 v[0:3], v[190:193], v[222:225], v[0:3]
	v_mfma_f32_16x16x32_bf16 v[52:55], v[186:189], v[202:205], v[52:55]
	v_mfma_f32_16x16x32_bf16 v[48:51], v[194:197], v[202:205], v[48:51]
	v_mfma_f32_16x16x32_bf16 v[36:39], v[186:189], v[210:213], v[36:39]
	v_mfma_f32_16x16x32_bf16 v[32:35], v[194:197], v[210:213], v[32:35]
	v_mfma_f32_16x16x32_bf16 v[20:23], v[186:189], v[218:221], v[20:23]
	v_mfma_f32_16x16x32_bf16 v[16:19], v[194:197], v[218:221], v[16:19]
	v_mfma_f32_16x16x32_bf16 v[4:7], v[186:189], v[228:231], v[4:7]
	v_mfma_f32_16x16x32_bf16 v[0:3], v[194:197], v[228:231], v[0:3]
	s_setprio 0
	s_barrier
	s_add_i32 s67, s67, 2
	s_add_u32 s65, s65, 0x100
	s_addc_u32 s66, s66, 0
	s_cmp_gt_u32 s67, 41
	s_mov_b64 s[16:17], s[18:19]
	s_cbranch_scc0 .LBB0_867
	s_lshl_b32 s16, s64, 8
	v_lshl_or_b32 v166, s63, 8, v148
	v_mov_b32 v136, 0
	v_xor_b32_e32 v169, 32, v165
	v_add3_u32 v167, s16, v146, v136
	v_add_u32_e32 v168, v166, v136
	v_lshl_add_u32 v136, v167, 10, v168
	v_lshl_add_u64 v[178:179], v[136:137], 1, s[40:41]
	v_add_u32_e32 v136, 0x80, v136
	global_load_dwordx4 v[170:173], v[178:179], off
	v_lshl_add_u64 v[180:181], v[136:137], 1, s[40:41]
	global_load_dwordx4 v[174:177], v[180:181], off
	v_add_u32_e32 v136, 16, v167
	v_lshl_add_u32 v136, v136, 10, v168
	v_lshl_add_u64 v[224:225], v[136:137], 1, s[40:41]
	v_add_u32_e32 v136, 0x80, v136
	global_load_dwordx4 v[192:195], v[224:225], off
	v_lshl_add_u64 v[248:249], v[136:137], 1, s[40:41]
	global_load_dwordx4 v[196:199], v[248:249], off
	v_add_u32_e32 v136, 32, v167
	v_lshl_add_u32 v136, v136, 10, v168
	v_lshl_add_u64 v[224:225], v[136:137], 1, s[40:41]
	v_add_u32_e32 v136, 0x80, v136
	global_load_dwordx4 v[200:203], v[224:225], off
	v_lshl_add_u64 v[248:249], v[136:137], 1, s[40:41]
	global_load_dwordx4 v[204:207], v[248:249], off
	v_add_u32_e32 v136, 48, v167
	v_lshl_add_u32 v136, v136, 10, v168
	v_lshl_add_u64 v[224:225], v[136:137], 1, s[40:41]
	v_add_u32_e32 v136, 0x80, v136
	global_load_dwordx4 v[208:211], v[224:225], off
	v_lshl_add_u64 v[248:249], v[136:137], 1, s[40:41]
	global_load_dwordx4 v[212:215], v[248:249], off
	v_add_u32_e32 v136, 0x80, v167
	v_lshl_add_u32 v136, v136, 10, v168
	v_lshl_add_u64 v[224:225], v[136:137], 1, s[40:41]
	v_add_u32_e32 v136, 0x80, v136
	global_load_dwordx4 v[216:219], v[224:225], off
	v_lshl_add_u64 v[248:249], v[136:137], 1, s[40:41]
	global_load_dwordx4 v[220:223], v[248:249], off
	v_add_u32_e32 v136, 0x90, v167
	v_lshl_add_u32 v136, v136, 10, v168
	v_lshl_add_u64 v[224:225], v[136:137], 1, s[40:41]
	v_add_u32_e32 v136, 0x80, v136
	global_load_dwordx4 v[228:231], v[224:225], off
	v_lshl_add_u64 v[248:249], v[136:137], 1, s[40:41]
	global_load_dwordx4 v[244:247], v[248:249], off
	v_and_b32_e32 v166, 64, v165
	v_xor_b32_e32 v136, 16, v165
	v_add_u32_e32 v166, 64, v166
	v_cmp_lt_i32_e32 vcc, v136, v166
	s_lshl_b32 s16, s63, 2
	s_or_b32 s18, s16, s48
	v_cndmask_b32_e32 v136, v165, v136, vcc
	v_cmp_lt_i32_e32 vcc, v169, v166
	v_lshlrev_b32_e32 v166, 2, v136
	s_waitcnt vmcnt(10)
;   __device__ __forceinline__ void operator()(const pg8::f32x4 (&acc)[2][2][4][2], const pg8::Unit& u, int wr, int wc, int fr, int fq) const {
;     ...
;       for (int m = 0; m < 4; ++m) {
;         const int tok = row0 + ai * 128 + m * 16; float ss = 0.f;
; #pragma unroll
;         for (int bj = 0; bj < 2; ++bj) {
;           const unsigned off = (unsigned)tok * DM + colb + 128 * bj;
;           f8_t n = __builtin_convertvector(*(const h8_t*)(x16 + off), f8_t);
; #pragma unroll
;           for (int c = 0; c < 4; ++c) { n[c] += sc * acc[ai][bj][m][0][c]; n[4 + c] += sc * acc[ai][bj][m][1][c]; }
;           if (aux) {
;             *(h8_t*)(x16 + off) = __builtin_convertvector(n, h8_t);
;             ss += ((n[0] * n[0] + n[1] * n[1]) + (n[2] * n[2] + n[3] * n[3])) + ((n[4] * n[4] + n[5] * n[5]) + (n[6] * n[6] + n[7] * n[7]));
;           } else {
;             *(f32x4*)(xout + off) = (f32x4){n[0], n[1], n[2], n[3]}; *(f32x4*)(xout + off + 4) = (f32x4){n[4], n[5], n[6], n[7]};
;           }
;         }
;         if (aux) { ss += __shfl_xor(ss, 16); ss += __shfl_xor(ss, 32); if (fq == 0) ssq[(unsigned)tok * 16 + u.pn * 4 + wc] = ss; }
;         if (m & 1) asm volatile("" ::: "memory");
	v_cvt_f32_f16_e32 v182, v173
	v_cvt_f32_f16_sdwa v183, v173 dst_sel:DWORD dst_unused:UNUSED_PAD src0_sel:WORD_1
	v_cvt_f32_f16_e32 v184, v171
	v_cvt_f32_f16_sdwa v185, v171 dst_sel:DWORD dst_unused:UNUSED_PAD src0_sel:WORD_1
	v_cvt_f32_f16_e32 v186, v172
	v_cvt_f32_f16_sdwa v187, v172 dst_sel:DWORD dst_unused:UNUSED_PAD src0_sel:WORD_1
	v_cvt_f32_f16_e32 v172, v170
	v_cvt_f32_f16_sdwa v173, v170 dst_sel:DWORD dst_unused:UNUSED_PAD src0_sel:WORD_1
	v_cvt_f32_f16_e32 v170, v177
	v_cvt_f32_f16_sdwa v171, v177 dst_sel:DWORD dst_unused:UNUSED_PAD src0_sel:WORD_1
	v_cvt_f32_f16_e32 v188, v175
	v_cvt_f32_f16_sdwa v189, v175 dst_sel:DWORD dst_unused:UNUSED_PAD src0_sel:WORD_1
	v_cvt_f32_f16_e32 v190, v176
	v_cvt_f32_f16_sdwa v191, v176 dst_sel:DWORD dst_unused:UNUSED_PAD src0_sel:WORD_1
	v_cvt_f32_f16_e32 v176, v174
	v_cvt_f32_f16_sdwa v177, v174 dst_sel:DWORD dst_unused:UNUSED_PAD src0_sel:WORD_1
	v_pk_fma_f32 v[124:125], v[124:125], 0.5, v[172:173] op_sel_hi:[1,0,1]
	v_pk_fma_f32 v[172:173], v[120:121], 0.5, v[186:187] op_sel_hi:[1,0,1]
	v_pk_fma_f32 v[126:127], v[126:127], 0.5, v[184:185] op_sel_hi:[1,0,1]
	v_pk_fma_f32 v[122:123], v[122:123], 0.5, v[182:183] op_sel_hi:[1,0,1]
	v_cvt_pk_f16_f32 v120, v172, v173
	v_cvt_pk_f16_f32 v121, v122, v123
	v_pk_mul_f32 v[174:175], v[124:125], v[124:125]
	v_pk_mul_f32 v[182:183], v[126:127], v[126:127]
	v_pk_mul_f32 v[172:173], v[172:173], v[172:173]
	v_pk_mul_f32 v[122:123], v[122:123], v[122:123]
	v_pk_fma_f32 v[176:177], v[116:117], 0.5, v[176:177] op_sel_hi:[1,0,1]
	v_pk_fma_f32 v[116:117], v[112:113], 0.5, v[190:191] op_sel_hi:[1,0,1]
	v_pk_fma_f32 v[184:185], v[118:119], 0.5, v[188:189] op_sel_hi:[1,0,1]
	v_pk_fma_f32 v[112:113], v[114:115], 0.5, v[170:171] op_sel_hi:[1,0,1]
	v_pk_mul_f32 v[114:115], v[176:177], v[176:177]
	v_pk_mul_f32 v[118:119], v[184:185], v[184:185]
	v_pk_mul_f32 v[170:171], v[116:117], v[116:117]
	v_pk_mul_f32 v[186:187], v[112:113], v[112:113]
	v_add_f32_e32 v122, v122, v123
	v_add_f32_e32 v123, v172, v173
	v_add_f32_e32 v136, v182, v183
	v_add_f32_e32 v172, v174, v175
	v_add_f32_e32 v122, v123, v122
	v_add_f32_e32 v123, v172, v136
	v_add_f32_e32 v136, v186, v187
	v_add_f32_e32 v170, v170, v171
	v_add_f32_e32 v118, v118, v119
	v_add_f32_e32 v114, v114, v115
	v_add_f32_e32 v119, v170, v136
	v_add_f32_e32 v114, v114, v118
	v_add_f32_e32 v115, v123, v122
	v_add_f32_e32 v114, v114, v119
	v_add_f32_e32 v114, v115, v114
	ds_bpermute_b32 v115, v166, v114
	v_cndmask_b32_e32 v169, v165, v169, vcc
	v_cvt_pk_f16_f32 v119, v126, v127
	v_cvt_pk_f16_f32 v118, v124, v125
	global_store_dwordx4 v[178:179], v[118:121], off
	s_nop 1
	v_cvt_pk_f16_f32 v119, v112, v113
	s_waitcnt lgkmcnt(0)
	v_add_f32_e32 v113, v114, v115
	v_lshlrev_b32_e32 v112, 2, v169
	ds_bpermute_b32 v114, v112, v113
	v_cvt_pk_f16_f32 v118, v116, v117
	v_cvt_pk_f16_f32 v117, v184, v185
	v_cvt_pk_f16_f32 v116, v176, v177
	global_store_dwordx4 v[180:181], v[116:119], off
	s_and_saveexec_b64 s[16:17], s[6:7]
	s_cbranch_execz .LBB0_870
	v_lshl_add_u32 v136, v167, 4, s18
	s_waitcnt lgkmcnt(0)
	v_add_f32_e32 v113, v113, v114
	v_lshl_add_u64 v[114:115], v[136:137], 2, s[42:43]
	global_store_dword v[114:115], v113, off
.LBB0_870:
	s_or_b64 exec, exec, s[16:17]
	v_add_u32_e32 v113, 16, v167
	v_lshl_add_u32 v136, v113, 10, v168
	v_lshl_add_u64 v[122:123], v[136:137], 1, s[40:41]
	v_add_u32_e32 v136, 0x80, v136
	v_lshl_add_u64 v[124:125], v[136:137], 1, s[40:41]
	s_waitcnt lgkmcnt(0)
	s_waitcnt vmcnt(10)
	v_cvt_f32_f16_e32 v126, v195
	v_cvt_f32_f16_sdwa v127, v195 dst_sel:DWORD dst_unused:UNUSED_PAD src0_sel:WORD_1
	v_cvt_f32_f16_e32 v170, v193
	v_cvt_f32_f16_sdwa v171, v193 dst_sel:DWORD dst_unused:UNUSED_PAD src0_sel:WORD_1
	v_cvt_f32_f16_e32 v172, v194
	v_cvt_f32_f16_sdwa v173, v194 dst_sel:DWORD dst_unused:UNUSED_PAD src0_sel:WORD_1
	v_cvt_f32_f16_e32 v116, v192
	v_cvt_f32_f16_sdwa v117, v192 dst_sel:DWORD dst_unused:UNUSED_PAD src0_sel:WORD_1
	v_cvt_f32_f16_e32 v114, v199
	v_cvt_f32_f16_sdwa v115, v199 dst_sel:DWORD dst_unused:UNUSED_PAD src0_sel:WORD_1
	v_cvt_f32_f16_e32 v174, v197
	v_cvt_f32_f16_sdwa v175, v197 dst_sel:DWORD dst_unused:UNUSED_PAD src0_sel:WORD_1
	v_cvt_f32_f16_e32 v176, v198
	v_cvt_f32_f16_sdwa v177, v198 dst_sel:DWORD dst_unused:UNUSED_PAD src0_sel:WORD_1
	v_cvt_f32_f16_e32 v120, v196
	v_cvt_f32_f16_sdwa v121, v196 dst_sel:DWORD dst_unused:UNUSED_PAD src0_sel:WORD_1
	v_pk_fma_f32 v[108:109], v[108:109], 0.5, v[116:117] op_sel_hi:[1,0,1]
	v_pk_fma_f32 v[116:117], v[104:105], 0.5, v[172:173] op_sel_hi:[1,0,1]
	v_pk_fma_f32 v[110:111], v[110:111], 0.5, v[170:171] op_sel_hi:[1,0,1]
	v_pk_fma_f32 v[106:107], v[106:107], 0.5, v[126:127] op_sel_hi:[1,0,1]
	v_pk_fma_f32 v[120:121], v[100:101], 0.5, v[120:121] op_sel_hi:[1,0,1]
	v_pk_fma_f32 v[170:171], v[96:97], 0.5, v[176:177] op_sel_hi:[1,0,1]
	v_pk_fma_f32 v[172:173], v[102:103], 0.5, v[174:175] op_sel_hi:[1,0,1]
	v_pk_fma_f32 v[96:97], v[98:99], 0.5, v[114:115] op_sel_hi:[1,0,1]
	v_cvt_pk_f16_f32 v105, v106, v107
	v_cvt_pk_f16_f32 v104, v116, v117
	v_pk_mul_f32 v[118:119], v[108:109], v[108:109]
	v_pk_mul_f32 v[126:127], v[110:111], v[110:111]
	v_pk_mul_f32 v[116:117], v[116:117], v[116:117]
	v_pk_mul_f32 v[106:107], v[106:107], v[106:107]
	v_pk_mul_f32 v[98:99], v[120:121], v[120:121]
	v_pk_mul_f32 v[100:101], v[172:173], v[172:173]
	v_pk_mul_f32 v[102:103], v[170:171], v[170:171]
	v_pk_mul_f32 v[114:115], v[96:97], v[96:97]
	v_add_f32_e32 v106, v106, v107
	v_add_f32_e32 v107, v116, v117
	v_add_f32_e32 v116, v126, v127
	v_add_f32_e32 v117, v118, v119
	v_add_f32_e32 v114, v114, v115
	v_add_f32_e32 v102, v102, v103
	v_add_f32_e32 v100, v100, v101
	v_add_f32_e32 v98, v98, v99
	v_add_f32_e32 v106, v107, v106
	v_add_f32_e32 v107, v117, v116
	v_add_f32_e32 v101, v102, v114
	v_add_f32_e32 v98, v98, v100
	v_add_f32_e32 v99, v107, v106
	v_add_f32_e32 v98, v98, v101
	v_add_f32_e32 v98, v99, v98
	ds_bpermute_b32 v99, v166, v98
	v_cvt_pk_f16_f32 v101, v96, v97
	v_cvt_pk_f16_f32 v103, v110, v111
	v_cvt_pk_f16_f32 v102, v108, v109
	v_cvt_pk_f16_f32 v100, v170, v171
	s_waitcnt lgkmcnt(0)
	v_add_f32_e32 v96, v98, v99
	ds_bpermute_b32 v97, v112, v96
	v_cvt_pk_f16_f32 v99, v172, v173
	v_cvt_pk_f16_f32 v98, v120, v121
	global_store_dwordx4 v[122:123], v[102:105], off
	global_store_dwordx4 v[124:125], v[98:101], off
	s_and_saveexec_b64 s[16:17], s[6:7]
	s_cbranch_execz .LBB0_872
	v_lshl_add_u32 v136, v113, 4, s18
	s_waitcnt lgkmcnt(0)
	v_add_f32_e32 v98, v96, v97
	v_lshl_add_u64 v[96:97], v[136:137], 2, s[42:43]
	global_store_dword v[96:97], v98, off
;   __device__ __forceinline__ void operator()(const pg8::f32x4 (&acc)[2][2][4][2], const pg8::Unit& u, int wr, int wc, int fr, int fq) const {
;     ...
;       for (int m = 0; m < 4; ++m) {
;         const int tok = row0 + ai * 128 + m * 16; float ss = 0.f;
; #pragma unroll
;         for (int bj = 0; bj < 2; ++bj) {
;           const unsigned off = (unsigned)tok * DM + colb + 128 * bj;
;           f8_t n = __builtin_convertvector(*(const h8_t*)(x16 + off), f8_t);
; #pragma unroll
;           for (int c = 0; c < 4; ++c) { n[c] += sc * acc[ai][bj][m][0][c]; n[4 + c] += sc * acc[ai][bj][m][1][c]; }
;           if (aux) {
;             *(h8_t*)(x16 + off) = __builtin_convertvector(n, h8_t);
;             ss += ((n[0] * n[0] + n[1] * n[1]) + (n[2] * n[2] + n[3] * n[3])) + ((n[4] * n[4] + n[5] * n[5]) + (n[6] * n[6] + n[7] * n[7]));
;           } else {
;             *(f32x4*)(xout + off) = (f32x4){n[0], n[1], n[2], n[3]}; *(f32x4*)(xout + off + 4) = (f32x4){n[4], n[5], n[6], n[7]};
;           }
;         }
;         if (aux) { ss += __shfl_xor(ss, 16); ss += __shfl_xor(ss, 32); if (fq == 0) ssq[(unsigned)tok * 16 + u.pn * 4 + wc] = ss; }
;         if (m & 1) asm volatile("" ::: "memory");
.LBB0_872:
	s_or_b64 exec, exec, s[16:17]
	v_add_u32_e32 v96, 32, v167
	v_lshl_add_u32 v136, v96, 10, v168
	v_lshl_add_u64 v[106:107], v[136:137], 1, s[40:41]
	v_add_u32_e32 v136, 0x80, v136
	v_lshl_add_u64 v[108:109], v[136:137], 1, s[40:41]
	s_waitcnt vmcnt(10)
	v_cvt_f32_f16_e32 v110, v203
	v_cvt_f32_f16_sdwa v111, v203 dst_sel:DWORD dst_unused:UNUSED_PAD src0_sel:WORD_1
	v_cvt_f32_f16_e32 v114, v201
	v_cvt_f32_f16_sdwa v115, v201 dst_sel:DWORD dst_unused:UNUSED_PAD src0_sel:WORD_1
	v_cvt_f32_f16_e32 v116, v202
	v_cvt_f32_f16_sdwa v117, v202 dst_sel:DWORD dst_unused:UNUSED_PAD src0_sel:WORD_1
	v_cvt_f32_f16_e32 v100, v200
	v_cvt_f32_f16_sdwa v101, v200 dst_sel:DWORD dst_unused:UNUSED_PAD src0_sel:WORD_1
	v_cvt_f32_f16_e32 v98, v207
	v_cvt_f32_f16_sdwa v99, v207 dst_sel:DWORD dst_unused:UNUSED_PAD src0_sel:WORD_1
	v_cvt_f32_f16_e32 v118, v205
	v_cvt_f32_f16_sdwa v119, v205 dst_sel:DWORD dst_unused:UNUSED_PAD src0_sel:WORD_1
	v_cvt_f32_f16_e32 v120, v206
	v_cvt_f32_f16_sdwa v121, v206 dst_sel:DWORD dst_unused:UNUSED_PAD src0_sel:WORD_1
	v_cvt_f32_f16_e32 v104, v204
	v_cvt_f32_f16_sdwa v105, v204 dst_sel:DWORD dst_unused:UNUSED_PAD src0_sel:WORD_1
	v_pk_fma_f32 v[92:93], v[92:93], 0.5, v[100:101] op_sel_hi:[1,0,1]
	v_pk_fma_f32 v[100:101], v[88:89], 0.5, v[116:117] op_sel_hi:[1,0,1]
	v_pk_fma_f32 v[94:95], v[94:95], 0.5, v[114:115] op_sel_hi:[1,0,1]
	v_pk_fma_f32 v[90:91], v[90:91], 0.5, v[110:111] op_sel_hi:[1,0,1]
	v_cvt_pk_f16_f32 v88, v100, v101
	v_cvt_pk_f16_f32 v89, v90, v91
	v_pk_mul_f32 v[102:103], v[92:93], v[92:93]
	v_pk_mul_f32 v[110:111], v[94:95], v[94:95]
	v_pk_mul_f32 v[100:101], v[100:101], v[100:101]
	v_pk_mul_f32 v[90:91], v[90:91], v[90:91]
	v_pk_fma_f32 v[104:105], v[84:85], 0.5, v[104:105] op_sel_hi:[1,0,1]
	v_pk_fma_f32 v[114:115], v[80:81], 0.5, v[120:121] op_sel_hi:[1,0,1]
	v_pk_fma_f32 v[116:117], v[86:87], 0.5, v[118:119] op_sel_hi:[1,0,1]
	v_pk_fma_f32 v[80:81], v[82:83], 0.5, v[98:99] op_sel_hi:[1,0,1]
	v_pk_mul_f32 v[82:83], v[104:105], v[104:105]
	v_pk_mul_f32 v[84:85], v[116:117], v[116:117]
	v_pk_mul_f32 v[86:87], v[114:115], v[114:115]
	v_pk_mul_f32 v[98:99], v[80:81], v[80:81]
	v_add_f32_e32 v90, v90, v91
	v_add_f32_e32 v91, v100, v101
	s_waitcnt lgkmcnt(0)
	v_add_f32_e32 v97, v110, v111
	v_add_f32_e32 v100, v102, v103
	v_add_f32_e32 v90, v91, v90
	v_add_f32_e32 v91, v100, v97
	v_add_f32_e32 v97, v98, v99
	v_add_f32_e32 v86, v86, v87
	v_add_f32_e32 v84, v84, v85
	v_add_f32_e32 v82, v82, v83
	v_add_f32_e32 v85, v86, v97
	v_add_f32_e32 v82, v82, v84
	v_add_f32_e32 v83, v91, v90
	v_add_f32_e32 v82, v82, v85
	v_add_f32_e32 v82, v83, v82
	ds_bpermute_b32 v83, v166, v82
	v_cvt_pk_f16_f32 v85, v80, v81
	v_cvt_pk_f16_f32 v87, v94, v95
	v_cvt_pk_f16_f32 v86, v92, v93
	v_cvt_pk_f16_f32 v84, v114, v115
	s_waitcnt lgkmcnt(0)
	v_add_f32_e32 v80, v82, v83
	ds_bpermute_b32 v81, v112, v80
	v_cvt_pk_f16_f32 v83, v116, v117
	v_cvt_pk_f16_f32 v82, v104, v105
	global_store_dwordx4 v[106:107], v[86:89], off
	global_store_dwordx4 v[108:109], v[82:85], off
	s_and_saveexec_b64 s[16:17], s[6:7]
	s_cbranch_execz .LBB0_874
	v_lshl_add_u32 v136, v96, 4, s18
	s_waitcnt lgkmcnt(0)
	v_add_f32_e32 v82, v80, v81
	v_lshl_add_u64 v[80:81], v[136:137], 2, s[42:43]
	global_store_dword v[80:81], v82, off
.LBB0_874:
	s_or_b64 exec, exec, s[16:17]
	v_add_u32_e32 v80, 48, v167
	v_lshl_add_u32 v136, v80, 10, v168
	v_lshl_add_u64 v[90:91], v[136:137], 1, s[40:41]
	v_add_u32_e32 v136, 0x80, v136
	v_lshl_add_u64 v[92:93], v[136:137], 1, s[40:41]
	s_waitcnt vmcnt(10)
	v_cvt_f32_f16_e32 v94, v211
	v_cvt_f32_f16_sdwa v95, v211 dst_sel:DWORD dst_unused:UNUSED_PAD src0_sel:WORD_1
	v_cvt_f32_f16_e32 v96, v209
	v_cvt_f32_f16_sdwa v97, v209 dst_sel:DWORD dst_unused:UNUSED_PAD src0_sel:WORD_1
	v_cvt_f32_f16_e32 v98, v210
	v_cvt_f32_f16_sdwa v99, v210 dst_sel:DWORD dst_unused:UNUSED_PAD src0_sel:WORD_1
	v_cvt_f32_f16_e32 v84, v208
	v_cvt_f32_f16_sdwa v85, v208 dst_sel:DWORD dst_unused:UNUSED_PAD src0_sel:WORD_1
	v_cvt_f32_f16_e32 v82, v215
	v_cvt_f32_f16_sdwa v83, v215 dst_sel:DWORD dst_unused:UNUSED_PAD src0_sel:WORD_1
	v_cvt_f32_f16_e32 v100, v213
	v_cvt_f32_f16_sdwa v101, v213 dst_sel:DWORD dst_unused:UNUSED_PAD src0_sel:WORD_1
	v_cvt_f32_f16_e32 v102, v214
	v_cvt_f32_f16_sdwa v103, v214 dst_sel:DWORD dst_unused:UNUSED_PAD src0_sel:WORD_1
	v_cvt_f32_f16_e32 v88, v212
	v_cvt_f32_f16_sdwa v89, v212 dst_sel:DWORD dst_unused:UNUSED_PAD src0_sel:WORD_1
	v_pk_fma_f32 v[76:77], v[76:77], 0.5, v[84:85] op_sel_hi:[1,0,1]
	v_pk_fma_f32 v[84:85], v[72:73], 0.5, v[98:99] op_sel_hi:[1,0,1]
	v_pk_fma_f32 v[78:79], v[78:79], 0.5, v[96:97] op_sel_hi:[1,0,1]
	v_pk_fma_f32 v[74:75], v[74:75], 0.5, v[94:95] op_sel_hi:[1,0,1]
	v_cvt_pk_f16_f32 v72, v84, v85
	v_cvt_pk_f16_f32 v73, v74, v75
	v_pk_mul_f32 v[86:87], v[76:77], v[76:77]
	v_pk_mul_f32 v[94:95], v[78:79], v[78:79]
	v_pk_mul_f32 v[84:85], v[84:85], v[84:85]
	v_pk_mul_f32 v[74:75], v[74:75], v[74:75]
	v_pk_fma_f32 v[88:89], v[68:69], 0.5, v[88:89] op_sel_hi:[1,0,1]
	v_pk_fma_f32 v[96:97], v[64:65], 0.5, v[102:103] op_sel_hi:[1,0,1]
	v_pk_fma_f32 v[98:99], v[70:71], 0.5, v[100:101] op_sel_hi:[1,0,1]
	v_pk_fma_f32 v[64:65], v[66:67], 0.5, v[82:83] op_sel_hi:[1,0,1]
	v_pk_mul_f32 v[66:67], v[88:89], v[88:89]
	v_pk_mul_f32 v[68:69], v[98:99], v[98:99]
	v_pk_mul_f32 v[70:71], v[96:97], v[96:97]
	v_pk_mul_f32 v[82:83], v[64:65], v[64:65]
	v_add_f32_e32 v74, v74, v75
	v_add_f32_e32 v75, v84, v85
	s_waitcnt lgkmcnt(0)
	v_add_f32_e32 v81, v94, v95
	v_add_f32_e32 v84, v86, v87
	v_add_f32_e32 v74, v75, v74
	v_add_f32_e32 v75, v84, v81
	v_add_f32_e32 v81, v82, v83
	v_add_f32_e32 v70, v70, v71
	v_add_f32_e32 v68, v68, v69
	v_add_f32_e32 v66, v66, v67
	v_add_f32_e32 v69, v70, v81
	v_add_f32_e32 v66, v66, v68
	v_add_f32_e32 v67, v75, v74
	v_add_f32_e32 v66, v66, v69
	v_add_f32_e32 v66, v67, v66
	ds_bpermute_b32 v67, v166, v66
	v_cvt_pk_f16_f32 v69, v64, v65
	v_cvt_pk_f16_f32 v71, v78, v79
	v_cvt_pk_f16_f32 v70, v76, v77
	v_cvt_pk_f16_f32 v68, v96, v97
	s_waitcnt lgkmcnt(0)
	v_add_f32_e32 v64, v66, v67
	ds_bpermute_b32 v65, v112, v64
	v_cvt_pk_f16_f32 v67, v98, v99
	v_cvt_pk_f16_f32 v66, v88, v89
	global_store_dwordx4 v[90:91], v[70:73], off
	global_store_dwordx4 v[92:93], v[66:69], off
	s_and_saveexec_b64 s[16:17], s[6:7]
	s_cbranch_execz .LBB0_876
	v_lshl_add_u32 v136, v80, 4, s18
	s_waitcnt lgkmcnt(0)
	v_add_f32_e32 v66, v64, v65
	v_lshl_add_u64 v[64:65], v[136:137], 2, s[42:43]
	global_store_dword v[64:65], v66, off
;   __device__ __forceinline__ void operator()(const pg8::f32x4 (&acc)[2][2][4][2], const pg8::Unit& u, int wr, int wc, int fr, int fq) const {
;     ...
;         const int tok = row0 + ai * 128 + m * 16; float ss = 0.f;
; #pragma unroll
;         for (int bj = 0; bj < 2; ++bj) {
;           const unsigned off = (unsigned)tok * DM + colb + 128 * bj;
;           f8_t n = __builtin_convertvector(*(const h8_t*)(x16 + off), f8_t);
; #pragma unroll
;           for (int c = 0; c < 4; ++c) { n[c] += sc * acc[ai][bj][m][0][c]; n[4 + c] += sc * acc[ai][bj][m][1][c]; }
;           if (aux) {
;             *(h8_t*)(x16 + off) = __builtin_convertvector(n, h8_t);
;             ss += ((n[0] * n[0] + n[1] * n[1]) + (n[2] * n[2] + n[3] * n[3])) + ((n[4] * n[4] + n[5] * n[5]) + (n[6] * n[6] + n[7] * n[7]));
;           } else {
;             *(f32x4*)(xout + off) = (f32x4){n[0], n[1], n[2], n[3]}; *(f32x4*)(xout + off + 4) = (f32x4){n[4], n[5], n[6], n[7]};
;           }
;         }
;         if (aux) { ss += __shfl_xor(ss, 16); ss += __shfl_xor(ss, 32); if (fq == 0) ssq[(unsigned)tok * 16 + u.pn * 4 + wc] = ss; }
;         if (m & 1) asm volatile("" ::: "memory");
;       }
.LBB0_876:
	s_or_b64 exec, exec, s[16:17]
	v_add_u32_e32 v64, 0x80, v167
	v_lshl_add_u32 v136, v64, 10, v168
	v_lshl_add_u64 v[74:75], v[136:137], 1, s[40:41]
	v_add_u32_e32 v136, 0x80, v136
	v_lshl_add_u64 v[76:77], v[136:137], 1, s[40:41]
	s_waitcnt vmcnt(10)
	v_cvt_f32_f16_e32 v78, v219
	v_cvt_f32_f16_sdwa v79, v219 dst_sel:DWORD dst_unused:UNUSED_PAD src0_sel:WORD_1
	v_cvt_f32_f16_e32 v80, v217
	v_cvt_f32_f16_sdwa v81, v217 dst_sel:DWORD dst_unused:UNUSED_PAD src0_sel:WORD_1
	v_cvt_f32_f16_e32 v82, v218
	v_cvt_f32_f16_sdwa v83, v218 dst_sel:DWORD dst_unused:UNUSED_PAD src0_sel:WORD_1
	v_cvt_f32_f16_e32 v68, v216
	v_cvt_f32_f16_sdwa v69, v216 dst_sel:DWORD dst_unused:UNUSED_PAD src0_sel:WORD_1
	v_cvt_f32_f16_e32 v66, v223
	v_cvt_f32_f16_sdwa v67, v223 dst_sel:DWORD dst_unused:UNUSED_PAD src0_sel:WORD_1
	v_cvt_f32_f16_e32 v84, v221
	v_cvt_f32_f16_sdwa v85, v221 dst_sel:DWORD dst_unused:UNUSED_PAD src0_sel:WORD_1
	v_cvt_f32_f16_e32 v86, v222
	v_cvt_f32_f16_sdwa v87, v222 dst_sel:DWORD dst_unused:UNUSED_PAD src0_sel:WORD_1
	v_cvt_f32_f16_e32 v72, v220
	v_cvt_f32_f16_sdwa v73, v220 dst_sel:DWORD dst_unused:UNUSED_PAD src0_sel:WORD_1
	v_pk_fma_f32 v[60:61], v[60:61], 0.5, v[68:69] op_sel_hi:[1,0,1]
	v_pk_fma_f32 v[68:69], v[56:57], 0.5, v[82:83] op_sel_hi:[1,0,1]
	v_pk_fma_f32 v[62:63], v[62:63], 0.5, v[80:81] op_sel_hi:[1,0,1]
	v_pk_fma_f32 v[58:59], v[58:59], 0.5, v[78:79] op_sel_hi:[1,0,1]
	v_cvt_pk_f16_f32 v56, v68, v69
	v_cvt_pk_f16_f32 v57, v58, v59
	v_pk_mul_f32 v[70:71], v[60:61], v[60:61]
	v_pk_mul_f32 v[78:79], v[62:63], v[62:63]
	v_pk_mul_f32 v[68:69], v[68:69], v[68:69]
	v_pk_mul_f32 v[58:59], v[58:59], v[58:59]
	v_pk_fma_f32 v[72:73], v[52:53], 0.5, v[72:73] op_sel_hi:[1,0,1]
	v_pk_fma_f32 v[80:81], v[48:49], 0.5, v[86:87] op_sel_hi:[1,0,1]
	v_pk_fma_f32 v[82:83], v[54:55], 0.5, v[84:85] op_sel_hi:[1,0,1]
	v_pk_fma_f32 v[48:49], v[50:51], 0.5, v[66:67] op_sel_hi:[1,0,1]
	v_pk_mul_f32 v[50:51], v[72:73], v[72:73]
	v_pk_mul_f32 v[52:53], v[82:83], v[82:83]
	v_pk_mul_f32 v[54:55], v[80:81], v[80:81]
	v_pk_mul_f32 v[66:67], v[48:49], v[48:49]
	v_add_f32_e32 v58, v58, v59
	v_add_f32_e32 v59, v68, v69
	s_waitcnt lgkmcnt(0)
	v_add_f32_e32 v65, v78, v79
	v_add_f32_e32 v68, v70, v71
	v_add_f32_e32 v58, v59, v58
	v_add_f32_e32 v59, v68, v65
	v_add_f32_e32 v65, v66, v67
	v_add_f32_e32 v54, v54, v55
	v_add_f32_e32 v52, v52, v53
	v_add_f32_e32 v50, v50, v51
	v_add_f32_e32 v53, v54, v65
	v_add_f32_e32 v50, v50, v52
	v_add_f32_e32 v51, v59, v58
	v_add_f32_e32 v50, v50, v53
	v_add_f32_e32 v50, v51, v50
	ds_bpermute_b32 v51, v166, v50
	v_cvt_pk_f16_f32 v53, v48, v49
	v_cvt_pk_f16_f32 v55, v62, v63
	v_cvt_pk_f16_f32 v54, v60, v61
	v_cvt_pk_f16_f32 v52, v80, v81
	s_waitcnt lgkmcnt(0)
	v_add_f32_e32 v48, v50, v51
	ds_bpermute_b32 v49, v112, v48
	v_cvt_pk_f16_f32 v51, v82, v83
	v_cvt_pk_f16_f32 v50, v72, v73
	global_store_dwordx4 v[74:75], v[54:57], off
	global_store_dwordx4 v[76:77], v[50:53], off
	s_and_saveexec_b64 s[16:17], s[6:7]
	s_cbranch_execz .LBB0_878
	v_lshl_add_u32 v136, v64, 4, s18
	s_waitcnt lgkmcnt(0)
	v_add_f32_e32 v50, v48, v49
	v_lshl_add_u64 v[48:49], v[136:137], 2, s[42:43]
	global_store_dword v[48:49], v50, off
.LBB0_878:
	s_or_b64 exec, exec, s[16:17]
	v_add_u32_e32 v48, 0x90, v167
	v_lshl_add_u32 v136, v48, 10, v168
	v_lshl_add_u64 v[58:59], v[136:137], 1, s[40:41]
	v_add_u32_e32 v136, 0x80, v136
	v_lshl_add_u64 v[60:61], v[136:137], 1, s[40:41]
	s_waitcnt vmcnt(10)
	v_cvt_f32_f16_e32 v62, v231
	v_cvt_f32_f16_sdwa v63, v231 dst_sel:DWORD dst_unused:UNUSED_PAD src0_sel:WORD_1
	v_cvt_f32_f16_e32 v64, v229
	v_cvt_f32_f16_sdwa v65, v229 dst_sel:DWORD dst_unused:UNUSED_PAD src0_sel:WORD_1
	v_cvt_f32_f16_e32 v66, v230
	v_cvt_f32_f16_sdwa v67, v230 dst_sel:DWORD dst_unused:UNUSED_PAD src0_sel:WORD_1
	v_cvt_f32_f16_e32 v52, v228
	v_cvt_f32_f16_sdwa v53, v228 dst_sel:DWORD dst_unused:UNUSED_PAD src0_sel:WORD_1
	v_cvt_f32_f16_e32 v50, v247
	v_cvt_f32_f16_sdwa v51, v247 dst_sel:DWORD dst_unused:UNUSED_PAD src0_sel:WORD_1
	v_cvt_f32_f16_e32 v68, v245
	v_cvt_f32_f16_sdwa v69, v245 dst_sel:DWORD dst_unused:UNUSED_PAD src0_sel:WORD_1
	v_cvt_f32_f16_e32 v70, v246
	v_cvt_f32_f16_sdwa v71, v246 dst_sel:DWORD dst_unused:UNUSED_PAD src0_sel:WORD_1
	v_cvt_f32_f16_e32 v56, v244
	v_cvt_f32_f16_sdwa v57, v244 dst_sel:DWORD dst_unused:UNUSED_PAD src0_sel:WORD_1
	v_pk_fma_f32 v[44:45], v[44:45], 0.5, v[52:53] op_sel_hi:[1,0,1]
	v_pk_fma_f32 v[52:53], v[40:41], 0.5, v[66:67] op_sel_hi:[1,0,1]
	v_pk_fma_f32 v[46:47], v[46:47], 0.5, v[64:65] op_sel_hi:[1,0,1]
	v_pk_fma_f32 v[42:43], v[42:43], 0.5, v[62:63] op_sel_hi:[1,0,1]
	v_cvt_pk_f16_f32 v40, v52, v53
	v_cvt_pk_f16_f32 v41, v42, v43
	v_pk_mul_f32 v[54:55], v[44:45], v[44:45]
	v_pk_mul_f32 v[62:63], v[46:47], v[46:47]
	v_pk_mul_f32 v[52:53], v[52:53], v[52:53]
	v_pk_mul_f32 v[42:43], v[42:43], v[42:43]
	v_pk_fma_f32 v[56:57], v[36:37], 0.5, v[56:57] op_sel_hi:[1,0,1]
	v_pk_fma_f32 v[64:65], v[32:33], 0.5, v[70:71] op_sel_hi:[1,0,1]
	v_pk_fma_f32 v[66:67], v[38:39], 0.5, v[68:69] op_sel_hi:[1,0,1]
	v_pk_fma_f32 v[32:33], v[34:35], 0.5, v[50:51] op_sel_hi:[1,0,1]
	v_pk_mul_f32 v[34:35], v[56:57], v[56:57]
	v_pk_mul_f32 v[36:37], v[66:67], v[66:67]
	v_pk_mul_f32 v[38:39], v[64:65], v[64:65]
	v_pk_mul_f32 v[50:51], v[32:33], v[32:33]
	v_add_f32_e32 v42, v42, v43
	v_add_f32_e32 v43, v52, v53
	s_waitcnt lgkmcnt(0)
	v_add_f32_e32 v49, v62, v63
	v_add_f32_e32 v52, v54, v55
	v_add_f32_e32 v42, v43, v42
	v_add_f32_e32 v43, v52, v49
	v_add_f32_e32 v49, v50, v51
	v_add_f32_e32 v38, v38, v39
	v_add_f32_e32 v36, v36, v37
	v_add_f32_e32 v34, v34, v35
	v_add_f32_e32 v37, v38, v49
	v_add_f32_e32 v34, v34, v36
	v_add_f32_e32 v35, v43, v42
	v_add_f32_e32 v34, v34, v37
	v_add_f32_e32 v34, v35, v34
	ds_bpermute_b32 v35, v166, v34
	v_cvt_pk_f16_f32 v37, v32, v33
	v_cvt_pk_f16_f32 v39, v46, v47
	v_cvt_pk_f16_f32 v38, v44, v45
	v_cvt_pk_f16_f32 v36, v64, v65
	s_waitcnt lgkmcnt(0)
	v_add_f32_e32 v32, v34, v35
	ds_bpermute_b32 v33, v112, v32
	v_cvt_pk_f16_f32 v35, v66, v67
	v_cvt_pk_f16_f32 v34, v56, v57
	global_store_dwordx4 v[58:59], v[38:41], off
	global_store_dwordx4 v[60:61], v[34:37], off
	s_and_saveexec_b64 s[16:17], s[6:7]
	s_cbranch_execz .LBB0_880
	v_lshl_add_u32 v136, v48, 4, s18
	s_waitcnt lgkmcnt(0)
	v_add_f32_e32 v34, v32, v33
	v_lshl_add_u64 v[32:33], v[136:137], 2, s[42:43]
	global_store_dword v[32:33], v34, off

; #define PG8_STAGE(bufoff, gbase, voff) do { _Pragma("unroll") for (int _i = 0; _i < 2; ++_i) \
;         __builtin_amdgcn_global_load_lds((const unsigned*)((const char*)(gbase) + (voff)[_i]), (PG8_LAS unsigned*)(lds + (bufoff) + ldsw + _i * 8192), 16, 0, 0); } while (0)
; #define PG8_LDA(dst, b, h) do { _Pragma("unroll") for (int m = 0; m < 4; ++m) _Pragma("unroll") for (int k = 0; k < 2; ++k) dst[m][k] = *(const PG8_LAS bf16x8*)(lds + PG8_SA(b, h) + aoff + m * 2048 + k * 1024); } while (0)
; #define PG8_LDB(dst, b, h) do { _Pragma("unroll") for (int n = 0; n < 2; ++n) _Pragma("unroll") for (int k = 0; k < 2; ++k) dst[n][k] = *(const PG8_LAS bf16x8*)(lds + PG8_SB(b, h) + boff + n * 2048 + k * 1024); } while (0)
; #define PG8_MMA(ai, bj, At, Bt) do { __builtin_amdgcn_s_setprio(1); _Pragma("unroll") for (int m = 0; m < 4; ++m) _Pragma("unroll") for (int n = 0; n < 2; ++n) _Pragma("unroll") for (int k = 0; k < 2; ++k) \
;         acc[ai][bj][m][n] = mma16<F16>(Bt[n][k], At[m][k], acc[ai][bj][m][n]); __builtin_amdgcn_s_setprio(0); } while (0)
; #define PG8_WAIT_V(n) asm volatile("s_waitcnt vmcnt(" #n ")" ::: "memory")
; #define PG8_WAIT_L(n) asm volatile("s_waitcnt lgkmcnt(" #n ")" ::: "memory")
; #define PG8_BAR __builtin_amdgcn_s_barrier()
; #define PG8_SCHED __builtin_amdgcn_sched_barrier(0)
; template <class Epi, class Sched, bool ALIGN_EPI = false, bool SP2 = false, bool F16 = false, bool TOKPERM = false>
; __device__ __forceinline__ void gemm_phase(PG8_LAS unsigned char* lds, const Gemm g, const Sched& S, const Epi& E, int wv) {
;     ...
;             PG8_LDB(B0, 0, 0); PG8_LDB(B1, 0, 1); PG8_SCHED; PG8_LDA(At, 0, 0); PG8_STAGE(PG8_SA(1, 1), a1 + hstep, voffA);
;             PG8_WAIT_V(8); PG8_WAIT_L(0); PG8_BAR; PG8_MMA(0, 0, At, B0); PG8_MMA(0, 1, At, B1); PG8_BAR; PG8_SCHED;
;             PG8_LDA(At, 0, 1); PG8_STAGE(PG8_SB(0, 0), b2, voffB); PG8_STAGE(PG8_SB(0, 1), b2 + hstep, voffB); PG8_STAGE(PG8_SA(0, 0), a2, voffA);
;             PG8_WAIT_V(8); PG8_WAIT_L(0); PG8_BAR; PG8_MMA(1, 0, At, B0); PG8_MMA(1, 1, At, B1); PG8_BAR; PG8_SCHED;
.LBB0_1524:
	ds_read_b128 v[166:169], v149
	ds_read_b128 v[170:173], v150
	ds_read_b128 v[174:177], v151
	ds_read_b128 v[178:181], v152
	ds_read_b128 v[182:185], v153
	ds_read_b128 v[186:189], v154
	ds_read_b128 v[190:193], v155
	ds_read_b128 v[194:197], v156
	s_add_u32 s44, s24, 0xfffc0080
	s_addc_u32 s45, s25, -1
	s_cmp_eq_u32 s65, 12
	s_cselect_b32 s47, s15, s45
	s_cselect_b32 s46, s21, s44
	s_cselect_b32 s45, s13, s64
	s_cselect_b32 s44, s62, s63
	s_mov_b32 m0, s60
	v_lshl_add_u64 v[232:233], s[24:25], 0, v[138:139]
	ds_read_b128 v[198:201], v147
	ds_read_b128 v[202:205], v147 offset:1024
	ds_read_b128 v[206:209], v147 offset:2048
	ds_read_b128 v[210:213], v147 offset:3072
	ds_read_b128 v[214:217], v147 offset:4096
	ds_read_b128 v[218:221], v147 offset:5120
	ds_read_b128 v[222:225], v147 offset:6144
	ds_read_b128 v[228:231], v147 offset:7168
	global_load_lds_dwordx4 v[232:233], off
	v_lshl_add_u64 v[232:233], s[24:25], 0, v[140:141]
	s_mov_b32 m0, s61
	s_nop 0
	global_load_lds_dwordx4 v[232:233], off
	s_waitcnt vmcnt(8)
	s_waitcnt lgkmcnt(0)
	s_barrier
	s_setprio 1
	s_waitcnt lgkmcnt(0)
	v_mfma_f32_16x16x32_bf16 v[124:127], v[166:169], v[198:201], v[124:127]
	v_mfma_f32_16x16x32_bf16 v[120:123], v[174:177], v[198:201], v[120:123]
	v_mfma_f32_16x16x32_bf16 v[108:111], v[166:169], v[206:209], v[108:111]
	v_mfma_f32_16x16x32_bf16 v[104:107], v[174:177], v[206:209], v[104:107]
	v_mfma_f32_16x16x32_bf16 v[92:95], v[166:169], v[214:217], v[92:95]
	v_mfma_f32_16x16x32_bf16 v[88:91], v[174:177], v[214:217], v[88:91]
	v_mfma_f32_16x16x32_bf16 v[76:79], v[166:169], v[222:225], v[76:79]
	v_mfma_f32_16x16x32_bf16 v[72:75], v[174:177], v[222:225], v[72:75]
	v_mfma_f32_16x16x32_bf16 v[124:127], v[170:173], v[202:205], v[124:127]
	v_mfma_f32_16x16x32_bf16 v[120:123], v[178:181], v[202:205], v[120:123]
	v_mfma_f32_16x16x32_bf16 v[108:111], v[170:173], v[210:213], v[108:111]
	v_mfma_f32_16x16x32_bf16 v[104:107], v[178:181], v[210:213], v[104:107]
	v_mfma_f32_16x16x32_bf16 v[92:95], v[170:173], v[218:221], v[92:95]
	v_mfma_f32_16x16x32_bf16 v[88:91], v[178:181], v[218:221], v[88:91]
	v_mfma_f32_16x16x32_bf16 v[76:79], v[170:173], v[228:231], v[76:79]
	v_mfma_f32_16x16x32_bf16 v[72:75], v[178:181], v[228:231], v[72:75]
	s_setprio 0
	s_setprio 1
	v_mfma_f32_16x16x32_bf16 v[116:119], v[182:185], v[198:201], v[116:119]
	v_mfma_f32_16x16x32_bf16 v[112:115], v[190:193], v[198:201], v[112:115]
	v_mfma_f32_16x16x32_bf16 v[100:103], v[182:185], v[206:209], v[100:103]
	v_mfma_f32_16x16x32_bf16 v[96:99], v[190:193], v[206:209], v[96:99]
	v_mfma_f32_16x16x32_bf16 v[84:87], v[182:185], v[214:217], v[84:87]
	v_mfma_f32_16x16x32_bf16 v[80:83], v[190:193], v[214:217], v[80:83]
	v_mfma_f32_16x16x32_bf16 v[68:71], v[182:185], v[222:225], v[68:71]
	v_mfma_f32_16x16x32_bf16 v[64:67], v[190:193], v[222:225], v[64:67]
	v_mfma_f32_16x16x32_bf16 v[116:119], v[186:189], v[202:205], v[116:119]
	v_mfma_f32_16x16x32_bf16 v[112:115], v[194:197], v[202:205], v[112:115]
	v_mfma_f32_16x16x32_bf16 v[100:103], v[186:189], v[210:213], v[100:103]
	v_mfma_f32_16x16x32_bf16 v[96:99], v[194:197], v[210:213], v[96:99]
	v_mfma_f32_16x16x32_bf16 v[84:87], v[186:189], v[218:221], v[84:87]
	v_mfma_f32_16x16x32_bf16 v[80:83], v[194:197], v[218:221], v[80:83]
	v_mfma_f32_16x16x32_bf16 v[68:71], v[186:189], v[228:231], v[68:71]
	v_mfma_f32_16x16x32_bf16 v[64:67], v[194:197], v[228:231], v[64:67]
	s_setprio 0
	s_barrier
	s_mov_b32 m0, s4
	v_lshl_add_u64 v[232:233], s[44:45], 0, v[130:131]
	s_add_u32 s66, s44, 0x40000
	ds_read_b128 v[198:201], v147 offset:16384
	ds_read_b128 v[202:205], v147 offset:17408
	ds_read_b128 v[206:209], v147 offset:18432
	ds_read_b128 v[210:213], v147 offset:19456
	ds_read_b128 v[214:217], v147 offset:20480
	ds_read_b128 v[218:221], v147 offset:21504
	ds_read_b128 v[222:225], v147 offset:22528
	ds_read_b128 v[228:231], v147 offset:23552
	global_load_lds_dwordx4 v[232:233], off
	v_lshl_add_u64 v[234:235], s[44:45], 0, v[134:135]
	s_mov_b32 m0, s5
	s_addc_u32 s67, s45, 0
	global_load_lds_dwordx4 v[234:235], off
	v_lshl_add_u64 v[236:237], s[66:67], 0, v[130:131]
	s_mov_b32 m0, s23
	v_lshl_add_u64 v[238:239], s[46:47], 0, v[132:133]
	global_load_lds_dwordx4 v[236:237], off
	v_lshl_add_u64 v[236:237], s[66:67], 0, v[134:135]
	s_mov_b32 m0, s33
	s_nop 0
	global_load_lds_dwordx4 v[236:237], off
	v_lshl_add_u64 v[236:237], s[46:47], 0, v[128:129]
	s_mov_b32 m0, s3
	s_nop 0
	global_load_lds_dwordx4 v[236:237], off
	s_mov_b32 m0, s36
	s_nop 0
	global_load_lds_dwordx4 v[238:239], off
	s_waitcnt vmcnt(8)
	s_waitcnt lgkmcnt(0)
	s_barrier
; #define PG8_STAGE(bufoff, gbase, voff) do { _Pragma("unroll") for (int _i = 0; _i < 2; ++_i) \
;         __builtin_amdgcn_global_load_lds((const unsigned*)((const char*)(gbase) + (voff)[_i]), (PG8_LAS unsigned*)(lds + (bufoff) + ldsw + _i * 8192), 16, 0, 0); } while (0)
; #define PG8_LDA(dst, b, h) do { _Pragma("unroll") for (int m = 0; m < 4; ++m) _Pragma("unroll") for (int k = 0; k < 2; ++k) dst[m][k] = *(const PG8_LAS bf16x8*)(lds + PG8_SA(b, h) + aoff + m * 2048 + k * 1024); } while (0)
; #define PG8_LDB(dst, b, h) do { _Pragma("unroll") for (int n = 0; n < 2; ++n) _Pragma("unroll") for (int k = 0; k < 2; ++k) dst[n][k] = *(const PG8_LAS bf16x8*)(lds + PG8_SB(b, h) + boff + n * 2048 + k * 1024); } while (0)
; #define PG8_MMA(ai, bj, At, Bt) do { __builtin_amdgcn_s_setprio(1); _Pragma("unroll") for (int m = 0; m < 4; ++m) _Pragma("unroll") for (int n = 0; n < 2; ++n) _Pragma("unroll") for (int k = 0; k < 2; ++k) \
;         acc[ai][bj][m][n] = mma16<F16>(Bt[n][k], At[m][k], acc[ai][bj][m][n]); __builtin_amdgcn_s_setprio(0); } while (0)
; #define PG8_WAIT_V(n) asm volatile("s_waitcnt vmcnt(" #n ")" ::: "memory")
; #define PG8_WAIT_L(n) asm volatile("s_waitcnt lgkmcnt(" #n ")" ::: "memory")
; #define PG8_BAR __builtin_amdgcn_s_barrier()
; #define PG8_SCHED __builtin_amdgcn_sched_barrier(0)
; template <class Epi, class Sched, bool ALIGN_EPI = false, bool SP2 = false, bool F16 = false, bool TOKPERM = false>
; __device__ __forceinline__ void gemm_phase(PG8_LAS unsigned char* lds, const Gemm g, const Sched& S, const Epi& E, int wv) {
;     ...
;             PG8_WAIT_V(8); PG8_WAIT_L(0); PG8_BAR; PG8_MMA(1, 0, At, B0); PG8_MMA(1, 1, At, B1); PG8_BAR; PG8_SCHED;
;             PG8_LDB(B0, 1, 0); PG8_LDB(B1, 1, 1); PG8_SCHED; PG8_LDA(At, 1, 0); PG8_STAGE(PG8_SA(0, 1), a2 + hstep, voffA);
;             PG8_WAIT_V(8); PG8_WAIT_L(0); PG8_BAR; PG8_MMA(0, 0, At, B0); PG8_MMA(0, 1, At, B1); PG8_BAR; PG8_SCHED;
;             PG8_LDA(At, 1, 1); PG8_STAGE(PG8_SB(1, 0), b3, voffB); PG8_STAGE(PG8_SB(1, 1), b3 + hstep, voffB); PG8_STAGE(PG8_SA(1, 0), a3, voffA);
;             PG8_WAIT_V(8); PG8_WAIT_L(0); PG8_BAR; PG8_MMA(1, 0, At, B0); PG8_MMA(1, 1, At, B1); PG8_BAR; PG8_SCHED;
	s_setprio 1
	s_waitcnt lgkmcnt(0)
	v_mfma_f32_16x16x32_bf16 v[60:63], v[166:169], v[198:201], v[60:63]
	v_mfma_f32_16x16x32_bf16 v[56:59], v[174:177], v[198:201], v[56:59]
	v_mfma_f32_16x16x32_bf16 v[44:47], v[166:169], v[206:209], v[44:47]
	v_mfma_f32_16x16x32_bf16 v[40:43], v[174:177], v[206:209], v[40:43]
	v_mfma_f32_16x16x32_bf16 v[28:31], v[166:169], v[214:217], v[28:31]
	v_mfma_f32_16x16x32_bf16 v[24:27], v[174:177], v[214:217], v[24:27]
	v_mfma_f32_16x16x32_bf16 v[12:15], v[166:169], v[222:225], v[12:15]
	v_mfma_f32_16x16x32_bf16 v[8:11], v[174:177], v[222:225], v[8:11]
	v_mfma_f32_16x16x32_bf16 v[60:63], v[170:173], v[202:205], v[60:63]
	v_mfma_f32_16x16x32_bf16 v[56:59], v[178:181], v[202:205], v[56:59]
	v_mfma_f32_16x16x32_bf16 v[44:47], v[170:173], v[210:213], v[44:47]
	v_mfma_f32_16x16x32_bf16 v[40:43], v[178:181], v[210:213], v[40:43]
	v_mfma_f32_16x16x32_bf16 v[28:31], v[170:173], v[218:221], v[28:31]
	v_mfma_f32_16x16x32_bf16 v[24:27], v[178:181], v[218:221], v[24:27]
	v_mfma_f32_16x16x32_bf16 v[12:15], v[170:173], v[228:231], v[12:15]
	v_mfma_f32_16x16x32_bf16 v[8:11], v[178:181], v[228:231], v[8:11]
	s_setprio 0
	s_setprio 1
	v_mfma_f32_16x16x32_bf16 v[52:55], v[182:185], v[198:201], v[52:55]
	v_mfma_f32_16x16x32_bf16 v[48:51], v[190:193], v[198:201], v[48:51]
	v_mfma_f32_16x16x32_bf16 v[36:39], v[182:185], v[206:209], v[36:39]
	v_mfma_f32_16x16x32_bf16 v[32:35], v[190:193], v[206:209], v[32:35]
	v_mfma_f32_16x16x32_bf16 v[20:23], v[182:185], v[214:217], v[20:23]
	v_mfma_f32_16x16x32_bf16 v[16:19], v[190:193], v[214:217], v[16:19]
	v_mfma_f32_16x16x32_bf16 v[4:7], v[182:185], v[222:225], v[4:7]
	v_mfma_f32_16x16x32_bf16 v[0:3], v[190:193], v[222:225], v[0:3]
	v_mfma_f32_16x16x32_bf16 v[52:55], v[186:189], v[202:205], v[52:55]
	v_mfma_f32_16x16x32_bf16 v[48:51], v[194:197], v[202:205], v[48:51]
	v_mfma_f32_16x16x32_bf16 v[36:39], v[186:189], v[210:213], v[36:39]
	v_mfma_f32_16x16x32_bf16 v[32:35], v[194:197], v[210:213], v[32:35]
	v_mfma_f32_16x16x32_bf16 v[20:23], v[186:189], v[218:221], v[20:23]
	v_mfma_f32_16x16x32_bf16 v[16:19], v[194:197], v[218:221], v[16:19]
	v_mfma_f32_16x16x32_bf16 v[4:7], v[186:189], v[228:231], v[4:7]
	v_mfma_f32_16x16x32_bf16 v[0:3], v[194:197], v[228:231], v[0:3]
	s_setprio 0
	s_barrier
	ds_read_b128 v[166:169], v157
	ds_read_b128 v[170:173], v158
	ds_read_b128 v[174:177], v159
	ds_read_b128 v[178:181], v160
	ds_read_b128 v[182:185], v161
	ds_read_b128 v[186:189], v162
	ds_read_b128 v[190:193], v163
	ds_read_b128 v[194:197], v164
	s_add_u32 s46, s46, 0x40000
	s_addc_u32 s47, s47, 0
	s_mov_b32 m0, s37
	v_lshl_add_u64 v[240:241], s[46:47], 0, v[128:129]
	ds_read_b128 v[198:201], v147 offset:32768
	ds_read_b128 v[202:205], v147 offset:33792
	ds_read_b128 v[206:209], v147 offset:34816
	ds_read_b128 v[210:213], v147 offset:35840
	ds_read_b128 v[214:217], v147 offset:36864
	ds_read_b128 v[218:221], v147 offset:37888
	ds_read_b128 v[222:225], v147 offset:38912
	ds_read_b128 v[228:231], v147 offset:39936
	global_load_lds_dwordx4 v[240:241], off
	v_lshl_add_u64 v[240:241], s[46:47], 0, v[132:133]
	s_mov_b32 m0, s48
	s_nop 0
	global_load_lds_dwordx4 v[240:241], off
	s_waitcnt vmcnt(8)
	s_waitcnt lgkmcnt(0)
	s_barrier
	s_setprio 1
	s_waitcnt lgkmcnt(0)
	v_mfma_f32_16x16x32_bf16 v[124:127], v[166:169], v[198:201], v[124:127]
	v_mfma_f32_16x16x32_bf16 v[120:123], v[174:177], v[198:201], v[120:123]
	v_mfma_f32_16x16x32_bf16 v[108:111], v[166:169], v[206:209], v[108:111]
	v_mfma_f32_16x16x32_bf16 v[104:107], v[174:177], v[206:209], v[104:107]
	v_mfma_f32_16x16x32_bf16 v[92:95], v[166:169], v[214:217], v[92:95]
	v_mfma_f32_16x16x32_bf16 v[88:91], v[174:177], v[214:217], v[88:91]
	v_mfma_f32_16x16x32_bf16 v[76:79], v[166:169], v[222:225], v[76:79]
	v_mfma_f32_16x16x32_bf16 v[72:75], v[174:177], v[222:225], v[72:75]
	v_mfma_f32_16x16x32_bf16 v[124:127], v[170:173], v[202:205], v[124:127]
	v_mfma_f32_16x16x32_bf16 v[120:123], v[178:181], v[202:205], v[120:123]
	v_mfma_f32_16x16x32_bf16 v[108:111], v[170:173], v[210:213], v[108:111]
	v_mfma_f32_16x16x32_bf16 v[104:107], v[178:181], v[210:213], v[104:107]
	v_mfma_f32_16x16x32_bf16 v[92:95], v[170:173], v[218:221], v[92:95]
	v_mfma_f32_16x16x32_bf16 v[88:91], v[178:181], v[218:221], v[88:91]
	v_mfma_f32_16x16x32_bf16 v[76:79], v[170:173], v[228:231], v[76:79]
	v_mfma_f32_16x16x32_bf16 v[72:75], v[178:181], v[228:231], v[72:75]
	s_setprio 0
	s_setprio 1
	v_mfma_f32_16x16x32_bf16 v[116:119], v[182:185], v[198:201], v[116:119]
	v_mfma_f32_16x16x32_bf16 v[112:115], v[190:193], v[198:201], v[112:115]
	v_mfma_f32_16x16x32_bf16 v[100:103], v[182:185], v[206:209], v[100:103]
	v_mfma_f32_16x16x32_bf16 v[96:99], v[190:193], v[206:209], v[96:99]
	v_mfma_f32_16x16x32_bf16 v[84:87], v[182:185], v[214:217], v[84:87]
	v_mfma_f32_16x16x32_bf16 v[80:83], v[190:193], v[214:217], v[80:83]
	v_mfma_f32_16x16x32_bf16 v[68:71], v[182:185], v[222:225], v[68:71]
	v_mfma_f32_16x16x32_bf16 v[64:67], v[190:193], v[222:225], v[64:67]
	v_mfma_f32_16x16x32_bf16 v[116:119], v[186:189], v[202:205], v[116:119]
	v_mfma_f32_16x16x32_bf16 v[112:115], v[194:197], v[202:205], v[112:115]
	v_mfma_f32_16x16x32_bf16 v[100:103], v[186:189], v[210:213], v[100:103]
	v_mfma_f32_16x16x32_bf16 v[96:99], v[194:197], v[210:213], v[96:99]
	v_mfma_f32_16x16x32_bf16 v[84:87], v[186:189], v[218:221], v[84:87]
	v_mfma_f32_16x16x32_bf16 v[80:83], v[194:197], v[218:221], v[80:83]
	v_mfma_f32_16x16x32_bf16 v[68:71], v[186:189], v[228:231], v[68:71]
	v_mfma_f32_16x16x32_bf16 v[64:67], v[194:197], v[228:231], v[64:67]
	s_setprio 0
	s_barrier
; #define PG8_STAGE(bufoff, gbase, voff) do { _Pragma("unroll") for (int _i = 0; _i < 2; ++_i) \
;         __builtin_amdgcn_global_load_lds((const unsigned*)((const char*)(gbase) + (voff)[_i]), (PG8_LAS unsigned*)(lds + (bufoff) + ldsw + _i * 8192), 16, 0, 0); } while (0)
; #define PG8_LDA(dst, b, h) do { _Pragma("unroll") for (int m = 0; m < 4; ++m) _Pragma("unroll") for (int k = 0; k < 2; ++k) dst[m][k] = *(const PG8_LAS bf16x8*)(lds + PG8_SA(b, h) + aoff + m * 2048 + k * 1024); } while (0)
; #define PG8_MMA(ai, bj, At, Bt) do { __builtin_amdgcn_s_setprio(1); _Pragma("unroll") for (int m = 0; m < 4; ++m) _Pragma("unroll") for (int n = 0; n < 2; ++n) _Pragma("unroll") for (int k = 0; k < 2; ++k) \
;         acc[ai][bj][m][n] = mma16<F16>(Bt[n][k], At[m][k], acc[ai][bj][m][n]); __builtin_amdgcn_s_setprio(0); } while (0)
; #define PG8_WAIT_V(n) asm volatile("s_waitcnt vmcnt(" #n ")" ::: "memory")
; #define PG8_WAIT_L(n) asm volatile("s_waitcnt lgkmcnt(" #n ")" ::: "memory")
; #define PG8_BAR __builtin_amdgcn_s_barrier()
; #define PG8_SCHED __builtin_amdgcn_sched_barrier(0)
; template <class Epi, class Sched, bool ALIGN_EPI = false, bool SP2 = false, bool F16 = false, bool TOKPERM = false>
; __device__ __forceinline__ void gemm_phase(PG8_LAS unsigned char* lds, const Gemm g, const Sched& S, const Epi& E, int wv) {
;     ...
;             PG8_LDA(At, 1, 1); PG8_STAGE(PG8_SB(1, 0), b3, voffB); PG8_STAGE(PG8_SB(1, 1), b3 + hstep, voffB); PG8_STAGE(PG8_SA(1, 0), a3, voffA);
;             PG8_WAIT_V(8); PG8_WAIT_L(0); PG8_BAR; PG8_MMA(1, 0, At, B0); PG8_MMA(1, 1, At, B1); PG8_BAR; PG8_SCHED;
;   __device__ __forceinline__ void operator()(const pg8::f32x4 (&acc)[2][2][4][2], const pg8::Unit& u, int wr, int wc, int fr, int fq) const {
;     ...
;         const int tok = row0 + ai * 128 + m * 16; float ss = 0.f;
; #pragma unroll
;         for (int bj = 0; bj < 2; ++bj) {
;           const unsigned off = (unsigned)tok * DM + colb + 128 * bj;
;           f8_t n = __builtin_convertvector(*(const h8_t*)(x16 + off), f8_t);
; #pragma unroll
;           for (int c = 0; c < 4; ++c) { n[c] += sc * acc[ai][bj][m][0][c]; n[4 + c] += sc * acc[ai][bj][m][1][c]; }
;           if (aux) {
;             *(h8_t*)(x16 + off) = __builtin_convertvector(n, h8_t);
;             ss += ((n[0] * n[0] + n[1] * n[1]) + (n[2] * n[2] + n[3] * n[3])) + ((n[4] * n[4] + n[5] * n[5]) + (n[6] * n[6] + n[7] * n[7]));
	s_mov_b32 m0, s50
	v_lshl_add_u64 v[232:233], v[232:233], 0, s[10:11]
	s_add_u32 s44, s44, 0x40080
	ds_read_b128 v[198:201], v147 offset:49152
	ds_read_b128 v[202:205], v147 offset:50176
	ds_read_b128 v[206:209], v147 offset:51200
	ds_read_b128 v[210:213], v147 offset:52224
	ds_read_b128 v[214:217], v147 offset:53248
	ds_read_b128 v[218:221], v147 offset:54272
	ds_read_b128 v[222:225], v147 offset:55296
	ds_read_b128 v[228:231], v147 offset:56320
	global_load_lds_dwordx4 v[232:233], off
	v_lshl_add_u64 v[232:233], v[234:235], 0, s[10:11]
	s_mov_b32 m0, s51
	s_addc_u32 s45, s45, 0
	global_load_lds_dwordx4 v[232:233], off
	v_lshl_add_u64 v[232:233], s[44:45], 0, v[130:131]
	s_mov_b32 m0, s54
	s_nop 0
	global_load_lds_dwordx4 v[232:233], off
	v_lshl_add_u64 v[232:233], s[44:45], 0, v[134:135]
	s_mov_b32 m0, s55
	s_nop 0
	global_load_lds_dwordx4 v[232:233], off
	v_lshl_add_u64 v[232:233], v[236:237], 0, s[10:11]
	s_mov_b32 m0, s52
	s_nop 0
	global_load_lds_dwordx4 v[232:233], off
	v_lshl_add_u64 v[232:233], v[238:239], 0, s[10:11]
	s_mov_b32 m0, s53
	s_nop 0
	global_load_lds_dwordx4 v[232:233], off
	s_waitcnt vmcnt(8)
	s_waitcnt lgkmcnt(0)
	s_barrier
	s_setprio 1
	s_waitcnt lgkmcnt(0)
	v_mfma_f32_16x16x32_bf16 v[60:63], v[166:169], v[198:201], v[60:63]
	v_mfma_f32_16x16x32_bf16 v[56:59], v[174:177], v[198:201], v[56:59]
	v_mfma_f32_16x16x32_bf16 v[44:47], v[166:169], v[206:209], v[44:47]
	v_mfma_f32_16x16x32_bf16 v[40:43], v[174:177], v[206:209], v[40:43]
	v_mfma_f32_16x16x32_bf16 v[28:31], v[166:169], v[214:217], v[28:31]
	v_mfma_f32_16x16x32_bf16 v[24:27], v[174:177], v[214:217], v[24:27]
	v_mfma_f32_16x16x32_bf16 v[12:15], v[166:169], v[222:225], v[12:15]
	v_mfma_f32_16x16x32_bf16 v[8:11], v[174:177], v[222:225], v[8:11]
	v_mfma_f32_16x16x32_bf16 v[60:63], v[170:173], v[202:205], v[60:63]
	v_mfma_f32_16x16x32_bf16 v[56:59], v[178:181], v[202:205], v[56:59]
	v_mfma_f32_16x16x32_bf16 v[44:47], v[170:173], v[210:213], v[44:47]
	v_mfma_f32_16x16x32_bf16 v[40:43], v[178:181], v[210:213], v[40:43]
	v_mfma_f32_16x16x32_bf16 v[28:31], v[170:173], v[218:221], v[28:31]
	v_mfma_f32_16x16x32_bf16 v[24:27], v[178:181], v[218:221], v[24:27]
	v_mfma_f32_16x16x32_bf16 v[12:15], v[170:173], v[228:231], v[12:15]
	v_mfma_f32_16x16x32_bf16 v[8:11], v[178:181], v[228:231], v[8:11]
	s_setprio 0
	s_setprio 1
	v_mfma_f32_16x16x32_bf16 v[52:55], v[182:185], v[198:201], v[52:55]
	v_mfma_f32_16x16x32_bf16 v[48:51], v[190:193], v[198:201], v[48:51]
	v_mfma_f32_16x16x32_bf16 v[36:39], v[182:185], v[206:209], v[36:39]
	v_mfma_f32_16x16x32_bf16 v[32:35], v[190:193], v[206:209], v[32:35]
	v_mfma_f32_16x16x32_bf16 v[20:23], v[182:185], v[214:217], v[20:23]
	v_mfma_f32_16x16x32_bf16 v[16:19], v[190:193], v[214:217], v[16:19]
	v_mfma_f32_16x16x32_bf16 v[4:7], v[182:185], v[222:225], v[4:7]
	v_mfma_f32_16x16x32_bf16 v[0:3], v[190:193], v[222:225], v[0:3]
	v_mfma_f32_16x16x32_bf16 v[52:55], v[186:189], v[202:205], v[52:55]
	v_mfma_f32_16x16x32_bf16 v[48:51], v[194:197], v[202:205], v[48:51]
	v_mfma_f32_16x16x32_bf16 v[36:39], v[186:189], v[210:213], v[36:39]
	v_mfma_f32_16x16x32_bf16 v[32:35], v[194:197], v[210:213], v[32:35]
	v_mfma_f32_16x16x32_bf16 v[20:23], v[186:189], v[218:221], v[20:23]
	v_mfma_f32_16x16x32_bf16 v[16:19], v[194:197], v[218:221], v[16:19]
	v_mfma_f32_16x16x32_bf16 v[4:7], v[186:189], v[228:231], v[4:7]
	v_mfma_f32_16x16x32_bf16 v[0:3], v[194:197], v[228:231], v[0:3]
	s_setprio 0
	s_barrier
	s_add_i32 s65, s65, 2
	s_add_u32 s24, s24, 0x100
	s_addc_u32 s25, s25, 0
	s_add_u32 s63, s63, 0x100
	s_addc_u32 s64, s64, 0
	s_cmp_gt_u32 s65, 13
	s_cbranch_scc0 .LBB0_1524
	s_lshl_b32 s13, s22, 8
	v_lshl_or_b32 v166, s20, 8, v148
	v_mov_b32 v136, 0
	v_xor_b32_e32 v169, 32, v165
	v_add3_u32 v167, s13, v146, v136
	v_add_u32_e32 v168, v166, v136
	v_lshl_add_u32 v136, v167, 10, v168
	v_lshl_add_u64 v[178:179], v[136:137], 1, s[40:41]
	v_add_u32_e32 v136, 0x80, v136
	global_load_dwordx4 v[170:173], v[178:179], off
	v_lshl_add_u64 v[180:181], v[136:137], 1, s[40:41]
	global_load_dwordx4 v[174:177], v[180:181], off
	v_add_u32_e32 v136, 16, v167
	v_lshl_add_u32 v136, v136, 10, v168
	v_lshl_add_u64 v[224:225], v[136:137], 1, s[40:41]
	v_add_u32_e32 v136, 0x80, v136
	global_load_dwordx4 v[192:195], v[224:225], off
	v_lshl_add_u64 v[248:249], v[136:137], 1, s[40:41]
	global_load_dwordx4 v[196:199], v[248:249], off
	v_add_u32_e32 v136, 32, v167
	v_lshl_add_u32 v136, v136, 10, v168
	v_lshl_add_u64 v[224:225], v[136:137], 1, s[40:41]
	v_add_u32_e32 v136, 0x80, v136
	global_load_dwordx4 v[200:203], v[224:225], off
	v_lshl_add_u64 v[248:249], v[136:137], 1, s[40:41]
	global_load_dwordx4 v[204:207], v[248:249], off
	v_add_u32_e32 v136, 48, v167
	v_lshl_add_u32 v136, v136, 10, v168
	v_lshl_add_u64 v[224:225], v[136:137], 1, s[40:41]
	v_add_u32_e32 v136, 0x80, v136
	global_load_dwordx4 v[208:211], v[224:225], off
	v_lshl_add_u64 v[248:249], v[136:137], 1, s[40:41]
	global_load_dwordx4 v[212:215], v[248:249], off
	v_add_u32_e32 v136, 0x80, v167
	v_lshl_add_u32 v136, v136, 10, v168
	v_lshl_add_u64 v[224:225], v[136:137], 1, s[40:41]
	v_add_u32_e32 v136, 0x80, v136
	global_load_dwordx4 v[216:219], v[224:225], off
	v_lshl_add_u64 v[248:249], v[136:137], 1, s[40:41]
	global_load_dwordx4 v[220:223], v[248:249], off
	v_add_u32_e32 v136, 0x90, v167
	v_lshl_add_u32 v136, v136, 10, v168
	v_lshl_add_u64 v[224:225], v[136:137], 1, s[40:41]
	v_add_u32_e32 v136, 0x80, v136
	global_load_dwordx4 v[228:231], v[224:225], off
	v_lshl_add_u64 v[248:249], v[136:137], 1, s[40:41]
	global_load_dwordx4 v[244:247], v[248:249], off
	v_and_b32_e32 v166, 64, v165
	v_xor_b32_e32 v136, 16, v165
	v_add_u32_e32 v166, 64, v166
	v_cmp_lt_i32_e32 vcc, v136, v166
	s_lshl_b32 s13, s20, 2
	s_or_b32 s13, s13, s49
	v_cndmask_b32_e32 v136, v165, v136, vcc
	v_cmp_lt_i32_e32 vcc, v169, v166
	v_lshlrev_b32_e32 v166, 2, v136
	s_waitcnt vmcnt(10)
;   __device__ __forceinline__ void operator()(const pg8::f32x4 (&acc)[2][2][4][2], const pg8::Unit& u, int wr, int wc, int fr, int fq) const {
;     ...
;         const int tok = row0 + ai * 128 + m * 16; float ss = 0.f;
; #pragma unroll
;         for (int bj = 0; bj < 2; ++bj) {
;           const unsigned off = (unsigned)tok * DM + colb + 128 * bj;
;           f8_t n = __builtin_convertvector(*(const h8_t*)(x16 + off), f8_t);
; #pragma unroll
;           for (int c = 0; c < 4; ++c) { n[c] += sc * acc[ai][bj][m][0][c]; n[4 + c] += sc * acc[ai][bj][m][1][c]; }
;           if (aux) {
;             *(h8_t*)(x16 + off) = __builtin_convertvector(n, h8_t);
;             ss += ((n[0] * n[0] + n[1] * n[1]) + (n[2] * n[2] + n[3] * n[3])) + ((n[4] * n[4] + n[5] * n[5]) + (n[6] * n[6] + n[7] * n[7]));
;           } else {
;             *(f32x4*)(xout + off) = (f32x4){n[0], n[1], n[2], n[3]}; *(f32x4*)(xout + off + 4) = (f32x4){n[4], n[5], n[6], n[7]};
;           }
;         }
;         if (aux) { ss += __shfl_xor(ss, 16); ss += __shfl_xor(ss, 32); if (fq == 0) ssq[(unsigned)tok * 16 + u.pn * 4 + wc] = ss; }
;         if (m & 1) asm volatile("" ::: "memory");
;       }
	v_cvt_f32_f16_e32 v182, v173
	v_cvt_f32_f16_sdwa v183, v173 dst_sel:DWORD dst_unused:UNUSED_PAD src0_sel:WORD_1
	v_cvt_f32_f16_e32 v184, v171
	v_cvt_f32_f16_sdwa v185, v171 dst_sel:DWORD dst_unused:UNUSED_PAD src0_sel:WORD_1
	v_cvt_f32_f16_e32 v186, v172
	v_cvt_f32_f16_sdwa v187, v172 dst_sel:DWORD dst_unused:UNUSED_PAD src0_sel:WORD_1
	v_cvt_f32_f16_e32 v172, v170
	v_cvt_f32_f16_sdwa v173, v170 dst_sel:DWORD dst_unused:UNUSED_PAD src0_sel:WORD_1
	v_cvt_f32_f16_e32 v170, v177
	v_cvt_f32_f16_sdwa v171, v177 dst_sel:DWORD dst_unused:UNUSED_PAD src0_sel:WORD_1
	v_cvt_f32_f16_e32 v188, v175
	v_cvt_f32_f16_sdwa v189, v175 dst_sel:DWORD dst_unused:UNUSED_PAD src0_sel:WORD_1
	v_cvt_f32_f16_e32 v190, v176
	v_cvt_f32_f16_sdwa v191, v176 dst_sel:DWORD dst_unused:UNUSED_PAD src0_sel:WORD_1
	v_cvt_f32_f16_e32 v176, v174
	v_cvt_f32_f16_sdwa v177, v174 dst_sel:DWORD dst_unused:UNUSED_PAD src0_sel:WORD_1
	v_pk_add_f32 v[124:125], v[124:125], v[172:173]
	v_pk_add_f32 v[172:173], v[120:121], v[186:187]
	v_pk_add_f32 v[126:127], v[126:127], v[184:185]
	v_pk_add_f32 v[122:123], v[122:123], v[182:183]
	v_cvt_pk_f16_f32 v120, v172, v173
	v_cvt_pk_f16_f32 v121, v122, v123
	v_pk_mul_f32 v[174:175], v[124:125], v[124:125]
	v_pk_mul_f32 v[182:183], v[126:127], v[126:127]
	v_pk_mul_f32 v[172:173], v[172:173], v[172:173]
	v_pk_mul_f32 v[122:123], v[122:123], v[122:123]
	v_pk_add_f32 v[176:177], v[116:117], v[176:177]
	v_pk_add_f32 v[116:117], v[112:113], v[190:191]
	v_pk_add_f32 v[184:185], v[118:119], v[188:189]
	v_pk_add_f32 v[112:113], v[114:115], v[170:171]
	v_pk_mul_f32 v[114:115], v[176:177], v[176:177]
	v_pk_mul_f32 v[118:119], v[184:185], v[184:185]
	v_pk_mul_f32 v[170:171], v[116:117], v[116:117]
	v_pk_mul_f32 v[186:187], v[112:113], v[112:113]
	v_add_f32_e32 v122, v122, v123
	v_add_f32_e32 v123, v172, v173
	v_add_f32_e32 v136, v182, v183
	v_add_f32_e32 v172, v174, v175
	v_add_f32_e32 v122, v123, v122
	v_add_f32_e32 v123, v172, v136
	v_add_f32_e32 v136, v186, v187
	v_add_f32_e32 v170, v170, v171
	v_add_f32_e32 v118, v118, v119
	v_add_f32_e32 v114, v114, v115
	v_add_f32_e32 v119, v170, v136
	v_add_f32_e32 v114, v114, v118
	v_add_f32_e32 v115, v123, v122
	v_add_f32_e32 v114, v114, v119
	v_add_f32_e32 v114, v115, v114
	ds_bpermute_b32 v115, v166, v114
	v_cndmask_b32_e32 v169, v165, v169, vcc
	v_cvt_pk_f16_f32 v119, v126, v127
	v_cvt_pk_f16_f32 v118, v124, v125
	global_store_dwordx4 v[178:179], v[118:121], off
	s_nop 1
	v_cvt_pk_f16_f32 v119, v112, v113
	s_waitcnt lgkmcnt(0)
	v_add_f32_e32 v113, v114, v115
	v_lshlrev_b32_e32 v112, 2, v169
	ds_bpermute_b32 v114, v112, v113
	v_cvt_pk_f16_f32 v118, v116, v117
	v_cvt_pk_f16_f32 v117, v184, v185
	v_cvt_pk_f16_f32 v116, v176, v177
	global_store_dwordx4 v[180:181], v[116:119], off
	s_and_saveexec_b64 s[20:21], s[6:7]
	s_cbranch_execz .LBB0_1527
	v_lshl_add_u32 v136, v167, 4, s13
	s_waitcnt lgkmcnt(0)
	v_add_f32_e32 v113, v113, v114
	v_lshl_add_u64 v[114:115], v[136:137], 2, s[42:43]
	global_store_dword v[114:115], v113, off
.LBB0_1527:
	s_or_b64 exec, exec, s[20:21]
	v_add_u32_e32 v113, 16, v167
	v_lshl_add_u32 v136, v113, 10, v168
	v_lshl_add_u64 v[122:123], v[136:137], 1, s[40:41]
	v_add_u32_e32 v136, 0x80, v136
	v_lshl_add_u64 v[124:125], v[136:137], 1, s[40:41]
	s_waitcnt lgkmcnt(0)
	s_waitcnt vmcnt(10)
	v_cvt_f32_f16_e32 v126, v195
	v_cvt_f32_f16_sdwa v127, v195 dst_sel:DWORD dst_unused:UNUSED_PAD src0_sel:WORD_1
	v_cvt_f32_f16_e32 v170, v193
	v_cvt_f32_f16_sdwa v171, v193 dst_sel:DWORD dst_unused:UNUSED_PAD src0_sel:WORD_1
	v_cvt_f32_f16_e32 v172, v194
	v_cvt_f32_f16_sdwa v173, v194 dst_sel:DWORD dst_unused:UNUSED_PAD src0_sel:WORD_1
	v_cvt_f32_f16_e32 v116, v192
	v_cvt_f32_f16_sdwa v117, v192 dst_sel:DWORD dst_unused:UNUSED_PAD src0_sel:WORD_1
	v_cvt_f32_f16_e32 v114, v199
	v_cvt_f32_f16_sdwa v115, v199 dst_sel:DWORD dst_unused:UNUSED_PAD src0_sel:WORD_1
	v_cvt_f32_f16_e32 v174, v197
	v_cvt_f32_f16_sdwa v175, v197 dst_sel:DWORD dst_unused:UNUSED_PAD src0_sel:WORD_1
	v_cvt_f32_f16_e32 v176, v198
	v_cvt_f32_f16_sdwa v177, v198 dst_sel:DWORD dst_unused:UNUSED_PAD src0_sel:WORD_1
	v_cvt_f32_f16_e32 v120, v196
	v_cvt_f32_f16_sdwa v121, v196 dst_sel:DWORD dst_unused:UNUSED_PAD src0_sel:WORD_1
	v_pk_add_f32 v[108:109], v[108:109], v[116:117]
	v_pk_add_f32 v[116:117], v[104:105], v[172:173]
	v_pk_add_f32 v[110:111], v[110:111], v[170:171]
	v_pk_add_f32 v[106:107], v[106:107], v[126:127]
	v_pk_add_f32 v[120:121], v[100:101], v[120:121]
	v_pk_add_f32 v[170:171], v[96:97], v[176:177]
	v_pk_add_f32 v[172:173], v[102:103], v[174:175]
	v_pk_add_f32 v[96:97], v[98:99], v[114:115]
	v_cvt_pk_f16_f32 v105, v106, v107
	v_cvt_pk_f16_f32 v104, v116, v117
	v_pk_mul_f32 v[118:119], v[108:109], v[108:109]
	v_pk_mul_f32 v[126:127], v[110:111], v[110:111]
	v_pk_mul_f32 v[116:117], v[116:117], v[116:117]
	v_pk_mul_f32 v[106:107], v[106:107], v[106:107]
	v_pk_mul_f32 v[98:99], v[120:121], v[120:121]
	v_pk_mul_f32 v[100:101], v[172:173], v[172:173]
	v_pk_mul_f32 v[102:103], v[170:171], v[170:171]
	v_pk_mul_f32 v[114:115], v[96:97], v[96:97]
	v_add_f32_e32 v106, v106, v107
	v_add_f32_e32 v107, v116, v117
	v_add_f32_e32 v116, v126, v127
	v_add_f32_e32 v117, v118, v119
	v_add_f32_e32 v114, v114, v115
	v_add_f32_e32 v102, v102, v103
	v_add_f32_e32 v100, v100, v101
	v_add_f32_e32 v98, v98, v99
	v_add_f32_e32 v106, v107, v106
	v_add_f32_e32 v107, v117, v116
	v_add_f32_e32 v101, v102, v114
	v_add_f32_e32 v98, v98, v100
	v_add_f32_e32 v99, v107, v106
	v_add_f32_e32 v98, v98, v101
	v_add_f32_e32 v98, v99, v98
	ds_bpermute_b32 v99, v166, v98
	v_cvt_pk_f16_f32 v101, v96, v97
	v_cvt_pk_f16_f32 v103, v110, v111
	v_cvt_pk_f16_f32 v102, v108, v109
	v_cvt_pk_f16_f32 v100, v170, v171
	s_waitcnt lgkmcnt(0)
	v_add_f32_e32 v96, v98, v99
	ds_bpermute_b32 v97, v112, v96
	v_cvt_pk_f16_f32 v99, v172, v173
	v_cvt_pk_f16_f32 v98, v120, v121
	global_store_dwordx4 v[122:123], v[102:105], off
	global_store_dwordx4 v[124:125], v[98:101], off
	s_and_saveexec_b64 s[20:21], s[6:7]
	s_cbranch_execz .LBB0_1529
	v_lshl_add_u32 v136, v113, 4, s13
	s_waitcnt lgkmcnt(0)
	v_add_f32_e32 v98, v96, v97
	v_lshl_add_u64 v[96:97], v[136:137], 2, s[42:43]
	global_store_dword v[96:97], v98, off
;   __device__ __forceinline__ void operator()(const pg8::f32x4 (&acc)[2][2][4][2], const pg8::Unit& u, int wr, int wc, int fr, int fq) const {
;     ...
;         const int tok = row0 + ai * 128 + m * 16; float ss = 0.f;
; #pragma unroll
;         for (int bj = 0; bj < 2; ++bj) {
;           const unsigned off = (unsigned)tok * DM + colb + 128 * bj;
;           f8_t n = __builtin_convertvector(*(const h8_t*)(x16 + off), f8_t);
; #pragma unroll
;           for (int c = 0; c < 4; ++c) { n[c] += sc * acc[ai][bj][m][0][c]; n[4 + c] += sc * acc[ai][bj][m][1][c]; }
;           if (aux) {
;             *(h8_t*)(x16 + off) = __builtin_convertvector(n, h8_t);
;             ss += ((n[0] * n[0] + n[1] * n[1]) + (n[2] * n[2] + n[3] * n[3])) + ((n[4] * n[4] + n[5] * n[5]) + (n[6] * n[6] + n[7] * n[7]));
;           } else {
;             *(f32x4*)(xout + off) = (f32x4){n[0], n[1], n[2], n[3]}; *(f32x4*)(xout + off + 4) = (f32x4){n[4], n[5], n[6], n[7]};
;           }
;         }
;         if (aux) { ss += __shfl_xor(ss, 16); ss += __shfl_xor(ss, 32); if (fq == 0) ssq[(unsigned)tok * 16 + u.pn * 4 + wc] = ss; }
;         if (m & 1) asm volatile("" ::: "memory");
;       }
.LBB0_1529:
	s_or_b64 exec, exec, s[20:21]
	v_add_u32_e32 v96, 32, v167
	v_lshl_add_u32 v136, v96, 10, v168
	v_lshl_add_u64 v[106:107], v[136:137], 1, s[40:41]
	v_add_u32_e32 v136, 0x80, v136
	v_lshl_add_u64 v[108:109], v[136:137], 1, s[40:41]
	s_waitcnt vmcnt(10)
	v_cvt_f32_f16_e32 v110, v203
	v_cvt_f32_f16_sdwa v111, v203 dst_sel:DWORD dst_unused:UNUSED_PAD src0_sel:WORD_1
	v_cvt_f32_f16_e32 v114, v201
	v_cvt_f32_f16_sdwa v115, v201 dst_sel:DWORD dst_unused:UNUSED_PAD src0_sel:WORD_1
	v_cvt_f32_f16_e32 v116, v202
	v_cvt_f32_f16_sdwa v117, v202 dst_sel:DWORD dst_unused:UNUSED_PAD src0_sel:WORD_1
	v_cvt_f32_f16_e32 v100, v200
	v_cvt_f32_f16_sdwa v101, v200 dst_sel:DWORD dst_unused:UNUSED_PAD src0_sel:WORD_1
	v_cvt_f32_f16_e32 v98, v207
	v_cvt_f32_f16_sdwa v99, v207 dst_sel:DWORD dst_unused:UNUSED_PAD src0_sel:WORD_1
	v_cvt_f32_f16_e32 v118, v205
	v_cvt_f32_f16_sdwa v119, v205 dst_sel:DWORD dst_unused:UNUSED_PAD src0_sel:WORD_1
	v_cvt_f32_f16_e32 v120, v206
	v_cvt_f32_f16_sdwa v121, v206 dst_sel:DWORD dst_unused:UNUSED_PAD src0_sel:WORD_1
	v_cvt_f32_f16_e32 v104, v204
	v_cvt_f32_f16_sdwa v105, v204 dst_sel:DWORD dst_unused:UNUSED_PAD src0_sel:WORD_1
	v_pk_add_f32 v[92:93], v[92:93], v[100:101]
	v_pk_add_f32 v[100:101], v[88:89], v[116:117]
	v_pk_add_f32 v[94:95], v[94:95], v[114:115]
	v_pk_add_f32 v[90:91], v[90:91], v[110:111]
	v_cvt_pk_f16_f32 v88, v100, v101
	v_cvt_pk_f16_f32 v89, v90, v91
	v_pk_mul_f32 v[102:103], v[92:93], v[92:93]
	v_pk_mul_f32 v[110:111], v[94:95], v[94:95]
	v_pk_mul_f32 v[100:101], v[100:101], v[100:101]
	v_pk_mul_f32 v[90:91], v[90:91], v[90:91]
	v_pk_add_f32 v[104:105], v[84:85], v[104:105]
	v_pk_add_f32 v[114:115], v[80:81], v[120:121]
	v_pk_add_f32 v[116:117], v[86:87], v[118:119]
	v_pk_add_f32 v[80:81], v[82:83], v[98:99]
	v_pk_mul_f32 v[82:83], v[104:105], v[104:105]
	v_pk_mul_f32 v[84:85], v[116:117], v[116:117]
	v_pk_mul_f32 v[86:87], v[114:115], v[114:115]
	v_pk_mul_f32 v[98:99], v[80:81], v[80:81]
	v_add_f32_e32 v90, v90, v91
	v_add_f32_e32 v91, v100, v101
	s_waitcnt lgkmcnt(0)
	v_add_f32_e32 v97, v110, v111
	v_add_f32_e32 v100, v102, v103
	v_add_f32_e32 v90, v91, v90
	v_add_f32_e32 v91, v100, v97
	v_add_f32_e32 v97, v98, v99
	v_add_f32_e32 v86, v86, v87
	v_add_f32_e32 v84, v84, v85
	v_add_f32_e32 v82, v82, v83
	v_add_f32_e32 v85, v86, v97
	v_add_f32_e32 v82, v82, v84
	v_add_f32_e32 v83, v91, v90
	v_add_f32_e32 v82, v82, v85
	v_add_f32_e32 v82, v83, v82
	ds_bpermute_b32 v83, v166, v82
	v_cvt_pk_f16_f32 v85, v80, v81
	v_cvt_pk_f16_f32 v87, v94, v95
	v_cvt_pk_f16_f32 v86, v92, v93
	v_cvt_pk_f16_f32 v84, v114, v115
	s_waitcnt lgkmcnt(0)
	v_add_f32_e32 v80, v82, v83
	ds_bpermute_b32 v81, v112, v80
	v_cvt_pk_f16_f32 v83, v116, v117
	v_cvt_pk_f16_f32 v82, v104, v105
	global_store_dwordx4 v[106:107], v[86:89], off
	global_store_dwordx4 v[108:109], v[82:85], off
	s_and_saveexec_b64 s[20:21], s[6:7]
	s_cbranch_execz .LBB0_1531
	v_lshl_add_u32 v136, v96, 4, s13
	s_waitcnt lgkmcnt(0)
	v_add_f32_e32 v82, v80, v81
	v_lshl_add_u64 v[80:81], v[136:137], 2, s[42:43]
	global_store_dword v[80:81], v82, off
.LBB0_1531:
	s_or_b64 exec, exec, s[20:21]
	v_add_u32_e32 v80, 48, v167
	v_lshl_add_u32 v136, v80, 10, v168
	v_lshl_add_u64 v[90:91], v[136:137], 1, s[40:41]
	v_add_u32_e32 v136, 0x80, v136
	v_lshl_add_u64 v[92:93], v[136:137], 1, s[40:41]
	s_waitcnt vmcnt(10)
	v_cvt_f32_f16_e32 v94, v211
	v_cvt_f32_f16_sdwa v95, v211 dst_sel:DWORD dst_unused:UNUSED_PAD src0_sel:WORD_1
	v_cvt_f32_f16_e32 v96, v209
	v_cvt_f32_f16_sdwa v97, v209 dst_sel:DWORD dst_unused:UNUSED_PAD src0_sel:WORD_1
	v_cvt_f32_f16_e32 v98, v210
	v_cvt_f32_f16_sdwa v99, v210 dst_sel:DWORD dst_unused:UNUSED_PAD src0_sel:WORD_1
	v_cvt_f32_f16_e32 v84, v208
	v_cvt_f32_f16_sdwa v85, v208 dst_sel:DWORD dst_unused:UNUSED_PAD src0_sel:WORD_1
	v_cvt_f32_f16_e32 v82, v215
	v_cvt_f32_f16_sdwa v83, v215 dst_sel:DWORD dst_unused:UNUSED_PAD src0_sel:WORD_1
	v_cvt_f32_f16_e32 v100, v213
	v_cvt_f32_f16_sdwa v101, v213 dst_sel:DWORD dst_unused:UNUSED_PAD src0_sel:WORD_1
	v_cvt_f32_f16_e32 v102, v214
	v_cvt_f32_f16_sdwa v103, v214 dst_sel:DWORD dst_unused:UNUSED_PAD src0_sel:WORD_1
	v_cvt_f32_f16_e32 v88, v212
	v_cvt_f32_f16_sdwa v89, v212 dst_sel:DWORD dst_unused:UNUSED_PAD src0_sel:WORD_1
	v_pk_add_f32 v[76:77], v[76:77], v[84:85]
	v_pk_add_f32 v[84:85], v[72:73], v[98:99]
	v_pk_add_f32 v[78:79], v[78:79], v[96:97]
	v_pk_add_f32 v[74:75], v[74:75], v[94:95]
	v_cvt_pk_f16_f32 v72, v84, v85
	v_cvt_pk_f16_f32 v73, v74, v75
	v_pk_mul_f32 v[86:87], v[76:77], v[76:77]
	v_pk_mul_f32 v[94:95], v[78:79], v[78:79]
	v_pk_mul_f32 v[84:85], v[84:85], v[84:85]
	v_pk_mul_f32 v[74:75], v[74:75], v[74:75]
	v_pk_add_f32 v[88:89], v[68:69], v[88:89]
	v_pk_add_f32 v[96:97], v[64:65], v[102:103]
	v_pk_add_f32 v[98:99], v[70:71], v[100:101]
	v_pk_add_f32 v[64:65], v[66:67], v[82:83]
	v_pk_mul_f32 v[66:67], v[88:89], v[88:89]
	v_pk_mul_f32 v[68:69], v[98:99], v[98:99]
	v_pk_mul_f32 v[70:71], v[96:97], v[96:97]
	v_pk_mul_f32 v[82:83], v[64:65], v[64:65]
	v_add_f32_e32 v74, v74, v75
	v_add_f32_e32 v75, v84, v85
	s_waitcnt lgkmcnt(0)
	v_add_f32_e32 v81, v94, v95
	v_add_f32_e32 v84, v86, v87
	v_add_f32_e32 v74, v75, v74
	v_add_f32_e32 v75, v84, v81
	v_add_f32_e32 v81, v82, v83
	v_add_f32_e32 v70, v70, v71
	v_add_f32_e32 v68, v68, v69
	v_add_f32_e32 v66, v66, v67
	v_add_f32_e32 v69, v70, v81
	v_add_f32_e32 v66, v66, v68
	v_add_f32_e32 v67, v75, v74
	v_add_f32_e32 v66, v66, v69
	v_add_f32_e32 v66, v67, v66
	ds_bpermute_b32 v67, v166, v66
	v_cvt_pk_f16_f32 v69, v64, v65
	v_cvt_pk_f16_f32 v71, v78, v79
	v_cvt_pk_f16_f32 v70, v76, v77
	v_cvt_pk_f16_f32 v68, v96, v97
	s_waitcnt lgkmcnt(0)
	v_add_f32_e32 v64, v66, v67
	ds_bpermute_b32 v65, v112, v64
	v_cvt_pk_f16_f32 v67, v98, v99
	v_cvt_pk_f16_f32 v66, v88, v89
	global_store_dwordx4 v[90:91], v[70:73], off
	global_store_dwordx4 v[92:93], v[66:69], off
	s_and_saveexec_b64 s[20:21], s[6:7]
	s_cbranch_execz .LBB0_1533
	v_lshl_add_u32 v136, v80, 4, s13
	s_waitcnt lgkmcnt(0)
	v_add_f32_e32 v66, v64, v65
	v_lshl_add_u64 v[64:65], v[136:137], 2, s[42:43]
	global_store_dword v[64:65], v66, off
;   __device__ __forceinline__ void operator()(const pg8::f32x4 (&acc)[2][2][4][2], const pg8::Unit& u, int wr, int wc, int fr, int fq) const {
;     ...
;         const int tok = row0 + ai * 128 + m * 16; float ss = 0.f;
; #pragma unroll
;         for (int bj = 0; bj < 2; ++bj) {
;           const unsigned off = (unsigned)tok * DM + colb + 128 * bj;
;           f8_t n = __builtin_convertvector(*(const h8_t*)(x16 + off), f8_t);
; #pragma unroll
;           for (int c = 0; c < 4; ++c) { n[c] += sc * acc[ai][bj][m][0][c]; n[4 + c] += sc * acc[ai][bj][m][1][c]; }
;           if (aux) {
;             *(h8_t*)(x16 + off) = __builtin_convertvector(n, h8_t);
;             ss += ((n[0] * n[0] + n[1] * n[1]) + (n[2] * n[2] + n[3] * n[3])) + ((n[4] * n[4] + n[5] * n[5]) + (n[6] * n[6] + n[7] * n[7]));
;           } else {
;             *(f32x4*)(xout + off) = (f32x4){n[0], n[1], n[2], n[3]}; *(f32x4*)(xout + off + 4) = (f32x4){n[4], n[5], n[6], n[7]};
;           }
;         }
;         if (aux) { ss += __shfl_xor(ss, 16); ss += __shfl_xor(ss, 32); if (fq == 0) ssq[(unsigned)tok * 16 + u.pn * 4 + wc] = ss; }
;         if (m & 1) asm volatile("" ::: "memory");
;       }
.LBB0_1533:
	s_or_b64 exec, exec, s[20:21]
	v_add_u32_e32 v64, 0x80, v167
	v_lshl_add_u32 v136, v64, 10, v168
	v_lshl_add_u64 v[74:75], v[136:137], 1, s[40:41]
	v_add_u32_e32 v136, 0x80, v136
	v_lshl_add_u64 v[76:77], v[136:137], 1, s[40:41]
	s_waitcnt vmcnt(10)
	v_cvt_f32_f16_e32 v78, v219
	v_cvt_f32_f16_sdwa v79, v219 dst_sel:DWORD dst_unused:UNUSED_PAD src0_sel:WORD_1
	v_cvt_f32_f16_e32 v80, v217
	v_cvt_f32_f16_sdwa v81, v217 dst_sel:DWORD dst_unused:UNUSED_PAD src0_sel:WORD_1
	v_cvt_f32_f16_e32 v82, v218
	v_cvt_f32_f16_sdwa v83, v218 dst_sel:DWORD dst_unused:UNUSED_PAD src0_sel:WORD_1
	v_cvt_f32_f16_e32 v68, v216
	v_cvt_f32_f16_sdwa v69, v216 dst_sel:DWORD dst_unused:UNUSED_PAD src0_sel:WORD_1
	v_cvt_f32_f16_e32 v66, v223
	v_cvt_f32_f16_sdwa v67, v223 dst_sel:DWORD dst_unused:UNUSED_PAD src0_sel:WORD_1
	v_cvt_f32_f16_e32 v84, v221
	v_cvt_f32_f16_sdwa v85, v221 dst_sel:DWORD dst_unused:UNUSED_PAD src0_sel:WORD_1
	v_cvt_f32_f16_e32 v86, v222
	v_cvt_f32_f16_sdwa v87, v222 dst_sel:DWORD dst_unused:UNUSED_PAD src0_sel:WORD_1
	v_cvt_f32_f16_e32 v72, v220
	v_cvt_f32_f16_sdwa v73, v220 dst_sel:DWORD dst_unused:UNUSED_PAD src0_sel:WORD_1
	v_pk_add_f32 v[60:61], v[60:61], v[68:69]
	v_pk_add_f32 v[68:69], v[56:57], v[82:83]
	v_pk_add_f32 v[62:63], v[62:63], v[80:81]
	v_pk_add_f32 v[58:59], v[58:59], v[78:79]
	v_cvt_pk_f16_f32 v56, v68, v69
	v_cvt_pk_f16_f32 v57, v58, v59
	v_pk_mul_f32 v[70:71], v[60:61], v[60:61]
	v_pk_mul_f32 v[78:79], v[62:63], v[62:63]
	v_pk_mul_f32 v[68:69], v[68:69], v[68:69]
	v_pk_mul_f32 v[58:59], v[58:59], v[58:59]
	v_pk_add_f32 v[72:73], v[52:53], v[72:73]
	v_pk_add_f32 v[80:81], v[48:49], v[86:87]
	v_pk_add_f32 v[82:83], v[54:55], v[84:85]
	v_pk_add_f32 v[48:49], v[50:51], v[66:67]
	v_pk_mul_f32 v[50:51], v[72:73], v[72:73]
	v_pk_mul_f32 v[52:53], v[82:83], v[82:83]
	v_pk_mul_f32 v[54:55], v[80:81], v[80:81]
	v_pk_mul_f32 v[66:67], v[48:49], v[48:49]
	v_add_f32_e32 v58, v58, v59
	v_add_f32_e32 v59, v68, v69
	s_waitcnt lgkmcnt(0)
	v_add_f32_e32 v65, v78, v79
	v_add_f32_e32 v68, v70, v71
	v_add_f32_e32 v58, v59, v58
	v_add_f32_e32 v59, v68, v65
	v_add_f32_e32 v65, v66, v67
	v_add_f32_e32 v54, v54, v55
	v_add_f32_e32 v52, v52, v53
	v_add_f32_e32 v50, v50, v51
	v_add_f32_e32 v53, v54, v65
	v_add_f32_e32 v50, v50, v52
	v_add_f32_e32 v51, v59, v58
	v_add_f32_e32 v50, v50, v53
	v_add_f32_e32 v50, v51, v50
	ds_bpermute_b32 v51, v166, v50
	v_cvt_pk_f16_f32 v53, v48, v49
	v_cvt_pk_f16_f32 v55, v62, v63
	v_cvt_pk_f16_f32 v54, v60, v61
	v_cvt_pk_f16_f32 v52, v80, v81
	s_waitcnt lgkmcnt(0)
	v_add_f32_e32 v48, v50, v51
	ds_bpermute_b32 v49, v112, v48
	v_cvt_pk_f16_f32 v51, v82, v83
	v_cvt_pk_f16_f32 v50, v72, v73
	global_store_dwordx4 v[74:75], v[54:57], off
	global_store_dwordx4 v[76:77], v[50:53], off
	s_and_saveexec_b64 s[20:21], s[6:7]
	s_cbranch_execz .LBB0_1535
	v_lshl_add_u32 v136, v64, 4, s13
	s_waitcnt lgkmcnt(0)
	v_add_f32_e32 v50, v48, v49
	v_lshl_add_u64 v[48:49], v[136:137], 2, s[42:43]
	global_store_dword v[48:49], v50, off
.LBB0_1535:
	s_or_b64 exec, exec, s[20:21]
	v_add_u32_e32 v48, 0x90, v167
	v_lshl_add_u32 v136, v48, 10, v168
	v_lshl_add_u64 v[58:59], v[136:137], 1, s[40:41]
	v_add_u32_e32 v136, 0x80, v136
	v_lshl_add_u64 v[60:61], v[136:137], 1, s[40:41]
	s_waitcnt vmcnt(10)
	v_cvt_f32_f16_e32 v62, v231
	v_cvt_f32_f16_sdwa v63, v231 dst_sel:DWORD dst_unused:UNUSED_PAD src0_sel:WORD_1
	v_cvt_f32_f16_e32 v64, v229
	v_cvt_f32_f16_sdwa v65, v229 dst_sel:DWORD dst_unused:UNUSED_PAD src0_sel:WORD_1
	v_cvt_f32_f16_e32 v66, v230
	v_cvt_f32_f16_sdwa v67, v230 dst_sel:DWORD dst_unused:UNUSED_PAD src0_sel:WORD_1
	v_cvt_f32_f16_e32 v52, v228
	v_cvt_f32_f16_sdwa v53, v228 dst_sel:DWORD dst_unused:UNUSED_PAD src0_sel:WORD_1
	v_cvt_f32_f16_e32 v50, v247
	v_cvt_f32_f16_sdwa v51, v247 dst_sel:DWORD dst_unused:UNUSED_PAD src0_sel:WORD_1
	v_cvt_f32_f16_e32 v68, v245
	v_cvt_f32_f16_sdwa v69, v245 dst_sel:DWORD dst_unused:UNUSED_PAD src0_sel:WORD_1
	v_cvt_f32_f16_e32 v70, v246
	v_cvt_f32_f16_sdwa v71, v246 dst_sel:DWORD dst_unused:UNUSED_PAD src0_sel:WORD_1
	v_cvt_f32_f16_e32 v56, v244
	v_cvt_f32_f16_sdwa v57, v244 dst_sel:DWORD dst_unused:UNUSED_PAD src0_sel:WORD_1
	v_pk_add_f32 v[44:45], v[44:45], v[52:53]
	v_pk_add_f32 v[52:53], v[40:41], v[66:67]
	v_pk_add_f32 v[46:47], v[46:47], v[64:65]
	v_pk_add_f32 v[42:43], v[42:43], v[62:63]
	v_cvt_pk_f16_f32 v40, v52, v53
	v_cvt_pk_f16_f32 v41, v42, v43
	v_pk_mul_f32 v[54:55], v[44:45], v[44:45]
	v_pk_mul_f32 v[62:63], v[46:47], v[46:47]
	v_pk_mul_f32 v[52:53], v[52:53], v[52:53]
	v_pk_mul_f32 v[42:43], v[42:43], v[42:43]
	v_pk_add_f32 v[56:57], v[36:37], v[56:57]
	v_pk_add_f32 v[64:65], v[32:33], v[70:71]
	v_pk_add_f32 v[66:67], v[38:39], v[68:69]
	v_pk_add_f32 v[32:33], v[34:35], v[50:51]
	v_pk_mul_f32 v[34:35], v[56:57], v[56:57]
	v_pk_mul_f32 v[36:37], v[66:67], v[66:67]
	v_pk_mul_f32 v[38:39], v[64:65], v[64:65]
	v_pk_mul_f32 v[50:51], v[32:33], v[32:33]
	v_add_f32_e32 v42, v42, v43
	v_add_f32_e32 v43, v52, v53
	s_waitcnt lgkmcnt(0)
	v_add_f32_e32 v49, v62, v63
	v_add_f32_e32 v52, v54, v55
	v_add_f32_e32 v42, v43, v42
	v_add_f32_e32 v43, v52, v49
	v_add_f32_e32 v49, v50, v51
	v_add_f32_e32 v38, v38, v39
	v_add_f32_e32 v36, v36, v37
	v_add_f32_e32 v34, v34, v35
	v_add_f32_e32 v37, v38, v49
	v_add_f32_e32 v34, v34, v36
	v_add_f32_e32 v35, v43, v42
	v_add_f32_e32 v34, v34, v37
	v_add_f32_e32 v34, v35, v34
	ds_bpermute_b32 v35, v166, v34
	v_cvt_pk_f16_f32 v37, v32, v33
	v_cvt_pk_f16_f32 v39, v46, v47
	v_cvt_pk_f16_f32 v38, v44, v45
	v_cvt_pk_f16_f32 v36, v64, v65
	s_waitcnt lgkmcnt(0)
	v_add_f32_e32 v32, v34, v35
	ds_bpermute_b32 v33, v112, v32
	v_cvt_pk_f16_f32 v35, v66, v67
	v_cvt_pk_f16_f32 v34, v56, v57
	global_store_dwordx4 v[58:59], v[38:41], off
	global_store_dwordx4 v[60:61], v[34:37], off
	s_and_saveexec_b64 s[20:21], s[6:7]
	s_cbranch_execz .LBB0_1537
	v_lshl_add_u32 v136, v48, 4, s13
	s_waitcnt lgkmcnt(0)
	v_add_f32_e32 v34, v32, v33
	v_lshl_add_u64 v[32:33], v[136:137], 2, s[42:43]
	global_store_dword v[32:33], v34, off
